# f32->bf16 pair packing: compiler bit trick (bfe/add3/shift/and_or) replaced by v_cvt_pk_bf16_f32 at 62 sites (row norm, transposes, transpose-norm, Hyena output)
# speedup vs baseline: 1.0110x; 1.0110x over previous
.LBB0_198:
	v_add_u32_e32 v56, 0xfffef800, v97
	v_add_u32_e32 v58, 0xfffef884, v97
	v_add_u32_e32 v57, 0xffff3a00, v97
	v_add_u32_e32 v59, 0xffff3a84, v97
	ds_read_u16 v56, v56
	ds_read_u16 v57, v57
	ds_read_u16 v58, v58
	ds_read_u16 v59, v59
	v_add_u32_e32 v62, 0xffff7c84, v97
	v_add_u32_e32 v63, 0xffffbe84, v97
	s_waitcnt lgkmcnt(3)
	v_lshlrev_b32_e32 v56, 16, v56
	s_waitcnt lgkmcnt(1)
	v_lshlrev_b32_e32 v58, 16, v58
	s_waitcnt lgkmcnt(0)
	v_lshlrev_b32_e32 v59, 16, v59
	v_lshlrev_b32_e32 v57, 16, v57
	v_pk_mul_f32 v[60:61], v[58:59], v[58:59]
	s_nop 0
	v_pk_fma_f32 v[100:101], v[56:57], v[56:57], v[60:61]
	v_add_u32_e32 v60, 0xffff7c00, v97
	v_add_u32_e32 v61, 0xffffbe00, v97
	ds_read_u16 v60, v60
	ds_read_u16 v61, v61
	ds_read_u16 v62, v62
	ds_read_u16 v63, v63
	v_mov_b32_e32 v109, v100
	s_waitcnt lgkmcnt(3)
	v_lshlrev_b32_e32 v60, 16, v60
	s_waitcnt lgkmcnt(1)
	v_lshlrev_b32_e32 v62, 16, v62
	s_waitcnt lgkmcnt(0)
	v_lshlrev_b32_e32 v63, 16, v63
	v_lshlrev_b32_e32 v61, 16, v61
	v_pk_mul_f32 v[64:65], v[62:63], v[62:63]
	s_nop 0
	v_pk_fma_f32 v[102:103], v[60:61], v[60:61], v[64:65]
	ds_read_u16 v64, v97
	ds_read_u16 v65, v97 offset:16896
	ds_read_u16 v66, v97 offset:132
	ds_read_u16 v67, v97 offset:17028
	s_waitcnt lgkmcnt(3)
	v_lshlrev_b32_e32 v64, 16, v64
	s_waitcnt lgkmcnt(1)
	v_lshlrev_b32_e32 v66, 16, v66
	s_waitcnt lgkmcnt(0)
	v_lshlrev_b32_e32 v67, 16, v67
	v_lshlrev_b32_e32 v65, 16, v65
	v_pk_mul_f32 v[68:69], v[66:67], v[66:67]
	s_nop 0
	v_pk_fma_f32 v[104:105], v[64:65], v[64:65], v[68:69]
	ds_read_u16 v68, v97 offset:33792
	ds_read_u16 v69, v97 offset:50688
	ds_read_u16 v70, v97 offset:33924
	ds_read_u16 v71, v97 offset:50820
	v_mov_b32_e32 v108, v104
	v_mov_b32_e32 v100, v105
	s_waitcnt lgkmcnt(3)
	v_lshlrev_b32_e32 v68, 16, v68
	s_waitcnt lgkmcnt(1)
	v_lshlrev_b32_e32 v70, 16, v70
	s_waitcnt lgkmcnt(0)
	v_lshlrev_b32_e32 v71, 16, v71
	v_lshlrev_b32_e32 v69, 16, v69
	v_pk_mul_f32 v[106:107], v[70:71], v[70:71]
	v_pk_add_f32 v[100:101], v[108:109], v[100:101]
	v_pk_fma_f32 v[106:107], v[68:69], v[68:69], v[106:107]
	v_mov_b32_e32 v105, v102
	v_mov_b32_e32 v104, v106
	v_pk_add_f32 v[100:101], v[100:101], v[104:105]
	v_mov_b32_e32 v102, v107
	v_pk_add_f32 v[100:101], v[100:101], v[102:103]
	ds_bpermute_b32 v103, v73, v101
	ds_bpermute_b32 v102, v73, v100
	v_add_u32_e32 v97, 2, v97
	s_waitcnt lgkmcnt(0)
	v_pk_add_f32 v[100:101], v[100:101], v[102:103]
	ds_bpermute_b32 v103, v74, v101
	ds_bpermute_b32 v102, v74, v100
	s_waitcnt lgkmcnt(0)
	v_pk_add_f32 v[100:101], v[100:101], v[102:103]
	ds_bpermute_b32 v103, v75, v101
	ds_bpermute_b32 v102, v75, v100
	s_waitcnt lgkmcnt(0)
	v_pk_add_f32 v[100:101], v[100:101], v[102:103]
	ds_bpermute_b32 v103, v76, v101
	ds_bpermute_b32 v102, v76, v100
	s_waitcnt lgkmcnt(0)
	v_pk_add_f32 v[100:101], v[100:101], v[102:103]
	ds_bpermute_b32 v103, v77, v101
	ds_bpermute_b32 v102, v77, v100
	s_waitcnt lgkmcnt(0)
	v_pk_add_f32 v[100:101], v[100:101], v[102:103]
	ds_bpermute_b32 v103, v78, v101
	ds_bpermute_b32 v102, v78, v100
	s_waitcnt lgkmcnt(0)
	v_pk_add_f32 v[100:101], v[100:101], v[102:103]
	s_nop 0
	v_pk_fma_f32 v[100:101], v[100:101], s[4:5], v[178:179] op_sel_hi:[1,0,0]
	s_nop 0
	v_mul_f32_e32 v99, 0x4b800000, v101
	v_cmp_gt_f32_e64 s[0:1], s23, v101
	v_cmp_gt_f32_e32 vcc, s23, v100
	s_nop 0
	v_cndmask_b32_e64 v99, v101, v99, s[0:1]
	v_rsq_f32_e32 v99, v99
	s_nop 0
	v_mul_f32_e32 v101, 0x45800000, v99
	v_cndmask_b32_e64 v99, v99, v101, s[0:1]
	v_mul_f32_e32 v101, 0x4b800000, v100
	v_cndmask_b32_e32 v100, v100, v101, vcc
	v_rsq_f32_e32 v100, v100
	v_mul_f32_e32 v56, v99, v56
	v_mul_f32_e32 v56, v40, v56
	v_mul_f32_e32 v58, v99, v58
	v_mul_f32_e32 v101, 0x45800000, v100
	v_cndmask_b32_e32 v102, v100, v101, vcc
	v_add_u32_e32 v100, s7, v98
	v_mul_f32_e32 v58, v41, v58
	v_ashrrev_i32_e32 v101, 31, v100
	v_lshlrev_b64 v[100:101], 11, v[100:101]
	v_cvt_pk_bf16_f32 v56, v56, v58
	v_lshl_add_u64 v[100:101], v[38:39], 0, v[100:101]
	global_store_dword v[100:101], v56, off
	v_mul_f32_e32 v56, v99, v57
	v_mul_f32_e32 v56, v42, v56
	v_mul_f32_e32 v57, v99, v59
	v_mul_f32_e32 v57, v43, v57
	v_cvt_pk_bf16_f32 v56, v56, v57
	global_store_dword v[100:101], v56, off offset:256
	v_mul_f32_e32 v56, v99, v60
	v_mul_f32_e32 v56, v44, v56
	v_mul_f32_e32 v57, v99, v62
	v_mul_f32_e32 v57, v45, v57
	v_cvt_pk_bf16_f32 v56, v56, v57
	global_store_dword v[100:101], v56, off offset:512
	v_mul_f32_e32 v56, v99, v61
	v_mul_f32_e32 v56, v46, v56
	v_mul_f32_e32 v57, v99, v63
	v_mul_f32_e32 v57, v47, v57
	v_cvt_pk_bf16_f32 v56, v56, v57
	global_store_dword v[100:101], v56, off offset:768
	v_mul_f32_e32 v56, v102, v64
	v_mul_f32_e32 v56, v48, v56
	v_mul_f32_e32 v57, v102, v66
	v_mul_f32_e32 v57, v49, v57
	v_cvt_pk_bf16_f32 v56, v56, v57
	global_store_dword v[100:101], v56, off offset:1024
	v_mul_f32_e32 v56, v102, v65
	v_mul_f32_e32 v56, v50, v56
	v_mul_f32_e32 v57, v102, v67
	v_mul_f32_e32 v57, v51, v57
	v_cvt_pk_bf16_f32 v56, v56, v57
	global_store_dword v[100:101], v56, off offset:1280
	v_mul_f32_e32 v56, v102, v68
	v_mul_f32_e32 v56, v52, v56
	v_mul_f32_e32 v57, v102, v70
	v_mul_f32_e32 v57, v53, v57
	v_cvt_pk_bf16_f32 v56, v56, v57
	global_store_dword v[100:101], v56, off offset:1536
	v_mul_f32_e32 v56, v102, v69
	v_mul_f32_e32 v56, v54, v56
	v_mul_f32_e32 v57, v102, v71
	v_mul_f32_e32 v57, v55, v57
	v_cvt_pk_bf16_f32 v56, v56, v57
	global_store_dword v[100:101], v56, off offset:1792
	v_add_u32_e32 v56, 1, v98
	v_cmp_ge_i32_e32 vcc, v98, v79
	s_or_b64 s[38:39], vcc, s[38:39]
	v_mov_b32_e32 v98, v56
	s_andn2_b64 exec, exec, s[38:39]
	s_cbranch_execnz .LBB0_198
	s_or_b64 exec, exec, s[38:39]
	s_add_i32 s9, s9, s3
	s_add_i32 s7, s7, s6
	s_cmpk_gt_i32 s9, 0x1ff
	s_cbranch_scc0 .LBB0_197

.LBB0_209:
	s_waitcnt vmcnt(5)
	v_lshlrev_b32_e32 v10, 16, v143
	v_and_b32_e32 v121, 0x1ff, v212
	v_cmp_eq_u32_e32 vcc, 0, v121
	v_and_b32_e32 v12, 0xffff0000, v4
	v_lshlrev_b32_e32 v13, 16, v4
	v_cndmask_b32_e64 v10, v10, 0, vcc
	v_pk_mul_f32 v[14:15], v[32:33], v[12:13]
	v_mov_b32_e32 v105, v13
	v_fma_f32 v4, v41, v10, v15
	v_add_f32_e32 v4, v14, v4
	v_add_f32_e32 v14, v219, v4
	v_and_b32_e32 v4, 0xffff0000, v5
	v_lshlrev_b32_e32 v5, 16, v5
	v_mov_b32_e32 v104, v5
	v_pk_mul_f32 v[104:105], v[40:41], v[104:105]
	v_pk_mul_f32 v[106:107], v[32:33], v[4:5]
	v_fma_f32 v10, v33, v12, v105
	v_add_f32_e32 v10, v104, v10
	v_add_f32_e32 v104, v219, v10
	v_fma_f32 v10, v41, v12, v107
	v_lshlrev_b32_e32 v107, 16, v6
	v_mov_b32_e32 v108, v107
	v_mov_b32_e32 v109, v5
	v_add_f32_e32 v10, v106, v10
	v_and_b32_e32 v106, 0xffff0000, v6
	v_pk_mul_f32 v[108:109], v[40:41], v[108:109]
	v_pk_mul_f32 v[110:111], v[32:33], v[106:107]
	v_fma_f32 v5, v33, v4, v109
	v_add_f32_e32 v5, v108, v5
	v_fma_f32 v4, v41, v4, v111
	v_add_f32_e32 v108, v219, v5
	v_add_f32_e32 v4, v110, v4
	v_lshlrev_b32_e32 v5, 16, v7
	v_add_f32_e32 v110, v219, v4
	v_and_b32_e32 v4, 0xffff0000, v7
	v_mov_b32_e32 v6, v5
	v_mov_b32_e32 v7, v107
	v_pk_mul_f32 v[6:7], v[40:41], v[6:7]
	s_waitcnt vmcnt(4)
	v_lshlrev_b32_e32 v11, 16, v142
	v_fma_f32 v7, v33, v106, v7
	v_add_f32_e32 v6, v6, v7
	v_add_f32_e32 v112, v219, v6
	v_pk_mul_f32 v[6:7], v[32:33], v[4:5]
	v_cmp_eq_u32_e64 s[0:1], s37, v121
	v_fma_f32 v7, v41, v106, v7
	v_add_f32_e32 v12, v219, v10
	v_cndmask_b32_e64 v11, v11, 0, s[0:1]
	v_add_f32_e32 v6, v6, v7
	v_mov_b32_e32 v10, v5
	v_add_f32_e32 v106, v219, v6
	v_pk_mul_f32 v[6:7], v[98:99], v[10:11]
	s_waitcnt vmcnt(2)
	v_lshlrev_b32_e32 v5, 16, v140
	v_fma_f32 v4, v33, v4, v6
	v_add_f32_e32 v4, v4, v7
	v_add_f32_e32 v10, v219, v4
	v_lshlrev_b32_e32 v4, 16, v141
	v_and_b32_e32 v6, 0xffff0000, v0
	v_lshlrev_b32_e32 v7, 16, v0
	v_cndmask_b32_e64 v4, v4, 0, vcc
	v_pk_mul_f32 v[114:115], v[32:33], v[6:7]
	v_mov_b32_e32 v117, v7
	v_fma_f32 v0, v41, v4, v115
	v_add_f32_e32 v0, v114, v0
	v_add_f32_e32 v114, v219, v0
	v_and_b32_e32 v0, 0xffff0000, v1
	v_lshlrev_b32_e32 v1, 16, v1
	v_mov_b32_e32 v116, v1
	v_pk_mul_f32 v[116:117], v[40:41], v[116:117]
	v_lshlrev_b32_e32 v7, 16, v2
	v_fma_f32 v4, v33, v6, v117
	v_mov_b32_e32 v118, v7
	v_mov_b32_e32 v119, v1
	v_add_f32_e32 v4, v116, v4
	v_pk_mul_f32 v[116:117], v[32:33], v[0:1]
	v_pk_mul_f32 v[118:119], v[40:41], v[118:119]
	v_add_f32_e32 v105, v219, v4
	v_fma_f32 v4, v41, v6, v117
	v_and_b32_e32 v6, 0xffff0000, v2
	v_fma_f32 v1, v33, v0, v119
	v_add_f32_e32 v1, v118, v1
	v_pk_mul_f32 v[118:119], v[32:33], v[6:7]
	v_add_f32_e32 v109, v219, v1
	v_fma_f32 v0, v41, v0, v119
	v_add_f32_e32 v0, v118, v0
	v_lshlrev_b32_e32 v1, 16, v3
	v_add_f32_e32 v118, v219, v0
	v_and_b32_e32 v0, 0xffff0000, v3
	v_mov_b32_e32 v2, v1
	v_mov_b32_e32 v3, v7
	v_pk_mul_f32 v[2:3], v[40:41], v[2:3]
	v_add_f32_e32 v4, v116, v4
	v_fma_f32 v3, v33, v6, v3
	v_add_f32_e32 v2, v2, v3
	v_add_f32_e32 v113, v219, v2
	v_pk_mul_f32 v[2:3], v[32:33], v[0:1]
	v_cndmask_b32_e64 v5, v5, 0, s[0:1]
	v_fma_f32 v3, v41, v6, v3
	v_add_f32_e32 v116, v219, v4
	v_add_f32_e32 v2, v2, v3
	v_mov_b32_e32 v4, v1
	v_add_f32_e32 v120, v219, v2
	v_pk_mul_f32 v[2:3], v[98:99], v[4:5]
	v_lshlrev_b32_e32 v122, 3, v121
	v_fma_f32 v0, v33, v0, v2
	v_add_f32_e32 v0, v0, v3
	v_add_f32_e32 v11, v219, v0
	v_add_u32_e32 v0, -1, v122
	v_cndmask_b32_e64 v176, v0, 0, vcc
	v_add_u32_e32 v0, 8, v122
	s_add_u32 s44, s28, s42
	v_cndmask_b32_e64 v13, v0, v229, s[0:1]
	v_lshlrev_b32_e32 v0, 4, v121
	v_mov_b32_e32 v1, v177
	s_addc_u32 s45, s29, s43
	v_bfe_u32 v8, v212, 1, 8
	v_lshl_add_u64 v[0:1], s[44:45], 0, v[0:1]
	v_add_u32_e32 v126, v122, v8
	v_mov_b32_e32 v9, v214
	v_mov_b32_e32 v8, v213
	v_add_co_u32_e32 v2, vcc, s5, v0
	v_lshl_add_u32 v117, v126, 3, 0
	s_nop 0
	v_addc_co_u32_e32 v3, vcc, 0, v1, vcc
	v_xor_b32_e32 v126, 0x80000000, v9
	v_mov_b32_e32 v127, v8
	s_mov_b32 s9, s30
	v_add_co_u32_e32 v4, vcc, s27, v0
	v_pk_mul_f32 v[126:127], v[126:127], v[114:115] op_sel_hi:[1,0]
	v_pk_mul_f32 v[128:129], v[214:215], s[8:9] op_sel_hi:[0,1]
	v_addc_co_u32_e32 v5, vcc, 0, v1, vcc
	v_pk_fma_f32 v[126:127], v[8:9], v[14:15], v[126:127] op_sel_hi:[1,0,1]
	v_pk_fma_f32 v[8:9], v[212:213], s[30:31], v[128:129] op_sel:[1,0,0]
	v_mov_b32_e32 v15, v114
	global_load_dwordx4 v[0:3], v[2:3], off
	s_nop 0
	global_load_dwordx4 v[4:7], v[4:5], off
	ds_write2_b64 v117, v[14:15], v[104:105] offset1:1
	v_pk_mul_f32 v[14:15], v[104:105], v[8:9] op_sel:[1,1] op_sel_hi:[1,0] neg_lo:[0,1]
	v_lshl_add_u64 v[122:123], v[176:177], 1, s[44:45]
	v_lshlrev_b32_e32 v176, 1, v13
	v_add_u32_e32 v13, 0x8800, v117
	v_pk_fma_f32 v[14:15], v[8:9], v[104:105], v[14:15] op_sel_hi:[1,0,1]
	ds_write2_b64 v13, v[126:127], v[14:15] offset1:1
	v_pk_mul_f32 v[14:15], v[8:9], s[8:9] op_sel:[1,0]
	v_add_u32_e32 v107, 0x8810, v117
	v_pk_fma_f32 v[8:9], v[8:9], s[30:31], v[14:15] op_sel_hi:[0,1,1]
	v_pk_mul_f32 v[14:15], v[116:117], v[8:9] op_sel:[0,1] op_sel_hi:[0,0] neg_lo:[0,1]
	v_pk_mul_f32 v[104:105], v[8:9], s[8:9] op_sel:[1,0]
	v_pk_fma_f32 v[14:15], v[12:13], v[8:9], v[14:15] op_sel_hi:[0,1,1]
	v_pk_fma_f32 v[8:9], v[8:9], s[30:31], v[104:105] op_sel_hi:[0,1,1]
	v_mov_b32_e32 v13, v116
	ds_write2_b64 v117, v[12:13], v[108:109] offset0:2 offset1:3
	v_pk_mul_f32 v[12:13], v[108:109], v[8:9] op_sel:[1,1] op_sel_hi:[1,0] neg_lo:[0,1]
	v_pk_fma_f32 v[12:13], v[108:109], v[8:9], v[12:13] op_sel_hi:[0,1,1]
	ds_write2_b64 v107, v[14:15], v[12:13] offset1:1
	v_pk_mul_f32 v[12:13], v[8:9], s[8:9] op_sel:[1,0]
	v_add_u32_e32 v107, 0x8820, v117
	v_pk_fma_f32 v[8:9], v[8:9], s[30:31], v[12:13] op_sel_hi:[0,1,1]
	v_pk_mul_f32 v[12:13], v[118:119], v[8:9] op_sel:[0,1] op_sel_hi:[0,0] neg_lo:[0,1]
	v_pk_mul_f32 v[14:15], v[8:9], s[8:9] op_sel:[1,0]
	v_pk_fma_f32 v[12:13], v[110:111], v[8:9], v[12:13] op_sel_hi:[0,1,1]
	v_pk_fma_f32 v[8:9], v[8:9], s[30:31], v[14:15] op_sel_hi:[0,1,1]
	v_pk_mul_f32 v[14:15], v[112:113], v[8:9] op_sel:[1,1] op_sel_hi:[1,0] neg_lo:[0,1]
	v_pk_fma_f32 v[14:15], v[112:113], v[8:9], v[14:15] op_sel_hi:[0,1,1]
	ds_write2_b64 v107, v[12:13], v[14:15] offset1:1
	v_pk_mul_f32 v[12:13], v[8:9], s[8:9] op_sel:[1,0]
	v_add_u32_e32 v108, 0x8830, v117
	v_pk_fma_f32 v[8:9], v[8:9], s[30:31], v[12:13] op_sel_hi:[0,1,1]
	v_pk_mul_f32 v[12:13], v[120:121], v[8:9] op_sel:[0,1] op_sel_hi:[0,0] neg_lo:[0,1]
	v_pk_mul_f32 v[14:15], v[8:9], s[8:9] op_sel:[1,0]
	v_pk_fma_f32 v[12:13], v[106:107], v[8:9], v[12:13] op_sel_hi:[0,1,1]
	v_pk_fma_f32 v[8:9], v[8:9], s[30:31], v[14:15] op_sel_hi:[0,1,1]
	v_pk_mul_f32 v[14:15], v[10:11], v[8:9] op_sel:[1,1] op_sel_hi:[1,0] neg_lo:[0,1]
	v_pk_fma_f32 v[8:9], v[10:11], v[8:9], v[14:15] op_sel_hi:[0,1,1]
	ds_write2_b64 v108, v[12:13], v[8:9] offset1:1
	v_add_co_u32_e32 v8, vcc, s27, v122
	v_mov_b32_e32 v107, v120
	s_nop 0
	v_addc_co_u32_e32 v9, vcc, 0, v123, vcc
	ds_write2_b64 v117, v[106:107], v[10:11] offset0:6 offset1:7
	v_add_co_u32_e32 v10, vcc, s5, v122
	v_lshl_add_u64 v[124:125], s[44:45], 0, v[176:177]
	s_nop 0
	v_addc_co_u32_e32 v11, vcc, 0, v123, vcc
	v_add_co_u32_e32 v12, vcc, s27, v124
	v_mov_b32_e32 v111, v118
	s_nop 0
	v_addc_co_u32_e32 v13, vcc, 0, v125, vcc
	ds_write2_b64 v117, v[110:111], v[112:113] offset0:4 offset1:5
	v_add_co_u32_e32 v14, vcc, s5, v124
	v_mov_b32_e32 v110, 1.0
	s_nop 0
	v_addc_co_u32_e32 v15, vcc, 0, v125, vcc
	global_load_ushort v162, v[8:9], off
	global_load_ushort v163, v[10:11], off
	global_load_ushort v160, v[12:13], off
	global_load_ushort v161, v[14:15], off
	v_mov_b32_e32 v111, v177
	v_pk_mul_f32 v[10:11], v[208:209], v[208:209] op_sel:[1,1] op_sel_hi:[0,1] neg_lo:[1,0]
	s_waitcnt lgkmcnt(0)
	v_pk_fma_f32 v[10:11], v[208:209], v[208:209], v[10:11] op_sel_hi:[0,1,1]
	v_pk_mul_f32 v[104:105], v[10:11], v[10:11] op_sel:[1,1] op_sel_hi:[1,0] neg_lo:[0,1]
	v_pk_mul_f32 v[12:13], v[208:209], v[176:177] op_sel:[1,1] op_sel_hi:[0,1] neg_lo:[1,0]
	v_pk_fma_f32 v[104:105], v[10:11], v[10:11], v[104:105] op_sel_hi:[1,0,1]
	v_pk_fma_f32 v[114:115], v[208:209], v[110:111], v[12:13] op_sel_hi:[1,0,1]
	v_pk_mul_f32 v[8:9], v[176:177], v[10:11] op_sel:[1,1] op_sel_hi:[1,0] neg_lo:[0,1]
	v_pk_fma_f32 v[116:117], v[110:111], v[10:11], v[8:9] op_sel_hi:[0,1,1]
	v_pk_mul_f32 v[8:9], v[114:115], v[10:11] op_sel:[1,1] op_sel_hi:[1,0] neg_lo:[0,1]
	v_pk_mul_f32 v[108:109], v[104:105], v[104:105] op_sel:[1,1] op_sel_hi:[1,0] neg_lo:[0,1]
	v_pk_fma_f32 v[118:119], v[10:11], v[114:115], v[8:9] op_sel_hi:[1,0,1]
	v_pk_mul_f32 v[8:9], v[176:177], v[104:105] op_sel:[1,1] op_sel_hi:[1,0] neg_lo:[0,1]
	v_pk_fma_f32 v[120:121], v[110:111], v[104:105], v[8:9] op_sel_hi:[0,1,1]
	v_pk_mul_f32 v[8:9], v[114:115], v[104:105] op_sel:[1,1] op_sel_hi:[1,0] neg_lo:[0,1]
	s_barrier
	v_pk_fma_f32 v[122:123], v[114:115], v[104:105], v[8:9] op_sel_hi:[0,1,1]
	v_pk_mul_f32 v[8:9], v[116:117], v[104:105] op_sel:[1,1] op_sel_hi:[1,0] neg_lo:[0,1]
	v_pk_fma_f32 v[124:125], v[104:105], v[116:117], v[8:9] op_sel_hi:[1,0,1]
	v_pk_mul_f32 v[8:9], v[118:119], v[104:105] op_sel:[1,1] op_sel_hi:[1,0] neg_lo:[0,1]
	v_pk_fma_f32 v[126:127], v[104:105], v[118:119], v[8:9] op_sel_hi:[1,0,1]
	v_pk_fma_f32 v[8:9], v[104:105], v[104:105], v[108:109] op_sel_hi:[1,0,1]
	v_pk_mul_f32 v[10:11], v[176:177], v[8:9] op_sel:[1,1] op_sel_hi:[1,0] neg_lo:[0,1]
	v_pk_fma_f32 v[112:113], v[110:111], v[8:9], v[10:11] op_sel_hi:[0,1,1]
	v_pk_mul_f32 v[10:11], v[114:115], v[8:9] op_sel:[1,1] op_sel_hi:[1,0] neg_lo:[0,1]
	v_pk_fma_f32 v[108:109], v[114:115], v[8:9], v[10:11] op_sel_hi:[0,1,1]
	v_pk_mul_f32 v[10:11], v[116:117], v[8:9] op_sel:[1,1] op_sel_hi:[1,0] neg_lo:[0,1]
	v_pk_fma_f32 v[106:107], v[116:117], v[8:9], v[10:11] op_sel_hi:[0,1,1]
	v_pk_mul_f32 v[10:11], v[118:119], v[8:9] op_sel:[1,1] op_sel_hi:[1,0] neg_lo:[0,1]
	v_pk_fma_f32 v[104:105], v[118:119], v[8:9], v[10:11] op_sel_hi:[0,1,1]
	v_pk_mul_f32 v[10:11], v[120:121], v[8:9] op_sel:[1,1] op_sel_hi:[1,0] neg_lo:[0,1]
	v_pk_fma_f32 v[14:15], v[8:9], v[120:121], v[10:11] op_sel_hi:[1,0,1]
	v_pk_mul_f32 v[10:11], v[122:123], v[8:9] op_sel:[1,1] op_sel_hi:[1,0] neg_lo:[0,1]
	v_pk_fma_f32 v[12:13], v[8:9], v[122:123], v[10:11] op_sel_hi:[1,0,1]
	v_pk_mul_f32 v[10:11], v[124:125], v[8:9] op_sel:[1,1] op_sel_hi:[1,0] neg_lo:[0,1]
	v_pk_mul_f32 v[128:129], v[126:127], v[8:9] op_sel:[1,1] op_sel_hi:[1,0] neg_lo:[0,1]
	v_pk_fma_f32 v[10:11], v[8:9], v[124:125], v[10:11] op_sel_hi:[1,0,1]
	v_pk_fma_f32 v[8:9], v[8:9], v[126:127], v[128:129] op_sel_hi:[1,0,1]
	v_mov_b32_e32 v128, v206
	s_nop 0
	v_lshlrev_b32_sdwa v129, v228, v128 dst_sel:DWORD dst_unused:UNUSED_PAD src0_sel:DWORD src1_sel:BYTE_0
	v_lshrrev_b32_e32 v128, 1, v206
	v_and_b32_e32 v128, 0x78, v128
	v_add3_u32 v168, v207, v129, v128
	ds_read_b64 v[128:129], v168
	ds_read_b64 v[130:131], v168 offset:2176
	ds_read_b64 v[132:133], v168 offset:4352
	ds_read_b64 v[134:135], v168 offset:6528
	ds_read_b64 v[136:137], v168 offset:8704
	ds_read_b64 v[138:139], v168 offset:10880
	ds_read_b64 v[140:141], v168 offset:13056
	ds_read_b64 v[142:143], v168 offset:15232
	ds_read_b64 v[144:145], v168 offset:17408
	ds_read_b64 v[146:147], v168 offset:19584
	ds_read_b64 v[148:149], v168 offset:21760
	ds_read_b64 v[150:151], v168 offset:23936
	ds_read_b64 v[152:153], v168 offset:26112
	ds_read_b64 v[154:155], v168 offset:28288
	ds_read_b64 v[156:157], v168 offset:30464
	ds_read_b64 v[158:159], v168 offset:32640
	s_waitcnt lgkmcnt(7)
	v_pk_add_f32 v[164:165], v[128:129], v[144:145]
	v_pk_add_f32 v[128:129], v[128:129], v[144:145] neg_lo:[0,1] neg_hi:[0,1]
	s_waitcnt lgkmcnt(3)
	v_pk_add_f32 v[144:145], v[136:137], v[152:153]
	v_pk_add_f32 v[136:137], v[136:137], v[152:153] neg_lo:[0,1] neg_hi:[0,1]
	v_pk_add_f32 v[166:167], v[128:129], v[136:137] op_sel:[0,1] op_sel_hi:[1,0] neg_hi:[0,1]
	v_pk_add_f32 v[128:129], v[128:129], v[136:137] op_sel:[0,1] op_sel_hi:[1,0] neg_lo:[0,1]
	v_pk_add_f32 v[152:153], v[130:131], v[146:147]
	v_pk_add_f32 v[130:131], v[130:131], v[146:147] neg_lo:[0,1] neg_hi:[0,1]
	s_waitcnt lgkmcnt(2)
	v_pk_add_f32 v[146:147], v[138:139], v[154:155]
	v_pk_add_f32 v[138:139], v[138:139], v[154:155] neg_lo:[0,1] neg_hi:[0,1]
	v_pk_add_f32 v[136:137], v[164:165], v[144:145]
	v_xor_b32_e32 v155, 0x80000000, v138
	v_mov_b32_e32 v154, v139
	v_pk_add_f32 v[138:139], v[152:153], v[146:147]
	v_pk_add_f32 v[146:147], v[152:153], v[146:147] neg_lo:[0,1] neg_hi:[0,1]
	v_pk_add_f32 v[152:153], v[132:133], v[148:149]
	v_pk_add_f32 v[132:133], v[132:133], v[148:149] neg_lo:[0,1] neg_hi:[0,1]
	s_waitcnt lgkmcnt(1)
	v_pk_add_f32 v[148:149], v[140:141], v[156:157]
	v_pk_add_f32 v[140:141], v[140:141], v[156:157] neg_lo:[0,1] neg_hi:[0,1]
	v_pk_add_f32 v[144:145], v[164:165], v[144:145] neg_lo:[0,1] neg_hi:[0,1]
	v_pk_add_f32 v[164:165], v[130:131], v[154:155]
	v_pk_add_f32 v[130:131], v[130:131], v[154:155] neg_lo:[0,1] neg_hi:[0,1]
	v_xor_b32_e32 v155, 0x80000000, v140
	v_mov_b32_e32 v154, v141
	v_pk_add_f32 v[140:141], v[152:153], v[148:149]
	v_pk_add_f32 v[148:149], v[152:153], v[148:149] neg_lo:[0,1] neg_hi:[0,1]
	v_pk_add_f32 v[152:153], v[134:135], v[150:151]
	v_pk_add_f32 v[134:135], v[134:135], v[150:151] neg_lo:[0,1] neg_hi:[0,1]
	s_waitcnt lgkmcnt(0)
	v_pk_add_f32 v[150:151], v[142:143], v[158:159]
	v_pk_add_f32 v[142:143], v[142:143], v[158:159] neg_lo:[0,1] neg_hi:[0,1]
	v_pk_add_f32 v[156:157], v[132:133], v[154:155]
	v_pk_add_f32 v[132:133], v[132:133], v[154:155] neg_lo:[0,1] neg_hi:[0,1]
	v_pk_add_f32 v[158:159], v[134:135], v[142:143] op_sel:[0,1] op_sel_hi:[1,0] neg_hi:[0,1]
	v_pk_add_f32 v[134:135], v[134:135], v[142:143] op_sel:[0,1] op_sel_hi:[1,0] neg_lo:[0,1]
	v_pk_mul_f32 v[154:155], v[146:147], s[12:13] op_sel:[1,0] op_sel_hi:[0,0] neg_lo:[1,0]
	v_pk_add_f32 v[142:143], v[152:153], v[150:151]
	v_pk_fma_f32 v[146:147], v[146:147], s[12:13], v[154:155] op_sel_hi:[1,0,1] neg_lo:[0,0,1] neg_hi:[0,0,1]
	v_pk_mul_f32 v[154:155], v[130:131], s[36:37] op_sel:[1,0] op_sel_hi:[0,0] neg_lo:[1,0]
	v_pk_add_f32 v[150:151], v[152:153], v[150:151] neg_lo:[0,1] neg_hi:[0,1]
	v_pk_fma_f32 v[130:131], v[130:131], s[22:23], v[154:155] op_sel_hi:[1,0,1] neg_lo:[0,0,1] neg_hi:[0,0,1]
	v_pk_mul_f32 v[154:155], v[156:157], s[12:13] op_sel:[1,0] op_sel_hi:[0,0] neg_lo:[1,0]
	v_pk_fma_f32 v[154:155], v[156:157], s[12:13], v[154:155] op_sel_hi:[1,0,1] neg_lo:[0,0,1] neg_hi:[0,0,1]
	v_pk_fma_f32 v[148:149], v[148:149], 0, v[148:149] op_sel:[0,0,1] op_sel_hi:[1,0,0] neg_hi:[0,0,1]
	v_pk_mul_f32 v[156:157], v[132:133], s[12:13] op_sel:[1,0] op_sel_hi:[0,0] neg_lo:[1,0]
	v_pk_fma_f32 v[132:133], v[132:133], s[18:19], v[156:157] op_sel_hi:[1,0,1] neg_lo:[0,0,1] neg_hi:[0,0,1]
	v_pk_mul_f32 v[156:157], v[158:159], s[36:37] op_sel:[1,0] op_sel_hi:[0,0] neg_lo:[1,0]
	v_pk_mul_f32 v[152:153], v[164:165], s[22:23] op_sel:[1,0] op_sel_hi:[0,0] neg_lo:[1,0]
	v_pk_fma_f32 v[156:157], v[158:159], s[22:23], v[156:157] op_sel_hi:[1,0,1] neg_lo:[0,0,1] neg_hi:[0,0,1]
	v_pk_mul_f32 v[158:159], v[150:151], s[12:13] op_sel:[1,0] op_sel_hi:[0,0] neg_lo:[1,0]
	v_pk_fma_f32 v[152:153], v[164:165], s[36:37], v[152:153] op_sel_hi:[1,0,1] neg_lo:[0,0,1] neg_hi:[0,0,1]
	v_pk_fma_f32 v[150:151], v[150:151], s[18:19], v[158:159] op_sel_hi:[1,0,1] neg_lo:[0,0,1] neg_hi:[0,0,1]
	v_xor_b32_e32 v158, 0x80000000, v135
	v_mov_b32_e32 v159, v134
	v_pk_mul_f32 v[134:135], v[134:135], s[36:37] op_sel_hi:[1,0]
	v_pk_fma_f32 v[134:135], v[158:159], s[22:23], v[134:135] op_sel_hi:[1,0,1] neg_lo:[0,0,1] neg_hi:[0,0,1]
	v_pk_add_f32 v[158:159], v[136:137], v[140:141]
	v_pk_add_f32 v[136:137], v[136:137], v[140:141] neg_lo:[0,1] neg_hi:[0,1]
	v_pk_add_f32 v[140:141], v[138:139], v[142:143]
	v_pk_add_f32 v[138:139], v[138:139], v[142:143] neg_lo:[0,1] neg_hi:[0,1]
	v_xor_b32_e32 v143, 0x80000000, v138
	v_mov_b32_e32 v142, v139
	v_pk_add_f32 v[138:139], v[158:159], v[140:141]
	v_pk_add_f32 v[140:141], v[158:159], v[140:141] neg_lo:[0,1] neg_hi:[0,1]
	v_pk_add_f32 v[158:159], v[152:153], v[156:157]
	v_pk_add_f32 v[152:153], v[152:153], v[156:157] neg_lo:[0,1] neg_hi:[0,1]
	v_pk_add_f32 v[164:165], v[136:137], v[142:143]
	v_pk_add_f32 v[136:137], v[136:137], v[142:143] neg_lo:[0,1] neg_hi:[0,1]
	v_pk_add_f32 v[142:143], v[166:167], v[154:155]
	v_pk_add_f32 v[154:155], v[166:167], v[154:155] neg_lo:[0,1] neg_hi:[0,1]
	v_pk_add_f32 v[166:167], v[154:155], v[152:153] op_sel:[0,1] op_sel_hi:[1,0] neg_hi:[0,1]
	v_pk_add_f32 v[154:155], v[154:155], v[152:153] op_sel:[0,1] op_sel_hi:[1,0] neg_lo:[0,1]
	v_pk_add_f32 v[156:157], v[144:145], v[148:149]
	v_pk_add_f32 v[144:145], v[144:145], v[148:149] neg_lo:[0,1] neg_hi:[0,1]
	v_pk_add_f32 v[148:149], v[146:147], v[150:151]
	v_pk_add_f32 v[146:147], v[146:147], v[150:151] neg_lo:[0,1] neg_hi:[0,1]
	v_pk_add_f32 v[152:153], v[142:143], v[158:159]
	v_pk_add_f32 v[142:143], v[142:143], v[158:159] neg_lo:[0,1] neg_hi:[0,1]
	v_pk_add_f32 v[158:159], v[144:145], v[146:147] op_sel:[0,1] op_sel_hi:[1,0] neg_hi:[0,1]
	v_pk_add_f32 v[144:145], v[144:145], v[146:147] op_sel:[0,1] op_sel_hi:[1,0] neg_lo:[0,1]
	v_pk_add_f32 v[150:151], v[128:129], v[132:133]
	v_pk_add_f32 v[128:129], v[128:129], v[132:133] neg_lo:[0,1] neg_hi:[0,1]
	v_pk_add_f32 v[132:133], v[130:131], v[134:135]
	v_pk_add_f32 v[130:131], v[130:131], v[134:135] neg_lo:[0,1] neg_hi:[0,1]
	v_pk_add_f32 v[146:147], v[156:157], v[148:149]
	v_pk_add_f32 v[148:149], v[156:157], v[148:149] neg_lo:[0,1] neg_hi:[0,1]
	v_pk_add_f32 v[156:157], v[128:129], v[130:131] op_sel:[0,1] op_sel_hi:[1,0] neg_hi:[0,1]
	v_pk_add_f32 v[128:129], v[128:129], v[130:131] op_sel:[0,1] op_sel_hi:[1,0] neg_lo:[0,1]
	v_xor_b32_e32 v134, 0x80000000, v111
	v_mov_b32_e32 v135, v110
	v_pk_mul_f32 v[134:135], v[134:135], v[138:139] op_sel:[0,1]
	v_pk_add_f32 v[130:131], v[150:151], v[132:133]
	v_pk_fma_f32 v[110:111], v[110:111], v[138:139], v[134:135] op_sel_hi:[1,0,1]
	ds_write_b64 v168, v[110:111]
	v_pk_mul_f32 v[110:111], v[114:115], v[152:153] op_sel:[1,1] op_sel_hi:[0,1] neg_lo:[1,0]
	v_pk_add_f32 v[132:133], v[150:151], v[132:133] neg_lo:[0,1] neg_hi:[0,1]
	v_pk_fma_f32 v[110:111], v[114:115], v[152:153], v[110:111] op_sel_hi:[1,0,1]
	ds_write_b64 v168, v[110:111] offset:2176
	v_pk_mul_f32 v[110:111], v[116:117], v[146:147] op_sel:[1,1] op_sel_hi:[0,1] neg_lo:[1,0]
	v_pk_fma_f32 v[110:111], v[116:117], v[146:147], v[110:111] op_sel_hi:[1,0,1]
	ds_write_b64 v168, v[110:111] offset:4352
	v_pk_mul_f32 v[110:111], v[118:119], v[130:131] op_sel:[1,1] op_sel_hi:[0,1] neg_lo:[1,0]
	v_pk_fma_f32 v[110:111], v[118:119], v[130:131], v[110:111] op_sel_hi:[1,0,1]
	ds_write_b64 v168, v[110:111] offset:6528
	v_pk_mul_f32 v[110:111], v[120:121], v[164:165] op_sel:[1,1] op_sel_hi:[0,1] neg_lo:[1,0]
	v_pk_fma_f32 v[110:111], v[120:121], v[164:165], v[110:111] op_sel_hi:[1,0,1]
	ds_write_b64 v168, v[110:111] offset:8704
	v_pk_mul_f32 v[110:111], v[122:123], v[166:167] op_sel:[1,1] op_sel_hi:[0,1] neg_lo:[1,0]
	v_pk_fma_f32 v[110:111], v[122:123], v[166:167], v[110:111] op_sel_hi:[1,0,1]
	ds_write_b64 v168, v[110:111] offset:10880
	v_pk_mul_f32 v[110:111], v[124:125], v[158:159] op_sel:[1,1] op_sel_hi:[0,1] neg_lo:[1,0]
	v_pk_fma_f32 v[110:111], v[124:125], v[158:159], v[110:111] op_sel_hi:[1,0,1]
	ds_write_b64 v168, v[110:111] offset:13056
	v_pk_mul_f32 v[110:111], v[126:127], v[156:157] op_sel:[1,1] op_sel_hi:[0,1] neg_lo:[1,0]
	v_pk_fma_f32 v[110:111], v[126:127], v[156:157], v[110:111] op_sel_hi:[1,0,1]
	ds_write_b64 v168, v[110:111] offset:15232
	v_pk_mul_f32 v[110:111], v[112:113], v[140:141] op_sel:[1,1] op_sel_hi:[0,1] neg_lo:[1,0]
	v_pk_fma_f32 v[110:111], v[112:113], v[140:141], v[110:111] op_sel_hi:[1,0,1]
	ds_write_b64 v168, v[110:111] offset:17408
	v_pk_mul_f32 v[110:111], v[108:109], v[142:143] op_sel:[1,1] op_sel_hi:[0,1] neg_lo:[1,0]
	v_pk_fma_f32 v[108:109], v[108:109], v[142:143], v[110:111] op_sel_hi:[1,0,1]
	ds_write_b64 v168, v[108:109] offset:19584
	v_pk_mul_f32 v[108:109], v[106:107], v[148:149] op_sel:[1,1] op_sel_hi:[0,1] neg_lo:[1,0]
	v_pk_fma_f32 v[106:107], v[106:107], v[148:149], v[108:109] op_sel_hi:[1,0,1]
	ds_write_b64 v168, v[106:107] offset:21760
	v_pk_mul_f32 v[106:107], v[104:105], v[132:133] op_sel:[1,1] op_sel_hi:[0,1] neg_lo:[1,0]
	v_pk_fma_f32 v[104:105], v[104:105], v[132:133], v[106:107] op_sel_hi:[1,0,1]
	ds_write_b64 v168, v[104:105] offset:23936
	v_pk_mul_f32 v[104:105], v[14:15], v[136:137] op_sel:[1,1] op_sel_hi:[0,1] neg_lo:[1,0]
	v_pk_fma_f32 v[14:15], v[14:15], v[136:137], v[104:105] op_sel_hi:[1,0,1]
	ds_write_b64 v168, v[14:15] offset:26112
	v_pk_mul_f32 v[14:15], v[12:13], v[154:155] op_sel:[1,1] op_sel_hi:[0,1] neg_lo:[1,0]
	v_pk_fma_f32 v[12:13], v[12:13], v[154:155], v[14:15] op_sel_hi:[1,0,1]
	ds_write_b64 v168, v[12:13] offset:28288
	v_pk_mul_f32 v[12:13], v[10:11], v[144:145] op_sel:[1,1] op_sel_hi:[0,1] neg_lo:[1,0]
	v_pk_fma_f32 v[10:11], v[10:11], v[144:145], v[12:13] op_sel_hi:[1,0,1]
	ds_write_b64 v168, v[10:11] offset:30464
	v_pk_mul_f32 v[10:11], v[8:9], v[128:129] op_sel:[1,1] op_sel_hi:[0,1] neg_lo:[1,0]
	v_pk_fma_f32 v[8:9], v[8:9], v[128:129], v[10:11] op_sel_hi:[1,0,1]
	ds_write_b64 v168, v[8:9] offset:32640
	v_mov_b32_e32 v116, 1.0
	v_pk_mul_f32 v[10:11], v[210:211], v[210:211] op_sel:[1,1] op_sel_hi:[0,1] neg_lo:[1,0]
	v_mov_b32_e32 v117, v177
	v_pk_fma_f32 v[10:11], v[210:211], v[210:211], v[10:11] op_sel_hi:[0,1,1]
	v_pk_mul_f32 v[104:105], v[10:11], v[10:11] op_sel:[1,1] op_sel_hi:[1,0] neg_lo:[0,1]
	v_pk_mul_f32 v[12:13], v[210:211], v[176:177] op_sel:[1,1] op_sel_hi:[0,1] neg_lo:[1,0]
	v_pk_fma_f32 v[104:105], v[10:11], v[10:11], v[104:105] op_sel_hi:[1,0,1]
	v_pk_fma_f32 v[126:127], v[210:211], v[116:117], v[12:13] op_sel_hi:[1,0,1]
	v_pk_mul_f32 v[8:9], v[176:177], v[10:11] op_sel:[1,1] op_sel_hi:[1,0] neg_lo:[0,1]
	v_pk_fma_f32 v[124:125], v[116:117], v[10:11], v[8:9] op_sel_hi:[0,1,1]
	v_pk_mul_f32 v[8:9], v[126:127], v[10:11] op_sel:[1,1] op_sel_hi:[1,0] neg_lo:[0,1]
	v_pk_mul_f32 v[108:109], v[104:105], v[104:105] op_sel:[1,1] op_sel_hi:[1,0] neg_lo:[0,1]
	v_pk_fma_f32 v[122:123], v[10:11], v[126:127], v[8:9] op_sel_hi:[1,0,1]
	v_pk_mul_f32 v[8:9], v[176:177], v[104:105] op_sel:[1,1] op_sel_hi:[1,0] neg_lo:[0,1]
	v_pk_fma_f32 v[120:121], v[116:117], v[104:105], v[8:9] op_sel_hi:[0,1,1]
	v_pk_mul_f32 v[8:9], v[126:127], v[104:105] op_sel:[1,1] op_sel_hi:[1,0] neg_lo:[0,1]
	s_waitcnt lgkmcnt(0)
	v_pk_fma_f32 v[118:119], v[126:127], v[104:105], v[8:9] op_sel_hi:[0,1,1]
	v_pk_mul_f32 v[8:9], v[124:125], v[104:105] op_sel:[1,1] op_sel_hi:[1,0] neg_lo:[0,1]
	s_barrier
	v_pk_fma_f32 v[114:115], v[104:105], v[124:125], v[8:9] op_sel_hi:[1,0,1]
	v_pk_mul_f32 v[8:9], v[122:123], v[104:105] op_sel:[1,1] op_sel_hi:[1,0] neg_lo:[0,1]
	v_pk_fma_f32 v[112:113], v[104:105], v[122:123], v[8:9] op_sel_hi:[1,0,1]
	v_pk_fma_f32 v[8:9], v[104:105], v[104:105], v[108:109] op_sel_hi:[1,0,1]
	v_pk_mul_f32 v[10:11], v[176:177], v[8:9] op_sel:[1,1] op_sel_hi:[1,0] neg_lo:[0,1]
	v_pk_fma_f32 v[110:111], v[116:117], v[8:9], v[10:11] op_sel_hi:[0,1,1]
	v_pk_mul_f32 v[10:11], v[126:127], v[8:9] op_sel:[1,1] op_sel_hi:[1,0] neg_lo:[0,1]
	v_pk_fma_f32 v[108:109], v[126:127], v[8:9], v[10:11] op_sel_hi:[0,1,1]
	v_pk_mul_f32 v[10:11], v[124:125], v[8:9] op_sel:[1,1] op_sel_hi:[1,0] neg_lo:[0,1]
	v_pk_fma_f32 v[106:107], v[124:125], v[8:9], v[10:11] op_sel_hi:[0,1,1]
	v_pk_mul_f32 v[10:11], v[122:123], v[8:9] op_sel:[1,1] op_sel_hi:[1,0] neg_lo:[0,1]
	v_pk_fma_f32 v[104:105], v[122:123], v[8:9], v[10:11] op_sel_hi:[0,1,1]
	v_pk_mul_f32 v[10:11], v[120:121], v[8:9] op_sel:[1,1] op_sel_hi:[1,0] neg_lo:[0,1]
	v_pk_fma_f32 v[14:15], v[8:9], v[120:121], v[10:11] op_sel_hi:[1,0,1]
	v_pk_mul_f32 v[10:11], v[118:119], v[8:9] op_sel:[1,1] op_sel_hi:[1,0] neg_lo:[0,1]
	v_pk_fma_f32 v[12:13], v[8:9], v[118:119], v[10:11] op_sel_hi:[1,0,1]
	v_pk_mul_f32 v[10:11], v[114:115], v[8:9] op_sel:[1,1] op_sel_hi:[1,0] neg_lo:[0,1]
	v_pk_mul_f32 v[128:129], v[112:113], v[8:9] op_sel:[1,1] op_sel_hi:[1,0] neg_lo:[0,1]
	v_pk_fma_f32 v[10:11], v[8:9], v[114:115], v[10:11] op_sel_hi:[1,0,1]
	v_pk_fma_f32 v[8:9], v[8:9], v[112:113], v[128:129] op_sel_hi:[1,0,1]
	s_nop 0
	v_bfe_u32 v129, v206, 4, 4
	v_and_b32_e32 v128, 15, v206
	v_mul_u32_u24_e32 v129, 0x880, v129
	v_lshlrev_b32_e32 v128, 3, v128
	v_add3_u32 v176, v207, v129, v128
	ds_read2_b64 v[128:131], v176 offset1:17
	ds_read2_b64 v[132:135], v176 offset0:34 offset1:51
	ds_read2_b64 v[136:139], v176 offset0:68 offset1:85
	ds_read2_b64 v[140:143], v176 offset0:136 offset1:153
	ds_read2_b64 v[144:147], v176 offset0:102 offset1:119
	ds_read2_b64 v[148:151], v176 offset0:204 offset1:221
	ds_read2_b64 v[152:155], v176 offset0:170 offset1:187
	ds_read2_b64 v[156:159], v176 offset0:238 offset1:255
	s_waitcnt lgkmcnt(4)
	v_pk_add_f32 v[164:165], v[128:129], v[140:141]
	v_pk_add_f32 v[128:129], v[128:129], v[140:141] neg_lo:[0,1] neg_hi:[0,1]
	s_waitcnt lgkmcnt(2)
	v_pk_add_f32 v[140:141], v[136:137], v[148:149]
	v_pk_add_f32 v[136:137], v[136:137], v[148:149] neg_lo:[0,1] neg_hi:[0,1]
	v_pk_add_f32 v[166:167], v[128:129], v[136:137] op_sel:[0,1] op_sel_hi:[1,0] neg_hi:[0,1]
	v_pk_add_f32 v[128:129], v[128:129], v[136:137] op_sel:[0,1] op_sel_hi:[1,0] neg_lo:[0,1]
	v_pk_add_f32 v[148:149], v[130:131], v[142:143]
	v_pk_add_f32 v[130:131], v[130:131], v[142:143] neg_lo:[0,1] neg_hi:[0,1]
	v_pk_add_f32 v[142:143], v[138:139], v[150:151]
	v_pk_add_f32 v[138:139], v[138:139], v[150:151] neg_lo:[0,1] neg_hi:[0,1]
	v_pk_add_f32 v[136:137], v[164:165], v[140:141]
	v_pk_add_f32 v[140:141], v[164:165], v[140:141] neg_lo:[0,1] neg_hi:[0,1]
	v_pk_add_f32 v[164:165], v[130:131], v[138:139] op_sel:[0,1] op_sel_hi:[1,0] neg_hi:[0,1]
	v_pk_add_f32 v[130:131], v[130:131], v[138:139] op_sel:[0,1] op_sel_hi:[1,0] neg_lo:[0,1]
	s_waitcnt lgkmcnt(0)
	v_pk_add_f32 v[150:151], v[144:145], v[156:157]
	v_pk_add_f32 v[144:145], v[144:145], v[156:157] neg_lo:[0,1] neg_hi:[0,1]
	v_pk_add_f32 v[138:139], v[148:149], v[142:143]
	v_pk_add_f32 v[142:143], v[148:149], v[142:143] neg_lo:[0,1] neg_hi:[0,1]
	v_pk_add_f32 v[148:149], v[132:133], v[152:153]
	v_pk_add_f32 v[132:133], v[132:133], v[152:153] neg_lo:[0,1] neg_hi:[0,1]
	v_pk_add_f32 v[156:157], v[132:133], v[144:145] op_sel:[0,1] op_sel_hi:[1,0] neg_hi:[0,1]
	v_pk_add_f32 v[132:133], v[132:133], v[144:145] op_sel:[0,1] op_sel_hi:[1,0] neg_lo:[0,1]
	v_pk_add_f32 v[152:153], v[146:147], v[158:159]
	v_pk_add_f32 v[146:147], v[146:147], v[158:159] neg_lo:[0,1] neg_hi:[0,1]
	v_pk_add_f32 v[144:145], v[148:149], v[150:151]
	v_pk_add_f32 v[148:149], v[148:149], v[150:151] neg_lo:[0,1] neg_hi:[0,1]
	v_pk_add_f32 v[150:151], v[134:135], v[154:155]
	v_pk_add_f32 v[134:135], v[134:135], v[154:155] neg_lo:[0,1] neg_hi:[0,1]
	v_pk_add_f32 v[158:159], v[134:135], v[146:147] op_sel:[0,1] op_sel_hi:[1,0] neg_hi:[0,1]
	v_pk_add_f32 v[134:135], v[134:135], v[146:147] op_sel:[0,1] op_sel_hi:[1,0] neg_lo:[0,1]
	v_pk_mul_f32 v[154:155], v[142:143], s[12:13] op_sel:[1,0] op_sel_hi:[0,0] neg_lo:[1,0]
	v_pk_add_f32 v[146:147], v[150:151], v[152:153]
	v_pk_fma_f32 v[142:143], v[142:143], s[12:13], v[154:155] op_sel_hi:[1,0,1] neg_lo:[0,0,1] neg_hi:[0,0,1]
	v_pk_mul_f32 v[154:155], v[130:131], s[36:37] op_sel:[1,0] op_sel_hi:[0,0] neg_lo:[1,0]
	v_pk_add_f32 v[150:151], v[150:151], v[152:153] neg_lo:[0,1] neg_hi:[0,1]
	v_pk_fma_f32 v[130:131], v[130:131], s[22:23], v[154:155] op_sel_hi:[1,0,1] neg_lo:[0,0,1] neg_hi:[0,0,1]
	v_pk_mul_f32 v[154:155], v[156:157], s[12:13] op_sel:[1,0] op_sel_hi:[0,0] neg_lo:[1,0]
	v_pk_fma_f32 v[154:155], v[156:157], s[12:13], v[154:155] op_sel_hi:[1,0,1] neg_lo:[0,0,1] neg_hi:[0,0,1]
	v_pk_fma_f32 v[148:149], v[148:149], 0, v[148:149] op_sel:[0,0,1] op_sel_hi:[1,0,0] neg_hi:[0,0,1]
	v_pk_mul_f32 v[156:157], v[132:133], s[12:13] op_sel:[1,0] op_sel_hi:[0,0] neg_lo:[1,0]
	v_pk_fma_f32 v[132:133], v[132:133], s[18:19], v[156:157] op_sel_hi:[1,0,1] neg_lo:[0,0,1] neg_hi:[0,0,1]
	v_pk_mul_f32 v[156:157], v[158:159], s[36:37] op_sel:[1,0] op_sel_hi:[0,0] neg_lo:[1,0]
	v_pk_mul_f32 v[152:153], v[164:165], s[22:23] op_sel:[1,0] op_sel_hi:[0,0] neg_lo:[1,0]
	v_pk_fma_f32 v[156:157], v[158:159], s[22:23], v[156:157] op_sel_hi:[1,0,1] neg_lo:[0,0,1] neg_hi:[0,0,1]
	v_pk_mul_f32 v[158:159], v[150:151], s[12:13] op_sel:[1,0] op_sel_hi:[0,0] neg_lo:[1,0]
	v_pk_fma_f32 v[152:153], v[164:165], s[36:37], v[152:153] op_sel_hi:[1,0,1] neg_lo:[0,0,1] neg_hi:[0,0,1]
	v_pk_fma_f32 v[150:151], v[150:151], s[18:19], v[158:159] op_sel_hi:[1,0,1] neg_lo:[0,0,1] neg_hi:[0,0,1]
	v_xor_b32_e32 v158, 0x80000000, v135
	v_mov_b32_e32 v159, v134
	v_pk_mul_f32 v[134:135], v[134:135], s[36:37] op_sel_hi:[1,0]
	v_pk_fma_f32 v[134:135], v[158:159], s[22:23], v[134:135] op_sel_hi:[1,0,1] neg_lo:[0,0,1] neg_hi:[0,0,1]
	v_pk_add_f32 v[158:159], v[136:137], v[144:145]
	v_pk_add_f32 v[136:137], v[136:137], v[144:145] neg_lo:[0,1] neg_hi:[0,1]
	v_pk_add_f32 v[144:145], v[138:139], v[146:147]
	v_pk_add_f32 v[138:139], v[138:139], v[146:147] neg_lo:[0,1] neg_hi:[0,1]
	v_xor_b32_e32 v147, 0x80000000, v138
	v_mov_b32_e32 v146, v139
	v_pk_add_f32 v[138:139], v[158:159], v[144:145]
	v_pk_add_f32 v[164:165], v[136:137], v[146:147]
	v_pk_add_f32 v[144:145], v[158:159], v[144:145] neg_lo:[0,1] neg_hi:[0,1]
	v_pk_add_f32 v[146:147], v[136:137], v[146:147] neg_lo:[0,1] neg_hi:[0,1]
	v_pk_add_f32 v[136:137], v[166:167], v[154:155]
	v_pk_add_f32 v[158:159], v[152:153], v[156:157]
	v_pk_add_f32 v[152:153], v[152:153], v[156:157] neg_lo:[0,1] neg_hi:[0,1]
	v_pk_add_f32 v[154:155], v[166:167], v[154:155] neg_lo:[0,1] neg_hi:[0,1]
	v_xor_b32_e32 v157, 0x80000000, v152
	v_mov_b32_e32 v156, v153
	v_pk_add_f32 v[152:153], v[136:137], v[158:159]
	v_pk_add_f32 v[168:169], v[136:137], v[158:159] neg_lo:[0,1] neg_hi:[0,1]
	v_pk_add_f32 v[136:137], v[140:141], v[148:149]
	v_pk_add_f32 v[140:141], v[140:141], v[148:149] neg_lo:[0,1] neg_hi:[0,1]
	v_pk_add_f32 v[148:149], v[142:143], v[150:151]
	v_pk_add_f32 v[166:167], v[154:155], v[156:157]
	v_pk_add_f32 v[170:171], v[154:155], v[156:157] neg_lo:[0,1] neg_hi:[0,1]
	v_pk_add_f32 v[142:143], v[142:143], v[150:151] neg_lo:[0,1] neg_hi:[0,1]
	v_pk_add_f32 v[154:155], v[136:137], v[148:149]
	v_pk_add_f32 v[148:149], v[136:137], v[148:149] neg_lo:[0,1] neg_hi:[0,1]
	v_pk_add_f32 v[136:137], v[128:129], v[132:133]
	v_pk_add_f32 v[128:129], v[128:129], v[132:133] neg_lo:[0,1] neg_hi:[0,1]
	v_pk_add_f32 v[132:133], v[130:131], v[134:135]
	v_pk_add_f32 v[130:131], v[130:131], v[134:135] neg_lo:[0,1] neg_hi:[0,1]
	v_xor_b32_e32 v151, 0x80000000, v142
	v_mov_b32_e32 v150, v143
	v_xor_b32_e32 v135, 0x80000000, v130
	v_mov_b32_e32 v134, v131
	v_xor_b32_e32 v142, 0x80000000, v117
	v_mov_b32_e32 v143, v116
	v_pk_add_f32 v[172:173], v[140:141], v[150:151]
	v_pk_add_f32 v[174:175], v[140:141], v[150:151] neg_lo:[0,1] neg_hi:[0,1]
	v_pk_add_f32 v[130:131], v[136:137], v[132:133]
	v_pk_add_f32 v[150:151], v[128:129], v[134:135]
	v_pk_add_f32 v[198:199], v[136:137], v[132:133] neg_lo:[0,1] neg_hi:[0,1]
	v_pk_add_f32 v[200:201], v[128:129], v[134:135] neg_lo:[0,1] neg_hi:[0,1]
	v_pk_mul_f32 v[128:129], v[142:143], v[138:139] op_sel:[0,1]
	v_pk_mul_f32 v[132:133], v[126:127], v[152:153] op_sel:[1,1] op_sel_hi:[0,1] neg_lo:[1,0]
	v_pk_fma_f32 v[128:129], v[116:117], v[138:139], v[128:129] op_sel_hi:[1,0,1]
	v_pk_fma_f32 v[132:133], v[126:127], v[152:153], v[132:133] op_sel_hi:[1,0,1]
	ds_write2_b64 v176, v[128:129], v[132:133] offset1:17
	v_pk_mul_f32 v[128:129], v[124:125], v[154:155] op_sel:[1,1] op_sel_hi:[0,1] neg_lo:[1,0]
	v_pk_mul_f32 v[132:133], v[122:123], v[130:131] op_sel:[1,1] op_sel_hi:[0,1] neg_lo:[1,0]
	v_pk_fma_f32 v[128:129], v[124:125], v[154:155], v[128:129] op_sel_hi:[1,0,1]
	v_pk_fma_f32 v[130:131], v[122:123], v[130:131], v[132:133] op_sel_hi:[1,0,1]
	ds_write2_b64 v176, v[128:129], v[130:131] offset0:34 offset1:51
	v_pk_mul_f32 v[128:129], v[120:121], v[164:165] op_sel:[1,1] op_sel_hi:[0,1] neg_lo:[1,0]
	v_pk_mul_f32 v[130:131], v[118:119], v[166:167] op_sel:[1,1] op_sel_hi:[0,1] neg_lo:[1,0]
	v_pk_fma_f32 v[128:129], v[120:121], v[164:165], v[128:129] op_sel_hi:[1,0,1]
	v_pk_fma_f32 v[130:131], v[118:119], v[166:167], v[130:131] op_sel_hi:[1,0,1]
	ds_write2_b64 v176, v[128:129], v[130:131] offset0:68 offset1:85
	v_pk_mul_f32 v[128:129], v[114:115], v[172:173] op_sel:[1,1] op_sel_hi:[0,1] neg_lo:[1,0]
	v_pk_mul_f32 v[130:131], v[112:113], v[150:151] op_sel:[1,1] op_sel_hi:[0,1] neg_lo:[1,0]
	v_pk_fma_f32 v[128:129], v[114:115], v[172:173], v[128:129] op_sel_hi:[1,0,1]
	v_pk_fma_f32 v[130:131], v[112:113], v[150:151], v[130:131] op_sel_hi:[1,0,1]
	ds_write2_b64 v176, v[128:129], v[130:131] offset0:102 offset1:119
	v_pk_mul_f32 v[128:129], v[110:111], v[144:145] op_sel:[1,1] op_sel_hi:[0,1] neg_lo:[1,0]
	v_pk_mul_f32 v[130:131], v[108:109], v[168:169] op_sel:[1,1] op_sel_hi:[0,1] neg_lo:[1,0]
	v_pk_fma_f32 v[128:129], v[110:111], v[144:145], v[128:129] op_sel_hi:[1,0,1]
	v_pk_fma_f32 v[130:131], v[108:109], v[168:169], v[130:131] op_sel_hi:[1,0,1]
	ds_write2_b64 v176, v[128:129], v[130:131] offset0:136 offset1:153
	v_pk_mul_f32 v[128:129], v[106:107], v[148:149] op_sel:[1,1] op_sel_hi:[0,1] neg_lo:[1,0]
	v_pk_fma_f32 v[128:129], v[106:107], v[148:149], v[128:129] op_sel_hi:[1,0,1]
	v_pk_mul_f32 v[130:131], v[104:105], v[198:199] op_sel:[1,1] op_sel_hi:[0,1] neg_lo:[1,0]
	v_pk_fma_f32 v[130:131], v[104:105], v[198:199], v[130:131] op_sel_hi:[1,0,1]
	ds_write2_b64 v176, v[128:129], v[130:131] offset0:170 offset1:187
	v_pk_mul_f32 v[128:129], v[14:15], v[146:147] op_sel:[1,1] op_sel_hi:[0,1] neg_lo:[1,0]
	v_pk_fma_f32 v[128:129], v[14:15], v[146:147], v[128:129] op_sel_hi:[1,0,1]
	v_pk_mul_f32 v[144:145], v[12:13], v[170:171] op_sel:[1,1] op_sel_hi:[0,1] neg_lo:[1,0]
	v_pk_fma_f32 v[144:145], v[12:13], v[170:171], v[144:145] op_sel_hi:[1,0,1]
	ds_write2_b64 v176, v[128:129], v[144:145] offset0:204 offset1:221
	v_pk_mul_f32 v[144:145], v[10:11], v[174:175] op_sel:[1,1] op_sel_hi:[0,1] neg_lo:[1,0]
	v_pk_fma_f32 v[164:165], v[10:11], v[174:175], v[144:145] op_sel_hi:[1,0,1]
	v_pk_mul_f32 v[166:167], v[8:9], v[200:201] op_sel:[1,1] op_sel_hi:[0,1] neg_lo:[1,0]
	v_pk_fma_f32 v[166:167], v[8:9], v[200:201], v[166:167] op_sel_hi:[1,0,1]
	ds_write2_b64 v176, v[164:165], v[166:167] offset0:238 offset1:255
	s_waitcnt lgkmcnt(0)
	s_barrier
	s_nop 0
	v_and_b32_e32 v129, 0xff, v206
	v_mad_u32_u24 v129, v129, s19, v207
	ds_read2_b64 v[164:167], v129 offset1:1
	ds_read2_b64 v[168:171], v129 offset0:2 offset1:3
	ds_read2_b64 v[172:175], v129 offset0:8 offset1:9
	ds_read2_b64 v[198:201], v129 offset0:4 offset1:5
	ds_read2_b64 v[202:205], v129 offset0:6 offset1:7
	ds_read2_b64 v[232:235], v129 offset0:12 offset1:13
	ds_read2_b64 v[236:239], v129 offset0:10 offset1:11
	ds_read2_b64 v[240:243], v129 offset0:14 offset1:15
	s_waitcnt lgkmcnt(5)
	v_pk_add_f32 v[244:245], v[164:165], v[172:173]
	v_pk_add_f32 v[164:165], v[164:165], v[172:173] neg_lo:[0,1] neg_hi:[0,1]
	s_waitcnt lgkmcnt(2)
	v_pk_add_f32 v[172:173], v[198:199], v[232:233]
	v_pk_add_f32 v[198:199], v[198:199], v[232:233] neg_lo:[0,1] neg_hi:[0,1]
	v_pk_add_f32 v[246:247], v[164:165], v[198:199] op_sel:[0,1] op_sel_hi:[1,0] neg_hi:[0,1]
	v_pk_add_f32 v[164:165], v[164:165], v[198:199] op_sel:[0,1] op_sel_hi:[1,0] neg_lo:[0,1]
	v_pk_add_f32 v[232:233], v[166:167], v[174:175]
	v_pk_add_f32 v[166:167], v[166:167], v[174:175] neg_lo:[0,1] neg_hi:[0,1]
	v_pk_add_f32 v[174:175], v[200:201], v[234:235]
	v_pk_add_f32 v[200:201], v[200:201], v[234:235] neg_lo:[0,1] neg_hi:[0,1]
	v_pk_add_f32 v[198:199], v[244:245], v[172:173]
	v_pk_add_f32 v[172:173], v[244:245], v[172:173] neg_lo:[0,1] neg_hi:[0,1]
	v_pk_add_f32 v[244:245], v[166:167], v[200:201] op_sel:[0,1] op_sel_hi:[1,0] neg_hi:[0,1]
	v_pk_add_f32 v[166:167], v[166:167], v[200:201] op_sel:[0,1] op_sel_hi:[1,0] neg_lo:[0,1]
	s_waitcnt lgkmcnt(0)
	v_pk_add_f32 v[234:235], v[202:203], v[240:241]
	v_pk_add_f32 v[202:203], v[202:203], v[240:241] neg_lo:[0,1] neg_hi:[0,1]
	v_pk_add_f32 v[200:201], v[232:233], v[174:175]
	v_pk_add_f32 v[174:175], v[232:233], v[174:175] neg_lo:[0,1] neg_hi:[0,1]
	v_pk_add_f32 v[232:233], v[168:169], v[236:237]
	v_pk_add_f32 v[168:169], v[168:169], v[236:237] neg_lo:[0,1] neg_hi:[0,1]
	v_pk_add_f32 v[240:241], v[168:169], v[202:203] op_sel:[0,1] op_sel_hi:[1,0] neg_hi:[0,1]
	v_pk_add_f32 v[168:169], v[168:169], v[202:203] op_sel:[0,1] op_sel_hi:[1,0] neg_lo:[0,1]
	v_pk_add_f32 v[236:237], v[204:205], v[242:243]
	v_pk_add_f32 v[204:205], v[204:205], v[242:243] neg_lo:[0,1] neg_hi:[0,1]
	v_pk_add_f32 v[202:203], v[232:233], v[234:235]
	v_pk_add_f32 v[232:233], v[232:233], v[234:235] neg_lo:[0,1] neg_hi:[0,1]
	v_pk_add_f32 v[234:235], v[170:171], v[238:239]
	v_pk_add_f32 v[170:171], v[170:171], v[238:239] neg_lo:[0,1] neg_hi:[0,1]
	v_pk_add_f32 v[242:243], v[170:171], v[204:205] op_sel:[0,1] op_sel_hi:[1,0] neg_hi:[0,1]
	v_pk_add_f32 v[170:171], v[170:171], v[204:205] op_sel:[0,1] op_sel_hi:[1,0] neg_lo:[0,1]
	v_pk_mul_f32 v[238:239], v[174:175], s[12:13] op_sel:[1,0] op_sel_hi:[0,0] neg_lo:[1,0]
	v_pk_add_f32 v[204:205], v[234:235], v[236:237]
	v_pk_fma_f32 v[174:175], v[174:175], s[12:13], v[238:239] op_sel_hi:[1,0,1] neg_lo:[0,0,1] neg_hi:[0,0,1]
	v_pk_mul_f32 v[238:239], v[166:167], s[36:37] op_sel:[1,0] op_sel_hi:[0,0] neg_lo:[1,0]
	v_pk_add_f32 v[234:235], v[234:235], v[236:237] neg_lo:[0,1] neg_hi:[0,1]
	v_pk_fma_f32 v[166:167], v[166:167], s[22:23], v[238:239] op_sel_hi:[1,0,1] neg_lo:[0,0,1] neg_hi:[0,0,1]
	v_pk_mul_f32 v[238:239], v[240:241], s[12:13] op_sel:[1,0] op_sel_hi:[0,0] neg_lo:[1,0]
	v_pk_fma_f32 v[238:239], v[240:241], s[12:13], v[238:239] op_sel_hi:[1,0,1] neg_lo:[0,0,1] neg_hi:[0,0,1]
	v_pk_fma_f32 v[232:233], v[232:233], 0, v[232:233] op_sel:[0,0,1] op_sel_hi:[1,0,0] neg_hi:[0,0,1]
	v_pk_mul_f32 v[240:241], v[168:169], s[12:13] op_sel:[1,0] op_sel_hi:[0,0] neg_lo:[1,0]
	v_pk_fma_f32 v[168:169], v[168:169], s[18:19], v[240:241] op_sel_hi:[1,0,1] neg_lo:[0,0,1] neg_hi:[0,0,1]
	v_pk_mul_f32 v[240:241], v[242:243], s[36:37] op_sel:[1,0] op_sel_hi:[0,0] neg_lo:[1,0]
	v_pk_mul_f32 v[236:237], v[244:245], s[22:23] op_sel:[1,0] op_sel_hi:[0,0] neg_lo:[1,0]
	v_pk_fma_f32 v[240:241], v[242:243], s[22:23], v[240:241] op_sel_hi:[1,0,1] neg_lo:[0,0,1] neg_hi:[0,0,1]
	v_pk_mul_f32 v[242:243], v[234:235], s[12:13] op_sel:[1,0] op_sel_hi:[0,0] neg_lo:[1,0]
	v_pk_fma_f32 v[236:237], v[244:245], s[36:37], v[236:237] op_sel_hi:[1,0,1] neg_lo:[0,0,1] neg_hi:[0,0,1]
	v_pk_fma_f32 v[234:235], v[234:235], s[18:19], v[242:243] op_sel_hi:[1,0,1] neg_lo:[0,0,1] neg_hi:[0,0,1]
	v_xor_b32_e32 v242, 0x80000000, v171
	v_mov_b32_e32 v243, v170
	v_pk_mul_f32 v[170:171], v[170:171], s[36:37] op_sel_hi:[1,0]
	v_pk_fma_f32 v[170:171], v[242:243], s[22:23], v[170:171] op_sel_hi:[1,0,1] neg_lo:[0,0,1] neg_hi:[0,0,1]
	v_pk_add_f32 v[242:243], v[198:199], v[202:203]
	v_pk_add_f32 v[198:199], v[198:199], v[202:203] neg_lo:[0,1] neg_hi:[0,1]
	v_pk_add_f32 v[202:203], v[200:201], v[204:205]
	v_pk_add_f32 v[200:201], v[200:201], v[204:205] neg_lo:[0,1] neg_hi:[0,1]
	v_xor_b32_e32 v205, 0x80000000, v200
	v_mov_b32_e32 v204, v201
	v_pk_add_f32 v[200:201], v[242:243], v[202:203]
	v_pk_add_f32 v[202:203], v[242:243], v[202:203] neg_lo:[0,1] neg_hi:[0,1]
	v_pk_add_f32 v[242:243], v[236:237], v[240:241]
	v_pk_add_f32 v[236:237], v[236:237], v[240:241] neg_lo:[0,1] neg_hi:[0,1]
	v_pk_add_f32 v[244:245], v[198:199], v[204:205]
	v_pk_add_f32 v[198:199], v[198:199], v[204:205] neg_lo:[0,1] neg_hi:[0,1]
	v_pk_add_f32 v[204:205], v[246:247], v[238:239]
	v_pk_add_f32 v[238:239], v[246:247], v[238:239] neg_lo:[0,1] neg_hi:[0,1]
	v_pk_add_f32 v[246:247], v[238:239], v[236:237] op_sel:[0,1] op_sel_hi:[1,0] neg_hi:[0,1]
	v_pk_add_f32 v[238:239], v[238:239], v[236:237] op_sel:[0,1] op_sel_hi:[1,0] neg_lo:[0,1]
	v_pk_add_f32 v[240:241], v[172:173], v[232:233]
	v_pk_add_f32 v[172:173], v[172:173], v[232:233] neg_lo:[0,1] neg_hi:[0,1]
	v_pk_add_f32 v[232:233], v[174:175], v[234:235]
	v_pk_add_f32 v[174:175], v[174:175], v[234:235] neg_lo:[0,1] neg_hi:[0,1]
	v_pk_add_f32 v[236:237], v[204:205], v[242:243]
	v_pk_add_f32 v[204:205], v[204:205], v[242:243] neg_lo:[0,1] neg_hi:[0,1]
	v_pk_add_f32 v[242:243], v[172:173], v[174:175] op_sel:[0,1] op_sel_hi:[1,0] neg_hi:[0,1]
	v_pk_add_f32 v[172:173], v[172:173], v[174:175] op_sel:[0,1] op_sel_hi:[1,0] neg_lo:[0,1]
	v_pk_add_f32 v[234:235], v[164:165], v[168:169]
	v_pk_add_f32 v[164:165], v[164:165], v[168:169] neg_lo:[0,1] neg_hi:[0,1]
	v_pk_add_f32 v[168:169], v[166:167], v[170:171]
	v_pk_add_f32 v[166:167], v[166:167], v[170:171] neg_lo:[0,1] neg_hi:[0,1]
	v_pk_add_f32 v[174:175], v[240:241], v[232:233]
	v_pk_add_f32 v[232:233], v[240:241], v[232:233] neg_lo:[0,1] neg_hi:[0,1]
	v_pk_add_f32 v[240:241], v[164:165], v[166:167] op_sel:[0,1] op_sel_hi:[1,0] neg_hi:[0,1]
	v_pk_add_f32 v[164:165], v[164:165], v[166:167] op_sel:[0,1] op_sel_hi:[1,0] neg_lo:[0,1]
	v_pk_mul_f32 v[170:171], v[66:67], v[200:201] op_sel:[0,1]
	v_pk_add_f32 v[166:167], v[234:235], v[168:169]
	v_pk_fma_f32 v[170:171], v[16:17], v[200:201], v[170:171] op_sel_hi:[1,0,1]
	v_pk_mul_f32 v[200:201], v[68:69], v[244:245] op_sel:[0,1]
	v_pk_add_f32 v[168:169], v[234:235], v[168:169] neg_lo:[0,1] neg_hi:[0,1]
	v_pk_fma_f32 v[200:201], v[18:19], v[244:245], v[200:201] op_sel_hi:[1,0,1]
	v_pk_mul_f32 v[244:245], v[78:79], v[204:205] op_sel:[0,1]
	v_pk_mul_f32 v[234:235], v[70:71], v[202:203] op_sel:[0,1]
	v_pk_fma_f32 v[204:205], v[46:47], v[204:205], v[244:245] op_sel_hi:[1,0,1]
	v_pk_mul_f32 v[244:245], v[80:81], v[238:239] op_sel:[0,1]
	v_pk_fma_f32 v[202:203], v[20:21], v[202:203], v[234:235] op_sel_hi:[1,0,1]
	v_pk_fma_f32 v[238:239], v[48:49], v[238:239], v[244:245] op_sel_hi:[1,0,1]
	v_pk_mul_f32 v[244:245], v[82:83], v[174:175] op_sel:[0,1]
	v_pk_mul_f32 v[234:235], v[72:73], v[198:199] op_sel:[0,1]
	v_pk_fma_f32 v[174:175], v[50:51], v[174:175], v[244:245] op_sel_hi:[1,0,1]
	v_pk_mul_f32 v[244:245], v[84:85], v[242:243] op_sel:[0,1]
	v_pk_fma_f32 v[198:199], v[22:23], v[198:199], v[234:235] op_sel_hi:[1,0,1]
	v_pk_fma_f32 v[242:243], v[52:53], v[242:243], v[244:245] op_sel_hi:[1,0,1]
	v_pk_mul_f32 v[244:245], v[86:87], v[232:233] op_sel:[0,1]
	v_pk_mul_f32 v[234:235], v[74:75], v[236:237] op_sel:[0,1]
	v_pk_fma_f32 v[232:233], v[54:55], v[232:233], v[244:245] op_sel_hi:[1,0,1]
	v_pk_mul_f32 v[244:245], v[88:89], v[172:173] op_sel:[0,1]
	v_pk_fma_f32 v[234:235], v[42:43], v[236:237], v[234:235] op_sel_hi:[1,0,1]
	v_pk_fma_f32 v[172:173], v[56:57], v[172:173], v[244:245] op_sel_hi:[1,0,1]
	v_pk_mul_f32 v[244:245], v[90:91], v[166:167] op_sel:[0,1]
	v_pk_mul_f32 v[236:237], v[76:77], v[246:247] op_sel:[0,1]
	v_pk_fma_f32 v[166:167], v[58:59], v[166:167], v[244:245] op_sel_hi:[1,0,1]
	v_pk_mul_f32 v[244:245], v[92:93], v[240:241] op_sel:[0,1]
	v_pk_fma_f32 v[236:237], v[44:45], v[246:247], v[236:237] op_sel_hi:[1,0,1]
	v_pk_fma_f32 v[240:241], v[60:61], v[240:241], v[244:245] op_sel_hi:[1,0,1]
	v_pk_mul_f32 v[244:245], v[94:95], v[168:169] op_sel:[0,1]
	v_pk_fma_f32 v[168:169], v[62:63], v[168:169], v[244:245] op_sel_hi:[1,0,1]
	v_pk_mul_f32 v[244:245], v[96:97], v[164:165] op_sel:[0,1]
	v_pk_fma_f32 v[164:165], v[64:65], v[164:165], v[244:245] op_sel_hi:[1,0,1]
	v_pk_add_f32 v[244:245], v[170:171], v[202:203]
	v_pk_add_f32 v[170:171], v[170:171], v[202:203] neg_lo:[0,1] neg_hi:[0,1]
	v_pk_add_f32 v[202:203], v[200:201], v[198:199]
	v_pk_add_f32 v[198:199], v[200:201], v[198:199] neg_lo:[0,1] neg_hi:[0,1]
	v_pk_add_f32 v[246:247], v[170:171], v[198:199] op_sel:[0,1] op_sel_hi:[1,0] neg_lo:[0,1]
	v_pk_add_f32 v[170:171], v[170:171], v[198:199] op_sel:[0,1] op_sel_hi:[1,0] neg_hi:[0,1]
	v_pk_add_f32 v[200:201], v[234:235], v[204:205]
	v_pk_add_f32 v[204:205], v[234:235], v[204:205] neg_lo:[0,1] neg_hi:[0,1]
	v_pk_add_f32 v[234:235], v[236:237], v[238:239]
	v_pk_add_f32 v[236:237], v[236:237], v[238:239] neg_lo:[0,1] neg_hi:[0,1]
	v_pk_add_f32 v[198:199], v[244:245], v[202:203]
	v_xor_b32_e32 v238, 0x80000000, v237
	v_mov_b32_e32 v239, v236
	v_pk_add_f32 v[236:237], v[200:201], v[234:235]
	v_pk_add_f32 v[200:201], v[200:201], v[234:235] neg_lo:[0,1] neg_hi:[0,1]
	v_pk_add_f32 v[234:235], v[174:175], v[232:233]
	v_pk_add_f32 v[174:175], v[174:175], v[232:233] neg_lo:[0,1] neg_hi:[0,1]
	v_pk_add_f32 v[232:233], v[242:243], v[172:173]
	v_pk_add_f32 v[172:173], v[242:243], v[172:173] neg_lo:[0,1] neg_hi:[0,1]
	v_pk_add_f32 v[202:203], v[244:245], v[202:203] neg_lo:[0,1] neg_hi:[0,1]
	v_pk_add_f32 v[244:245], v[204:205], v[238:239]
	v_pk_add_f32 v[204:205], v[204:205], v[238:239] neg_lo:[0,1] neg_hi:[0,1]
	v_xor_b32_e32 v238, 0x80000000, v173
	v_mov_b32_e32 v239, v172
	v_pk_add_f32 v[172:173], v[234:235], v[232:233]
	v_pk_add_f32 v[232:233], v[234:235], v[232:233] neg_lo:[0,1] neg_hi:[0,1]
	v_pk_add_f32 v[234:235], v[166:167], v[168:169]
	v_pk_add_f32 v[166:167], v[166:167], v[168:169] neg_lo:[0,1] neg_hi:[0,1]
	v_pk_add_f32 v[168:169], v[240:241], v[164:165]
	v_pk_add_f32 v[164:165], v[240:241], v[164:165] neg_lo:[0,1] neg_hi:[0,1]
	v_pk_add_f32 v[242:243], v[174:175], v[238:239]
	v_pk_add_f32 v[174:175], v[174:175], v[238:239] neg_lo:[0,1] neg_hi:[0,1]
	v_pk_add_f32 v[240:241], v[166:167], v[164:165] op_sel:[0,1] op_sel_hi:[1,0] neg_lo:[0,1]
	v_pk_add_f32 v[166:167], v[166:167], v[164:165] op_sel:[0,1] op_sel_hi:[1,0] neg_hi:[0,1]
	v_pk_mul_f32 v[238:239], v[200:201], s[12:13] op_sel:[1,0] op_sel_hi:[0,0] neg_lo:[1,0]
	v_pk_add_f32 v[164:165], v[234:235], v[168:169]
	v_pk_fma_f32 v[200:201], v[200:201], s[12:13], v[238:239] op_sel_hi:[1,0,1]
	v_pk_mul_f32 v[238:239], v[204:205], s[36:37] op_sel:[1,0] op_sel_hi:[0,0] neg_lo:[1,0]
	v_pk_add_f32 v[168:169], v[234:235], v[168:169] neg_lo:[0,1] neg_hi:[0,1]
	v_pk_fma_f32 v[204:205], v[204:205], s[22:23], v[238:239] op_sel_hi:[1,0,1]
	v_pk_mul_f32 v[238:239], v[242:243], s[12:13] op_sel:[1,0] op_sel_hi:[0,0] neg_lo:[1,0]
	v_pk_fma_f32 v[238:239], v[242:243], s[12:13], v[238:239] op_sel_hi:[1,0,1]
	v_pk_fma_f32 v[232:233], v[232:233], 0, v[232:233] op_sel:[0,0,1] op_sel_hi:[1,0,0] neg_lo:[0,0,1]
	v_xor_b32_e32 v242, 0x80000000, v175
	v_mov_b32_e32 v243, v174
	v_pk_mul_f32 v[174:175], v[174:175], s[12:13] op_sel_hi:[1,0]
	v_pk_fma_f32 v[174:175], v[242:243], s[12:13], v[174:175] op_sel_hi:[1,0,1] neg_lo:[0,0,1] neg_hi:[0,0,1]
	v_pk_mul_f32 v[242:243], v[240:241], s[36:37] op_sel:[1,0] op_sel_hi:[0,0] neg_lo:[1,0]
	v_pk_mul_f32 v[234:235], v[244:245], s[22:23] op_sel:[1,0] op_sel_hi:[0,0] neg_lo:[1,0]
	v_pk_fma_f32 v[240:241], v[240:241], s[22:23], v[242:243] op_sel_hi:[1,0,1]
	v_xor_b32_e32 v242, 0x80000000, v169
	v_mov_b32_e32 v243, v168
	v_pk_mul_f32 v[168:169], v[168:169], s[12:13] op_sel_hi:[1,0]
	v_pk_fma_f32 v[234:235], v[244:245], s[36:37], v[234:235] op_sel_hi:[1,0,1]
	v_pk_fma_f32 v[168:169], v[242:243], s[12:13], v[168:169] op_sel_hi:[1,0,1] neg_lo:[0,0,1] neg_hi:[0,0,1]
	v_pk_mul_f32 v[242:243], v[166:167], s[22:23] op_sel:[1,0] op_sel_hi:[0,0] neg_lo:[1,0]
	v_pk_fma_f32 v[166:167], v[166:167], s[26:27], v[242:243] op_sel_hi:[1,0,1] neg_lo:[0,0,1] neg_hi:[0,0,1]
	v_pk_add_f32 v[242:243], v[198:199], v[172:173]
	v_pk_add_f32 v[172:173], v[198:199], v[172:173] neg_lo:[0,1] neg_hi:[0,1]
	v_pk_add_f32 v[198:199], v[236:237], v[164:165]
	v_pk_add_f32 v[164:165], v[236:237], v[164:165] neg_lo:[0,1] neg_hi:[0,1]
	v_xor_b32_e32 v236, 0x80000000, v165
	v_mov_b32_e32 v237, v164
	v_pk_add_f32 v[164:165], v[242:243], v[198:199]
	v_pk_add_f32 v[198:199], v[242:243], v[198:199] neg_lo:[0,1] neg_hi:[0,1]
	v_pk_add_f32 v[242:243], v[234:235], v[240:241]
	v_pk_add_f32 v[234:235], v[234:235], v[240:241] neg_lo:[0,1] neg_hi:[0,1]
	v_pk_add_f32 v[244:245], v[172:173], v[236:237]
	v_pk_add_f32 v[172:173], v[172:173], v[236:237] neg_lo:[0,1] neg_hi:[0,1]
	v_pk_add_f32 v[236:237], v[246:247], v[238:239]
	v_pk_add_f32 v[238:239], v[246:247], v[238:239] neg_lo:[0,1] neg_hi:[0,1]
	v_pk_add_f32 v[246:247], v[238:239], v[234:235] op_sel:[0,1] op_sel_hi:[1,0] neg_lo:[0,1]
	v_pk_add_f32 v[238:239], v[238:239], v[234:235] op_sel:[0,1] op_sel_hi:[1,0] neg_hi:[0,1]
	v_pk_add_f32 v[240:241], v[202:203], v[232:233]
	v_pk_add_f32 v[202:203], v[202:203], v[232:233] neg_lo:[0,1] neg_hi:[0,1]
	v_pk_add_f32 v[232:233], v[200:201], v[168:169]
	v_pk_add_f32 v[168:169], v[200:201], v[168:169] neg_lo:[0,1] neg_hi:[0,1]
	v_pk_add_f32 v[234:235], v[236:237], v[242:243]
	v_pk_add_f32 v[236:237], v[236:237], v[242:243] neg_lo:[0,1] neg_hi:[0,1]
	v_pk_add_f32 v[242:243], v[202:203], v[168:169] op_sel:[0,1] op_sel_hi:[1,0] neg_lo:[0,1]
	v_pk_add_f32 v[200:201], v[202:203], v[168:169] op_sel:[0,1] op_sel_hi:[1,0] neg_hi:[0,1]
	v_pk_add_f32 v[202:203], v[170:171], v[174:175]
	v_pk_add_f32 v[170:171], v[170:171], v[174:175] neg_lo:[0,1] neg_hi:[0,1]
	v_pk_add_f32 v[174:175], v[204:205], v[166:167]
	v_pk_add_f32 v[166:167], v[204:205], v[166:167] neg_lo:[0,1] neg_hi:[0,1]
	v_pk_add_f32 v[168:169], v[240:241], v[232:233]
	v_xor_b32_e32 v204, 0x80000000, v167
	v_mov_b32_e32 v205, v166
	v_pk_add_f32 v[166:167], v[202:203], v[174:175]
	v_pk_add_f32 v[174:175], v[202:203], v[174:175] neg_lo:[0,1] neg_hi:[0,1]
	v_mov_b32_e32 v202, v116
	v_mov_b32_e32 v203, v142
	v_pk_mul_f32 v[142:143], v[202:203], v[164:165] op_sel_hi:[1,0]
	v_pk_add_f32 v[232:233], v[240:241], v[232:233] neg_lo:[0,1] neg_hi:[0,1]
	v_pk_fma_f32 v[116:117], v[116:117], v[164:165], v[142:143] op_sel:[1,1,0] op_sel_hi:[0,1,1]
	v_pk_mul_f32 v[142:143], v[126:127], v[234:235] op_sel_hi:[1,0] neg_hi:[1,0]
	v_pk_add_f32 v[240:241], v[170:171], v[204:205]
	v_pk_fma_f32 v[126:127], v[126:127], v[234:235], v[142:143] op_sel:[1,1,0] op_sel_hi:[0,1,1]
	ds_write2_b64 v129, v[116:117], v[126:127] offset1:1
	v_pk_mul_f32 v[116:117], v[124:125], v[168:169] op_sel_hi:[1,0] neg_hi:[1,0]
	v_pk_add_f32 v[170:171], v[170:171], v[204:205] neg_lo:[0,1] neg_hi:[0,1]
	v_pk_fma_f32 v[116:117], v[124:125], v[168:169], v[116:117] op_sel:[1,1,0] op_sel_hi:[0,1,1]
	v_pk_mul_f32 v[124:125], v[122:123], v[166:167] op_sel_hi:[1,0] neg_hi:[1,0]
	v_pk_fma_f32 v[122:123], v[122:123], v[166:167], v[124:125] op_sel:[1,1,0] op_sel_hi:[0,1,1]
	ds_write2_b64 v129, v[116:117], v[122:123] offset0:2 offset1:3
	v_pk_mul_f32 v[116:117], v[120:121], v[244:245] op_sel_hi:[1,0] neg_hi:[1,0]
	v_pk_fma_f32 v[116:117], v[120:121], v[244:245], v[116:117] op_sel:[1,1,0] op_sel_hi:[0,1,1]
	v_pk_mul_f32 v[120:121], v[118:119], v[246:247] op_sel_hi:[1,0] neg_hi:[1,0]
	v_pk_fma_f32 v[118:119], v[118:119], v[246:247], v[120:121] op_sel:[1,1,0] op_sel_hi:[0,1,1]
	ds_write2_b64 v129, v[116:117], v[118:119] offset0:4 offset1:5
	v_pk_mul_f32 v[116:117], v[114:115], v[242:243] op_sel_hi:[1,0] neg_hi:[1,0]
	v_pk_fma_f32 v[114:115], v[114:115], v[242:243], v[116:117] op_sel:[1,1,0] op_sel_hi:[0,1,1]
	v_pk_mul_f32 v[116:117], v[112:113], v[240:241] op_sel_hi:[1,0] neg_hi:[1,0]
	v_pk_fma_f32 v[112:113], v[112:113], v[240:241], v[116:117] op_sel:[1,1,0] op_sel_hi:[0,1,1]
	ds_write2_b64 v129, v[114:115], v[112:113] offset0:6 offset1:7
	v_pk_mul_f32 v[112:113], v[110:111], v[198:199] op_sel_hi:[1,0] neg_hi:[1,0]
	v_pk_fma_f32 v[110:111], v[110:111], v[198:199], v[112:113] op_sel:[1,1,0] op_sel_hi:[0,1,1]
	v_pk_mul_f32 v[112:113], v[108:109], v[236:237] op_sel_hi:[1,0] neg_hi:[1,0]
	v_pk_fma_f32 v[108:109], v[108:109], v[236:237], v[112:113] op_sel:[1,1,0] op_sel_hi:[0,1,1]
	ds_write2_b64 v129, v[110:111], v[108:109] offset0:8 offset1:9
	v_pk_mul_f32 v[108:109], v[106:107], v[232:233] op_sel_hi:[1,0] neg_hi:[1,0]
	v_pk_fma_f32 v[106:107], v[106:107], v[232:233], v[108:109] op_sel:[1,1,0] op_sel_hi:[0,1,1]
	v_pk_mul_f32 v[108:109], v[104:105], v[174:175] op_sel_hi:[1,0] neg_hi:[1,0]
	v_pk_fma_f32 v[104:105], v[104:105], v[174:175], v[108:109] op_sel:[1,1,0] op_sel_hi:[0,1,1]
	ds_write2_b64 v129, v[106:107], v[104:105] offset0:10 offset1:11
	v_pk_mul_f32 v[104:105], v[14:15], v[172:173] op_sel_hi:[1,0] neg_hi:[1,0]
	v_pk_fma_f32 v[14:15], v[14:15], v[172:173], v[104:105] op_sel:[1,1,0] op_sel_hi:[0,1,1]
	v_pk_mul_f32 v[104:105], v[12:13], v[238:239] op_sel_hi:[1,0] neg_hi:[1,0]
	v_pk_fma_f32 v[12:13], v[12:13], v[238:239], v[104:105] op_sel:[1,1,0] op_sel_hi:[0,1,1]
	ds_write2_b64 v129, v[14:15], v[12:13] offset0:12 offset1:13
	v_pk_mul_f32 v[12:13], v[10:11], v[200:201] op_sel_hi:[1,0] neg_hi:[1,0]
	v_pk_fma_f32 v[10:11], v[10:11], v[200:201], v[12:13] op_sel:[1,1,0] op_sel_hi:[0,1,1]
	v_pk_mul_f32 v[12:13], v[8:9], v[170:171] op_sel_hi:[1,0] neg_hi:[1,0]
	v_pk_fma_f32 v[8:9], v[8:9], v[170:171], v[12:13] op_sel:[1,1,0] op_sel_hi:[0,1,1]
	ds_write2_b64 v129, v[10:11], v[8:9] offset0:14 offset1:15
	v_mov_b32_e32 v8, v217
	v_mov_b32_e32 v9, v218
	v_mov_b32_e32 v138, v215
	v_xor_b32_e32 v12, 0x80000000, v9
	v_mov_b32_e32 v13, v8
	v_pk_mul_f32 v[10:11], v[12:13], v[218:219] op_sel_hi:[1,0]
	v_mov_b32_e32 v139, v216
	v_pk_fma_f32 v[10:11], v[216:217], v[8:9], v[10:11] op_sel:[1,0,0]
	v_pk_mul_f32 v[104:105], v[10:11], v[10:11] op_sel:[1,1] op_sel_hi:[1,0] neg_lo:[0,1]
	v_pk_mul_f32 v[12:13], v[12:13], v[216:217] op_sel_hi:[1,0]
	v_pk_fma_f32 v[104:105], v[10:11], v[10:11], v[104:105] op_sel_hi:[1,0,1]
	v_pk_fma_f32 v[140:141], v[8:9], v[214:215], v[12:13] op_sel:[0,1,0]
	v_pk_mul_f32 v[8:9], v[216:217], v[10:11] op_sel:[0,1] op_sel_hi:[0,0] neg_lo:[0,1]
	v_pk_fma_f32 v[142:143], v[214:215], v[10:11], v[8:9] op_sel:[1,0,0]
	v_pk_mul_f32 v[8:9], v[140:141], v[10:11] op_sel:[1,1] op_sel_hi:[1,0] neg_lo:[0,1]
	v_pk_mul_f32 v[108:109], v[104:105], v[104:105] op_sel:[1,1] op_sel_hi:[1,0] neg_lo:[0,1]
	v_pk_fma_f32 v[144:145], v[10:11], v[140:141], v[8:9] op_sel_hi:[1,0,1]
	v_pk_mul_f32 v[8:9], v[216:217], v[104:105] op_sel:[0,1] op_sel_hi:[0,0] neg_lo:[0,1]
	v_pk_fma_f32 v[146:147], v[214:215], v[104:105], v[8:9] op_sel:[1,0,0]
	v_pk_mul_f32 v[8:9], v[140:141], v[104:105] op_sel:[1,1] op_sel_hi:[1,0] neg_lo:[0,1]
	s_waitcnt lgkmcnt(0)
	v_pk_fma_f32 v[148:149], v[140:141], v[104:105], v[8:9] op_sel_hi:[0,1,1]
	v_pk_mul_f32 v[8:9], v[142:143], v[104:105] op_sel:[1,1] op_sel_hi:[1,0] neg_lo:[0,1]
	s_barrier
	v_pk_fma_f32 v[150:151], v[104:105], v[142:143], v[8:9] op_sel_hi:[1,0,1]
	v_pk_mul_f32 v[8:9], v[144:145], v[104:105] op_sel:[1,1] op_sel_hi:[1,0] neg_lo:[0,1]
	v_pk_fma_f32 v[152:153], v[104:105], v[144:145], v[8:9] op_sel_hi:[1,0,1]
	v_pk_fma_f32 v[8:9], v[104:105], v[104:105], v[108:109] op_sel_hi:[1,0,1]
	v_pk_mul_f32 v[10:11], v[216:217], v[8:9] op_sel:[0,1] op_sel_hi:[0,0] neg_lo:[0,1]
	v_pk_fma_f32 v[154:155], v[214:215], v[8:9], v[10:11] op_sel:[1,0,0]
	v_pk_mul_f32 v[10:11], v[140:141], v[8:9] op_sel:[1,1] op_sel_hi:[1,0] neg_lo:[0,1]
	v_pk_fma_f32 v[156:157], v[140:141], v[8:9], v[10:11] op_sel_hi:[0,1,1]
	v_pk_mul_f32 v[10:11], v[142:143], v[8:9] op_sel:[1,1] op_sel_hi:[1,0] neg_lo:[0,1]
	v_pk_fma_f32 v[158:159], v[142:143], v[8:9], v[10:11] op_sel_hi:[0,1,1]
	v_pk_mul_f32 v[10:11], v[144:145], v[8:9] op_sel:[1,1] op_sel_hi:[1,0] neg_lo:[0,1]
	v_pk_fma_f32 v[104:105], v[144:145], v[8:9], v[10:11] op_sel_hi:[0,1,1]
	v_pk_mul_f32 v[10:11], v[146:147], v[8:9] op_sel:[1,1] op_sel_hi:[1,0] neg_lo:[0,1]
	v_pk_fma_f32 v[14:15], v[8:9], v[146:147], v[10:11] op_sel_hi:[1,0,1]
	v_pk_mul_f32 v[10:11], v[148:149], v[8:9] op_sel:[1,1] op_sel_hi:[1,0] neg_lo:[0,1]
	v_pk_fma_f32 v[12:13], v[8:9], v[148:149], v[10:11] op_sel_hi:[1,0,1]
	v_pk_mul_f32 v[10:11], v[150:151], v[8:9] op_sel:[1,1] op_sel_hi:[1,0] neg_lo:[0,1]
	v_pk_mul_f32 v[106:107], v[152:153], v[8:9] op_sel:[1,1] op_sel_hi:[1,0] neg_lo:[0,1]
	v_pk_fma_f32 v[10:11], v[8:9], v[150:151], v[10:11] op_sel_hi:[1,0,1]
	v_pk_fma_f32 v[8:9], v[8:9], v[152:153], v[106:107] op_sel_hi:[1,0,1]
	s_nop 0
	v_bfe_u32 v107, v206, 4, 4
	v_and_b32_e32 v106, 15, v206
	v_mul_u32_u24_e32 v107, 0x880, v107
	v_lshlrev_b32_e32 v106, 3, v106
	v_add3_u32 v168, v207, v107, v106
	ds_read2_b64 v[106:109], v168 offset1:17
	ds_read2_b64 v[110:113], v168 offset0:34 offset1:51
	ds_read2_b64 v[114:117], v168 offset0:68 offset1:85
	ds_read2_b64 v[118:121], v168 offset0:136 offset1:153
	ds_read2_b64 v[122:125], v168 offset0:102 offset1:119
	ds_read2_b64 v[126:129], v168 offset0:204 offset1:221
	ds_read2_b64 v[130:133], v168 offset0:170 offset1:187
	ds_read2_b64 v[134:137], v168 offset0:238 offset1:255
	s_waitcnt lgkmcnt(4)
	v_pk_add_f32 v[164:165], v[106:107], v[118:119]
	v_pk_add_f32 v[106:107], v[106:107], v[118:119] neg_lo:[0,1] neg_hi:[0,1]
	s_waitcnt lgkmcnt(2)
	v_pk_add_f32 v[118:119], v[114:115], v[126:127]
	v_pk_add_f32 v[114:115], v[114:115], v[126:127] neg_lo:[0,1] neg_hi:[0,1]
	v_pk_add_f32 v[166:167], v[106:107], v[114:115] op_sel:[0,1] op_sel_hi:[1,0] neg_lo:[0,1]
	v_pk_add_f32 v[106:107], v[106:107], v[114:115] op_sel:[0,1] op_sel_hi:[1,0] neg_hi:[0,1]
	v_pk_add_f32 v[126:127], v[108:109], v[120:121]
	v_pk_add_f32 v[108:109], v[108:109], v[120:121] neg_lo:[0,1] neg_hi:[0,1]
	v_pk_add_f32 v[120:121], v[116:117], v[128:129]
	v_pk_add_f32 v[116:117], v[116:117], v[128:129] neg_lo:[0,1] neg_hi:[0,1]
	v_pk_add_f32 v[114:115], v[164:165], v[118:119]
	v_pk_add_f32 v[118:119], v[164:165], v[118:119] neg_lo:[0,1] neg_hi:[0,1]
	v_pk_add_f32 v[164:165], v[108:109], v[116:117] op_sel:[0,1] op_sel_hi:[1,0] neg_lo:[0,1]
	v_pk_add_f32 v[108:109], v[108:109], v[116:117] op_sel:[0,1] op_sel_hi:[1,0] neg_hi:[0,1]
	s_waitcnt lgkmcnt(0)
	v_pk_add_f32 v[128:129], v[122:123], v[134:135]
	v_pk_add_f32 v[122:123], v[122:123], v[134:135] neg_lo:[0,1] neg_hi:[0,1]
	v_pk_add_f32 v[116:117], v[126:127], v[120:121]
	v_pk_add_f32 v[120:121], v[126:127], v[120:121] neg_lo:[0,1] neg_hi:[0,1]
	v_pk_add_f32 v[126:127], v[110:111], v[130:131]
	v_pk_add_f32 v[110:111], v[110:111], v[130:131] neg_lo:[0,1] neg_hi:[0,1]
	v_pk_add_f32 v[134:135], v[110:111], v[122:123] op_sel:[0,1] op_sel_hi:[1,0] neg_lo:[0,1]
	v_pk_add_f32 v[110:111], v[110:111], v[122:123] op_sel:[0,1] op_sel_hi:[1,0] neg_hi:[0,1]
	v_pk_add_f32 v[130:131], v[124:125], v[136:137]
	v_pk_add_f32 v[124:125], v[124:125], v[136:137] neg_lo:[0,1] neg_hi:[0,1]
	v_pk_add_f32 v[122:123], v[126:127], v[128:129]
	v_pk_add_f32 v[126:127], v[126:127], v[128:129] neg_lo:[0,1] neg_hi:[0,1]
	v_pk_add_f32 v[128:129], v[112:113], v[132:133]
	v_pk_add_f32 v[112:113], v[112:113], v[132:133] neg_lo:[0,1] neg_hi:[0,1]
	v_pk_add_f32 v[136:137], v[112:113], v[124:125] op_sel:[0,1] op_sel_hi:[1,0] neg_lo:[0,1]
	v_pk_add_f32 v[112:113], v[112:113], v[124:125] op_sel:[0,1] op_sel_hi:[1,0] neg_hi:[0,1]
	v_pk_mul_f32 v[132:133], v[120:121], s[12:13] op_sel:[1,0] op_sel_hi:[0,0] neg_lo:[1,0]
	v_pk_add_f32 v[124:125], v[128:129], v[130:131]
	v_pk_fma_f32 v[120:121], v[120:121], s[12:13], v[132:133] op_sel_hi:[1,0,1]
	v_pk_mul_f32 v[132:133], v[108:109], s[36:37] op_sel:[1,0] op_sel_hi:[0,0] neg_lo:[1,0]
	v_pk_add_f32 v[128:129], v[128:129], v[130:131] neg_lo:[0,1] neg_hi:[0,1]
	v_pk_fma_f32 v[108:109], v[108:109], s[22:23], v[132:133] op_sel_hi:[1,0,1]
	v_pk_mul_f32 v[132:133], v[134:135], s[12:13] op_sel:[1,0] op_sel_hi:[0,0] neg_lo:[1,0]
	v_pk_fma_f32 v[132:133], v[134:135], s[12:13], v[132:133] op_sel_hi:[1,0,1]
	v_pk_fma_f32 v[126:127], v[126:127], 0, v[126:127] op_sel:[0,0,1] op_sel_hi:[1,0,0] neg_lo:[0,0,1]
	v_xor_b32_e32 v134, 0x80000000, v111
	v_mov_b32_e32 v135, v110
	v_pk_mul_f32 v[110:111], v[110:111], s[12:13] op_sel_hi:[1,0]
	v_pk_fma_f32 v[110:111], v[134:135], s[12:13], v[110:111] op_sel_hi:[1,0,1] neg_lo:[0,0,1] neg_hi:[0,0,1]
	v_pk_mul_f32 v[134:135], v[136:137], s[36:37] op_sel:[1,0] op_sel_hi:[0,0] neg_lo:[1,0]
	v_pk_mul_f32 v[130:131], v[164:165], s[22:23] op_sel:[1,0] op_sel_hi:[0,0] neg_lo:[1,0]
	v_pk_fma_f32 v[134:135], v[136:137], s[22:23], v[134:135] op_sel_hi:[1,0,1]
	v_xor_b32_e32 v136, 0x80000000, v129
	v_mov_b32_e32 v137, v128
	v_pk_mul_f32 v[128:129], v[128:129], s[12:13] op_sel_hi:[1,0]
	v_pk_fma_f32 v[130:131], v[164:165], s[36:37], v[130:131] op_sel_hi:[1,0,1]
	v_pk_fma_f32 v[128:129], v[136:137], s[12:13], v[128:129] op_sel_hi:[1,0,1] neg_lo:[0,0,1] neg_hi:[0,0,1]
	v_pk_mul_f32 v[136:137], v[112:113], s[22:23] op_sel:[1,0] op_sel_hi:[0,0] neg_lo:[1,0]
	v_pk_fma_f32 v[112:113], v[112:113], s[26:27], v[136:137] op_sel_hi:[1,0,1] neg_lo:[0,0,1] neg_hi:[0,0,1]
	v_pk_add_f32 v[136:137], v[114:115], v[122:123]
	v_pk_add_f32 v[114:115], v[114:115], v[122:123] neg_lo:[0,1] neg_hi:[0,1]
	v_pk_add_f32 v[122:123], v[116:117], v[124:125]
	v_pk_add_f32 v[116:117], v[116:117], v[124:125] neg_lo:[0,1] neg_hi:[0,1]
	v_xor_b32_e32 v124, 0x80000000, v117
	v_mov_b32_e32 v125, v116
	v_pk_add_f32 v[116:117], v[136:137], v[122:123]
	v_pk_add_f32 v[122:123], v[136:137], v[122:123] neg_lo:[0,1] neg_hi:[0,1]
	v_pk_add_f32 v[136:137], v[130:131], v[134:135]
	v_pk_add_f32 v[130:131], v[130:131], v[134:135] neg_lo:[0,1] neg_hi:[0,1]
	v_pk_add_f32 v[164:165], v[114:115], v[124:125]
	v_pk_add_f32 v[114:115], v[114:115], v[124:125] neg_lo:[0,1] neg_hi:[0,1]
	v_pk_add_f32 v[124:125], v[166:167], v[132:133]
	v_pk_add_f32 v[132:133], v[166:167], v[132:133] neg_lo:[0,1] neg_hi:[0,1]
	v_pk_add_f32 v[166:167], v[132:133], v[130:131] op_sel:[0,1] op_sel_hi:[1,0] neg_lo:[0,1]
	v_pk_add_f32 v[132:133], v[132:133], v[130:131] op_sel:[0,1] op_sel_hi:[1,0] neg_hi:[0,1]
	v_pk_add_f32 v[134:135], v[118:119], v[126:127]
	v_pk_add_f32 v[118:119], v[118:119], v[126:127] neg_lo:[0,1] neg_hi:[0,1]
	v_pk_add_f32 v[126:127], v[120:121], v[128:129]
	v_pk_add_f32 v[120:121], v[120:121], v[128:129] neg_lo:[0,1] neg_hi:[0,1]
	v_pk_add_f32 v[130:131], v[124:125], v[136:137]
	v_pk_add_f32 v[124:125], v[124:125], v[136:137] neg_lo:[0,1] neg_hi:[0,1]
	v_pk_add_f32 v[136:137], v[118:119], v[120:121] op_sel:[0,1] op_sel_hi:[1,0] neg_lo:[0,1]
	v_pk_add_f32 v[118:119], v[118:119], v[120:121] op_sel:[0,1] op_sel_hi:[1,0] neg_hi:[0,1]
	v_pk_add_f32 v[128:129], v[106:107], v[110:111]
	v_pk_add_f32 v[106:107], v[106:107], v[110:111] neg_lo:[0,1] neg_hi:[0,1]
	v_pk_add_f32 v[110:111], v[108:109], v[112:113]
	v_pk_add_f32 v[108:109], v[108:109], v[112:113] neg_lo:[0,1] neg_hi:[0,1]
	v_pk_add_f32 v[120:121], v[134:135], v[126:127]
	v_pk_add_f32 v[126:127], v[134:135], v[126:127] neg_lo:[0,1] neg_hi:[0,1]
	v_pk_add_f32 v[134:135], v[106:107], v[108:109] op_sel:[0,1] op_sel_hi:[1,0] neg_lo:[0,1]
	v_pk_add_f32 v[106:107], v[106:107], v[108:109] op_sel:[0,1] op_sel_hi:[1,0] neg_hi:[0,1]
	v_xor_b32_e32 v112, 0x80000000, v139
	v_mov_b32_e32 v113, v138
	v_pk_mul_f32 v[112:113], v[112:113], v[116:117] op_sel:[0,1]
	v_pk_add_f32 v[108:109], v[128:129], v[110:111]
	v_pk_fma_f32 v[112:113], v[138:139], v[116:117], v[112:113] op_sel_hi:[1,0,1]
	v_pk_mul_f32 v[116:117], v[140:141], v[130:131] op_sel:[1,1] op_sel_hi:[0,1] neg_lo:[1,0]
	v_pk_add_f32 v[110:111], v[128:129], v[110:111] neg_lo:[0,1] neg_hi:[0,1]
	v_pk_fma_f32 v[116:117], v[140:141], v[130:131], v[116:117] op_sel_hi:[1,0,1]
	ds_write2_b64 v168, v[112:113], v[116:117] offset1:17
	v_pk_mul_f32 v[112:113], v[142:143], v[120:121] op_sel:[1,1] op_sel_hi:[0,1] neg_lo:[1,0]
	v_pk_mul_f32 v[116:117], v[144:145], v[108:109] op_sel:[1,1] op_sel_hi:[0,1] neg_lo:[1,0]
	v_pk_fma_f32 v[112:113], v[142:143], v[120:121], v[112:113] op_sel_hi:[1,0,1]
	v_pk_fma_f32 v[108:109], v[144:145], v[108:109], v[116:117] op_sel_hi:[1,0,1]
	ds_write2_b64 v168, v[112:113], v[108:109] offset0:34 offset1:51
	v_pk_mul_f32 v[108:109], v[146:147], v[164:165] op_sel:[1,1] op_sel_hi:[0,1] neg_lo:[1,0]
	v_pk_mul_f32 v[112:113], v[148:149], v[166:167] op_sel:[1,1] op_sel_hi:[0,1] neg_lo:[1,0]
	v_pk_fma_f32 v[108:109], v[146:147], v[164:165], v[108:109] op_sel_hi:[1,0,1]
	v_pk_fma_f32 v[112:113], v[148:149], v[166:167], v[112:113] op_sel_hi:[1,0,1]
	ds_write2_b64 v168, v[108:109], v[112:113] offset0:68 offset1:85
	v_pk_mul_f32 v[108:109], v[150:151], v[136:137] op_sel:[1,1] op_sel_hi:[0,1] neg_lo:[1,0]
	v_pk_mul_f32 v[112:113], v[152:153], v[134:135] op_sel:[1,1] op_sel_hi:[0,1] neg_lo:[1,0]
	v_pk_fma_f32 v[108:109], v[150:151], v[136:137], v[108:109] op_sel_hi:[1,0,1]
	v_pk_fma_f32 v[112:113], v[152:153], v[134:135], v[112:113] op_sel_hi:[1,0,1]
	ds_write2_b64 v168, v[108:109], v[112:113] offset0:102 offset1:119
	v_pk_mul_f32 v[108:109], v[154:155], v[122:123] op_sel:[1,1] op_sel_hi:[0,1] neg_lo:[1,0]
	v_pk_mul_f32 v[112:113], v[156:157], v[124:125] op_sel:[1,1] op_sel_hi:[0,1] neg_lo:[1,0]
	v_pk_fma_f32 v[108:109], v[154:155], v[122:123], v[108:109] op_sel_hi:[1,0,1]
	v_pk_fma_f32 v[112:113], v[156:157], v[124:125], v[112:113] op_sel_hi:[1,0,1]
	ds_write2_b64 v168, v[108:109], v[112:113] offset0:136 offset1:153
	v_pk_mul_f32 v[108:109], v[158:159], v[126:127] op_sel:[1,1] op_sel_hi:[0,1] neg_lo:[1,0]
	v_pk_mul_f32 v[112:113], v[104:105], v[110:111] op_sel:[1,1] op_sel_hi:[0,1] neg_lo:[1,0]
	v_pk_fma_f32 v[108:109], v[158:159], v[126:127], v[108:109] op_sel_hi:[1,0,1]
	v_pk_fma_f32 v[104:105], v[104:105], v[110:111], v[112:113] op_sel_hi:[1,0,1]
	ds_write2_b64 v168, v[108:109], v[104:105] offset0:170 offset1:187
	v_pk_mul_f32 v[104:105], v[14:15], v[114:115] op_sel:[1,1] op_sel_hi:[0,1] neg_lo:[1,0]
	v_pk_fma_f32 v[14:15], v[14:15], v[114:115], v[104:105] op_sel_hi:[1,0,1]
	v_pk_mul_f32 v[104:105], v[12:13], v[132:133] op_sel:[1,1] op_sel_hi:[0,1] neg_lo:[1,0]
	v_pk_fma_f32 v[12:13], v[12:13], v[132:133], v[104:105] op_sel_hi:[1,0,1]
	ds_write2_b64 v168, v[14:15], v[12:13] offset0:204 offset1:221
	v_pk_mul_f32 v[12:13], v[10:11], v[118:119] op_sel:[1,1] op_sel_hi:[0,1] neg_lo:[1,0]
	v_pk_fma_f32 v[10:11], v[10:11], v[118:119], v[12:13] op_sel_hi:[1,0,1]
	v_pk_mul_f32 v[12:13], v[8:9], v[106:107] op_sel:[1,1] op_sel_hi:[0,1] neg_lo:[1,0]
	v_pk_fma_f32 v[8:9], v[8:9], v[106:107], v[12:13] op_sel_hi:[1,0,1]
	ds_write2_b64 v168, v[10:11], v[8:9] offset0:238 offset1:255
	v_mov_b32_e32 v8, v206
	s_waitcnt lgkmcnt(0)
	s_barrier
	s_nop 0
	v_lshlrev_b32_sdwa v9, v228, v8 dst_sel:DWORD dst_unused:UNUSED_PAD src0_sel:DWORD src1_sel:BYTE_0
	v_lshrrev_b32_e32 v8, 1, v206
	v_and_b32_e32 v8, 0x78, v8
	v_add3_u32 v132, v207, v9, v8
	ds_read_b64 v[8:9], v132
	ds_read_b64 v[10:11], v132 offset:2176
	ds_read_b64 v[12:13], v132 offset:4352
	ds_read_b64 v[14:15], v132 offset:6528
	ds_read_b64 v[104:105], v132 offset:8704
	ds_read_b64 v[106:107], v132 offset:10880
	ds_read_b64 v[108:109], v132 offset:13056
	ds_read_b64 v[110:111], v132 offset:15232
	ds_read_b64 v[112:113], v132 offset:17408
	ds_read_b64 v[114:115], v132 offset:19584
	ds_read_b64 v[116:117], v132 offset:21760
	ds_read_b64 v[118:119], v132 offset:23936
	ds_read_b64 v[120:121], v132 offset:26112
	ds_read_b64 v[122:123], v132 offset:28288
	ds_read_b64 v[124:125], v132 offset:30464
	ds_read_b64 v[126:127], v132 offset:32640
	s_waitcnt lgkmcnt(7)
	v_pk_add_f32 v[128:129], v[8:9], v[112:113]
	v_pk_add_f32 v[8:9], v[8:9], v[112:113] neg_lo:[0,1] neg_hi:[0,1]
	s_waitcnt lgkmcnt(3)
	v_pk_add_f32 v[112:113], v[104:105], v[120:121]
	v_pk_add_f32 v[104:105], v[104:105], v[120:121] neg_lo:[0,1] neg_hi:[0,1]
	v_pk_add_f32 v[130:131], v[8:9], v[104:105] op_sel:[0,1] op_sel_hi:[1,0] neg_lo:[0,1]
	v_pk_add_f32 v[8:9], v[8:9], v[104:105] op_sel:[0,1] op_sel_hi:[1,0] neg_hi:[0,1]
	v_pk_add_f32 v[120:121], v[10:11], v[114:115]
	v_pk_add_f32 v[10:11], v[10:11], v[114:115] neg_lo:[0,1] neg_hi:[0,1]
	s_waitcnt lgkmcnt(2)
	v_pk_add_f32 v[114:115], v[106:107], v[122:123]
	v_pk_add_f32 v[106:107], v[106:107], v[122:123] neg_lo:[0,1] neg_hi:[0,1]
	v_pk_add_f32 v[104:105], v[128:129], v[112:113]
	v_xor_b32_e32 v122, 0x80000000, v107
	v_mov_b32_e32 v123, v106
	v_pk_add_f32 v[106:107], v[120:121], v[114:115]
	v_pk_add_f32 v[114:115], v[120:121], v[114:115] neg_lo:[0,1] neg_hi:[0,1]
	v_pk_add_f32 v[120:121], v[12:13], v[116:117]
	v_pk_add_f32 v[12:13], v[12:13], v[116:117] neg_lo:[0,1] neg_hi:[0,1]
	s_waitcnt lgkmcnt(1)
	v_pk_add_f32 v[116:117], v[108:109], v[124:125]
	v_pk_add_f32 v[108:109], v[108:109], v[124:125] neg_lo:[0,1] neg_hi:[0,1]
	v_pk_add_f32 v[112:113], v[128:129], v[112:113] neg_lo:[0,1] neg_hi:[0,1]
	v_pk_add_f32 v[128:129], v[10:11], v[122:123]
	v_pk_add_f32 v[10:11], v[10:11], v[122:123] neg_lo:[0,1] neg_hi:[0,1]
	v_xor_b32_e32 v122, 0x80000000, v109
	v_mov_b32_e32 v123, v108
	v_pk_add_f32 v[108:109], v[120:121], v[116:117]
	v_pk_add_f32 v[116:117], v[120:121], v[116:117] neg_lo:[0,1] neg_hi:[0,1]
	v_pk_add_f32 v[120:121], v[14:15], v[118:119]
	v_pk_add_f32 v[14:15], v[14:15], v[118:119] neg_lo:[0,1] neg_hi:[0,1]
	s_waitcnt lgkmcnt(0)
	v_pk_add_f32 v[118:119], v[110:111], v[126:127]
	v_pk_add_f32 v[110:111], v[110:111], v[126:127] neg_lo:[0,1] neg_hi:[0,1]
	v_pk_add_f32 v[124:125], v[12:13], v[122:123]
	v_pk_add_f32 v[12:13], v[12:13], v[122:123] neg_lo:[0,1] neg_hi:[0,1]
	v_pk_add_f32 v[126:127], v[14:15], v[110:111] op_sel:[0,1] op_sel_hi:[1,0] neg_lo:[0,1]
	v_pk_add_f32 v[14:15], v[14:15], v[110:111] op_sel:[0,1] op_sel_hi:[1,0] neg_hi:[0,1]
	v_pk_mul_f32 v[122:123], v[114:115], s[12:13] op_sel:[1,0] op_sel_hi:[0,0] neg_lo:[1,0]
	v_pk_add_f32 v[110:111], v[120:121], v[118:119]
	v_pk_fma_f32 v[114:115], v[114:115], s[12:13], v[122:123] op_sel_hi:[1,0,1]
	v_pk_mul_f32 v[122:123], v[10:11], s[36:37] op_sel:[1,0] op_sel_hi:[0,0] neg_lo:[1,0]
	v_pk_add_f32 v[118:119], v[120:121], v[118:119] neg_lo:[0,1] neg_hi:[0,1]
	v_pk_fma_f32 v[10:11], v[10:11], s[22:23], v[122:123] op_sel_hi:[1,0,1]
	v_pk_mul_f32 v[122:123], v[124:125], s[12:13] op_sel:[1,0] op_sel_hi:[0,0] neg_lo:[1,0]
	v_pk_fma_f32 v[122:123], v[124:125], s[12:13], v[122:123] op_sel_hi:[1,0,1]
	v_pk_fma_f32 v[116:117], v[116:117], 0, v[116:117] op_sel:[0,0,1] op_sel_hi:[1,0,0] neg_lo:[0,0,1]
	v_xor_b32_e32 v124, 0x80000000, v13
	v_mov_b32_e32 v125, v12
	v_pk_mul_f32 v[12:13], v[12:13], s[12:13] op_sel_hi:[1,0]
	v_pk_fma_f32 v[12:13], v[124:125], s[12:13], v[12:13] op_sel_hi:[1,0,1] neg_lo:[0,0,1] neg_hi:[0,0,1]
	v_pk_mul_f32 v[124:125], v[126:127], s[36:37] op_sel:[1,0] op_sel_hi:[0,0] neg_lo:[1,0]
	v_pk_mul_f32 v[120:121], v[128:129], s[22:23] op_sel:[1,0] op_sel_hi:[0,0] neg_lo:[1,0]
	v_pk_fma_f32 v[124:125], v[126:127], s[22:23], v[124:125] op_sel_hi:[1,0,1]
	v_xor_b32_e32 v126, 0x80000000, v119
	v_mov_b32_e32 v127, v118
	v_pk_mul_f32 v[118:119], v[118:119], s[12:13] op_sel_hi:[1,0]
	v_pk_fma_f32 v[120:121], v[128:129], s[36:37], v[120:121] op_sel_hi:[1,0,1]
	v_pk_fma_f32 v[118:119], v[126:127], s[12:13], v[118:119] op_sel_hi:[1,0,1] neg_lo:[0,0,1] neg_hi:[0,0,1]
	v_pk_mul_f32 v[126:127], v[14:15], s[22:23] op_sel:[1,0] op_sel_hi:[0,0] neg_lo:[1,0]
	v_pk_fma_f32 v[14:15], v[14:15], s[26:27], v[126:127] op_sel_hi:[1,0,1] neg_lo:[0,0,1] neg_hi:[0,0,1]
	v_pk_add_f32 v[126:127], v[104:105], v[108:109]
	v_pk_add_f32 v[104:105], v[104:105], v[108:109] neg_lo:[0,1] neg_hi:[0,1]
	v_pk_add_f32 v[108:109], v[106:107], v[110:111]
	v_pk_add_f32 v[106:107], v[106:107], v[110:111] neg_lo:[0,1] neg_hi:[0,1]
	v_xor_b32_e32 v110, 0x80000000, v107
	v_mov_b32_e32 v111, v106
	v_pk_add_f32 v[106:107], v[126:127], v[108:109]
	v_pk_add_f32 v[108:109], v[126:127], v[108:109] neg_lo:[0,1] neg_hi:[0,1]
	v_pk_add_f32 v[126:127], v[120:121], v[124:125]
	v_pk_add_f32 v[120:121], v[120:121], v[124:125] neg_lo:[0,1] neg_hi:[0,1]
	v_pk_add_f32 v[128:129], v[104:105], v[110:111]
	v_pk_add_f32 v[104:105], v[104:105], v[110:111] neg_lo:[0,1] neg_hi:[0,1]
	v_pk_add_f32 v[110:111], v[130:131], v[122:123]
	v_pk_add_f32 v[122:123], v[130:131], v[122:123] neg_lo:[0,1] neg_hi:[0,1]
	v_pk_add_f32 v[130:131], v[122:123], v[120:121] op_sel:[0,1] op_sel_hi:[1,0] neg_lo:[0,1]
	v_pk_add_f32 v[122:123], v[122:123], v[120:121] op_sel:[0,1] op_sel_hi:[1,0] neg_hi:[0,1]
	v_pk_add_f32 v[124:125], v[112:113], v[116:117]
	v_pk_add_f32 v[112:113], v[112:113], v[116:117] neg_lo:[0,1] neg_hi:[0,1]
	v_pk_add_f32 v[116:117], v[114:115], v[118:119]
	v_pk_add_f32 v[114:115], v[114:115], v[118:119] neg_lo:[0,1] neg_hi:[0,1]
	v_pk_add_f32 v[120:121], v[110:111], v[126:127]
	v_pk_add_f32 v[110:111], v[110:111], v[126:127] neg_lo:[0,1] neg_hi:[0,1]
	v_pk_add_f32 v[126:127], v[112:113], v[114:115] op_sel:[0,1] op_sel_hi:[1,0] neg_lo:[0,1]
	v_pk_add_f32 v[112:113], v[112:113], v[114:115] op_sel:[0,1] op_sel_hi:[1,0] neg_hi:[0,1]
	v_pk_add_f32 v[118:119], v[8:9], v[12:13]
	v_pk_add_f32 v[8:9], v[8:9], v[12:13] neg_lo:[0,1] neg_hi:[0,1]
	v_pk_add_f32 v[12:13], v[10:11], v[14:15]
	v_pk_add_f32 v[10:11], v[10:11], v[14:15] neg_lo:[0,1] neg_hi:[0,1]
	v_pk_add_f32 v[114:115], v[124:125], v[116:117]
	v_pk_add_f32 v[116:117], v[124:125], v[116:117] neg_lo:[0,1] neg_hi:[0,1]
	v_pk_add_f32 v[124:125], v[8:9], v[10:11] op_sel:[0,1] op_sel_hi:[1,0] neg_lo:[0,1]
	v_pk_add_f32 v[8:9], v[8:9], v[10:11] op_sel:[0,1] op_sel_hi:[1,0] neg_hi:[0,1]
	v_pk_add_f32 v[10:11], v[118:119], v[12:13]
	v_pk_add_f32 v[12:13], v[118:119], v[12:13] neg_lo:[0,1] neg_hi:[0,1]
	ds_write_b64 v132, v[106:107]
	ds_write_b64 v132, v[128:129] offset:8704
	ds_write_b64 v132, v[108:109] offset:17408
	ds_write_b64 v132, v[104:105] offset:26112
	ds_write_b64 v132, v[120:121] offset:2176
	ds_write_b64 v132, v[130:131] offset:10880
	ds_write_b64 v132, v[110:111] offset:19584
	ds_write_b64 v132, v[122:123] offset:28288
	ds_write_b64 v132, v[114:115] offset:4352
	ds_write_b64 v132, v[126:127] offset:13056
	ds_write_b64 v132, v[116:117] offset:21760
	ds_write_b64 v132, v[112:113] offset:30464
	ds_write_b64 v132, v[10:11] offset:6528
	ds_write_b64 v132, v[124:125] offset:15232
	ds_write_b64 v132, v[12:13] offset:23936
	ds_write_b64 v132, v[8:9] offset:32640
	s_waitcnt lgkmcnt(0)
	s_barrier
	s_waitcnt vmcnt(4)
	v_lshlrev_b32_e32 v9, 16, v4
	v_and_b32_e32 v104, 0x1ff, v212
	v_lshlrev_b32_e32 v105, 3, v104
	v_bfe_u32 v8, v212, 1, 8
	v_add_u32_e32 v106, v105, v8
	v_lshlrev_b32_e32 v8, 16, v0
	v_and_b32_e32 v11, 0xffff0000, v4
	v_and_b32_e32 v10, 0xffff0000, v0
	s_waitcnt vmcnt(2)
	v_lshlrev_b32_e32 v0, 16, v163
	v_lshlrev_b32_e32 v4, 16, v162
	v_cmp_eq_u32_e32 vcc, 0, v104
	v_pk_mul_f32 v[14:15], v[38:39], v[10:11]
	v_cmp_eq_u32_e64 s[0:1], s37, v104
	v_cndmask_b32_e64 v13, v4, 0, vcc
	v_cndmask_b32_e64 v12, v0, 0, vcc
	v_pk_mul_f32 v[12:13], v[24:25], v[12:13]
	v_and_b32_e32 v4, 0xffff0000, v1
	v_pk_fma_f32 v[12:13], v[38:39], v[8:9], v[12:13]
	v_pk_fma_f32 v[8:9], v[24:25], v[8:9], v[14:15]
	v_pk_fma_f32 v[12:13], v[26:27], v[10:11], v[12:13]
	v_lshl_add_u32 v136, v106, 3, 0
	v_pk_add_f32 v[122:123], v[28:29], v[12:13]
	v_lshlrev_b32_e32 v13, 16, v5
	v_lshlrev_b32_e32 v12, 16, v1
	v_pk_mul_f32 v[0:1], v[38:39], v[12:13]
	v_pk_fma_f32 v[8:9], v[26:27], v[12:13], v[8:9]
	v_and_b32_e32 v5, 0xffff0000, v5
	v_pk_fma_f32 v[0:1], v[24:25], v[10:11], v[0:1]
	v_pk_add_f32 v[124:125], v[28:29], v[8:9]
	v_pk_fma_f32 v[0:1], v[26:27], v[4:5], v[0:1]
	v_pk_mul_f32 v[8:9], v[38:39], v[4:5]
	v_pk_add_f32 v[126:127], v[28:29], v[0:1]
	v_lshlrev_b32_e32 v1, 16, v6
	v_lshlrev_b32_e32 v0, 16, v2
	v_pk_fma_f32 v[8:9], v[24:25], v[12:13], v[8:9]
	v_pk_mul_f32 v[10:11], v[38:39], v[0:1]
	v_pk_fma_f32 v[8:9], v[26:27], v[0:1], v[8:9]
	v_pk_fma_f32 v[4:5], v[24:25], v[4:5], v[10:11]
	v_pk_add_f32 v[128:129], v[28:29], v[8:9]
	v_and_b32_e32 v9, 0xffff0000, v6
	v_and_b32_e32 v8, 0xffff0000, v2
	v_pk_fma_f32 v[4:5], v[26:27], v[8:9], v[4:5]
	v_lshlrev_b32_e32 v11, 16, v7
	v_pk_add_f32 v[130:131], v[28:29], v[4:5]
	v_pk_mul_f32 v[4:5], v[38:39], v[8:9]
	v_lshlrev_b32_e32 v10, 16, v3
	v_pk_fma_f32 v[0:1], v[24:25], v[0:1], v[4:5]
	s_waitcnt vmcnt(0)
	v_lshlrev_b32_e32 v6, 16, v161
	v_pk_fma_f32 v[0:1], v[26:27], v[10:11], v[0:1]
	v_cndmask_b32_e64 v6, v6, 0, s[0:1]
	v_pk_add_f32 v[4:5], v[28:29], v[0:1]
	v_and_b32_e32 v0, 0xffff0000, v3
	v_pk_mul_f32 v[2:3], v[38:39], v[10:11]
	v_and_b32_e32 v1, 0xffff0000, v7
	v_pk_fma_f32 v[2:3], v[24:25], v[8:9], v[2:3]
	v_lshlrev_b32_e32 v7, 16, v160
	v_pk_fma_f32 v[2:3], v[26:27], v[0:1], v[2:3]
	v_pk_mul_f32 v[0:1], v[38:39], v[0:1]
	v_cndmask_b32_e64 v7, v7, 0, s[0:1]
	v_pk_fma_f32 v[0:1], v[24:25], v[10:11], v[0:1]
	v_mov_b32_e32 v121, v214
	v_pk_fma_f32 v[0:1], v[26:27], v[6:7], v[0:1]
	v_add_u32_e32 v6, -1, v105
	v_cndmask_b32_e64 v176, v6, 0, vcc
	v_add_u32_e32 v6, 8, v105
	v_cndmask_b32_e64 v105, v6, v229, s[0:1]
	s_add_u32 s0, s39, s42
	v_lshlrev_b32_e32 v6, 4, v104
	v_mov_b32_e32 v7, v177
	s_addc_u32 s1, s46, s43
	v_lshl_add_u64 v[6:7], s[0:1], 0, v[6:7]
	v_add_co_u32_e32 v8, vcc, s5, v6
	v_mov_b32_e32 v120, v213
	s_nop 0
	v_addc_co_u32_e32 v9, vcc, 0, v7, vcc
	v_add_co_u32_e32 v6, vcc, s27, v6
	v_add_u32_e32 v137, 0x8800, v136
	s_nop 0
	v_addc_co_u32_e32 v7, vcc, 0, v7, vcc
	global_load_dwordx4 v[12:15], v[8:9], off
	s_nop 0
	global_load_dwordx4 v[8:11], v[6:7], off
	ds_read2_b64 v[108:111], v137 offset1:1
	v_lshl_add_u64 v[6:7], v[176:177], 1, s[0:1]
	v_lshlrev_b32_e32 v176, 1, v105
	ds_read2_b64 v[104:107], v136 offset1:1
	v_xor_b32_e32 v135, 0x80000000, v121
	v_mov_b32_e32 v134, v120
	v_add_u32_e32 v138, 0x8810, v136
	ds_read2_b64 v[112:115], v138 offset1:1
	s_waitcnt lgkmcnt(2)
	v_pk_mul_f32 v[116:117], v[134:135], v[108:109] op_sel_hi:[1,0]
	v_lshl_add_u64 v[132:133], s[0:1], 0, v[176:177]
	v_pk_fma_f32 v[108:109], v[120:121], v[108:109], v[116:117] op_sel:[1,1,0] op_sel_hi:[0,1,1]
	ds_read2_b64 v[116:119], v136 offset0:2 offset1:3
	s_waitcnt lgkmcnt(2)
	v_pk_add_f32 v[104:105], v[104:105], v[108:109]
	v_mov_b32_e32 v108, v135
	v_pk_mul_f32 v[104:105], v[122:123], v[104:105]
	v_mov_b32_e32 v109, v120
	v_pk_mul_f32 v[108:109], v[108:109], v[104:105] op_sel:[0,1]
	v_pk_mul_f32 v[122:123], v[214:215], s[8:9] op_sel_hi:[0,1]
	v_pk_fma_f32 v[108:109], v[120:121], v[104:105], v[108:109] op_sel_hi:[1,0,1]
	v_pk_fma_f32 v[120:121], v[212:213], s[30:31], v[122:123] op_sel:[1,0,0]
	v_pk_mul_f32 v[134:135], v[120:121], v[110:111] op_sel_hi:[1,0] neg_hi:[1,0]
	v_mov_b32_e32 v110, v111
	v_pk_fma_f32 v[110:111], v[120:121], v[110:111], v[134:135] op_sel:[1,1,0] op_sel_hi:[0,1,1]
	v_pk_add_f32 v[106:107], v[106:107], v[110:111]
	v_add_u32_e32 v122, 0x8820, v136
	v_pk_mul_f32 v[106:107], v[124:125], v[106:107]
	ds_write2_b64 v136, v[104:105], v[106:107] offset1:1
	v_pk_mul_f32 v[104:105], v[120:121], v[106:107] op_sel:[1,1] op_sel_hi:[0,1] neg_lo:[1,0]
	v_pk_add_f32 v[2:3], v[28:29], v[2:3]
	v_pk_fma_f32 v[104:105], v[120:121], v[106:107], v[104:105] op_sel_hi:[1,0,1]
	ds_write2_b64 v137, v[108:109], v[104:105] offset1:1
	v_pk_mul_f32 v[104:105], v[120:121], s[8:9] op_sel:[1,0]
	v_pk_add_f32 v[0:1], v[28:29], v[0:1]
	v_pk_fma_f32 v[104:105], v[120:121], s[30:31], v[104:105] op_sel_hi:[0,1,1]
	s_waitcnt lgkmcnt(3)
	v_pk_mul_f32 v[108:109], v[104:105], v[112:113] op_sel_hi:[1,0] neg_hi:[1,0]
	v_pk_fma_f32 v[108:109], v[104:105], v[112:113], v[108:109] op_sel:[1,1,0] op_sel_hi:[0,1,1]
	s_waitcnt lgkmcnt(2)
	v_pk_add_f32 v[108:109], v[116:117], v[108:109]
	v_pk_mul_f32 v[108:109], v[126:127], v[108:109]
	v_pk_mul_f32 v[110:111], v[104:105], s[8:9] op_sel:[1,0]
	v_pk_mul_f32 v[106:107], v[104:105], v[108:109] op_sel:[1,1] op_sel_hi:[0,1] neg_lo:[1,0]
	v_pk_fma_f32 v[110:111], v[104:105], s[30:31], v[110:111] op_sel_hi:[0,1,1]
	v_pk_fma_f32 v[106:107], v[104:105], v[108:109], v[106:107] op_sel_hi:[1,0,1]
	v_pk_mul_f32 v[112:113], v[110:111], v[114:115] op_sel_hi:[1,0] neg_hi:[1,0]
	v_pk_fma_f32 v[112:113], v[110:111], v[114:115], v[112:113] op_sel:[1,1,0] op_sel_hi:[0,1,1]
	v_pk_add_f32 v[112:113], v[118:119], v[112:113]
	v_pk_mul_f32 v[112:113], v[128:129], v[112:113]
	v_pk_mul_f32 v[104:105], v[110:111], v[112:113] op_sel:[1,1] op_sel_hi:[0,1] neg_lo:[1,0]
	ds_write2_b64 v136, v[108:109], v[112:113] offset0:2 offset1:3
	v_pk_fma_f32 v[104:105], v[110:111], v[112:113], v[104:105] op_sel_hi:[1,0,1]
	ds_write2_b64 v138, v[106:107], v[104:105] offset1:1
	ds_read2_b64 v[104:107], v122 offset1:1
	v_pk_mul_f32 v[108:109], v[110:111], s[8:9] op_sel:[1,0]
	v_pk_fma_f32 v[116:117], v[110:111], s[30:31], v[108:109] op_sel_hi:[0,1,1]
	ds_read2_b64 v[108:111], v136 offset0:4 offset1:5
	s_waitcnt lgkmcnt(1)
	v_pk_mul_f32 v[112:113], v[116:117], v[104:105] op_sel_hi:[1,0] neg_hi:[1,0]
	v_pk_fma_f32 v[104:105], v[116:117], v[104:105], v[112:113] op_sel:[1,1,0] op_sel_hi:[0,1,1]
	s_waitcnt lgkmcnt(0)
	v_pk_add_f32 v[104:105], v[108:109], v[104:105]
	v_pk_mul_f32 v[104:105], v[130:131], v[104:105]
	v_pk_mul_f32 v[108:109], v[116:117], v[104:105] op_sel:[1,1] op_sel_hi:[0,1] neg_lo:[1,0]
	v_pk_mul_f32 v[118:119], v[116:117], s[8:9] op_sel:[1,0]
	v_pk_fma_f32 v[108:109], v[116:117], v[104:105], v[108:109] op_sel_hi:[1,0,1]
	v_pk_fma_f32 v[116:117], v[116:117], s[30:31], v[118:119] op_sel_hi:[0,1,1]
	v_pk_mul_f32 v[120:121], v[116:117], v[106:107] op_sel_hi:[1,0] neg_hi:[1,0]
	v_mov_b32_e32 v106, v107
	v_pk_fma_f32 v[106:107], v[116:117], v[106:107], v[120:121] op_sel:[1,1,0] op_sel_hi:[0,1,1]
	v_pk_add_f32 v[106:107], v[110:111], v[106:107]
	ds_read2_b64 v[112:115], v136 offset0:6 offset1:7
	v_pk_mul_f32 v[4:5], v[4:5], v[106:107]
	v_add_co_u32_e32 v106, vcc, s5, v6
	s_nop 1
	v_addc_co_u32_e32 v107, vcc, 0, v7, vcc
	v_add_co_u32_e32 v110, vcc, s5, v132
	s_nop 1
	v_addc_co_u32_e32 v111, vcc, 0, v133, vcc
	v_add_co_u32_e32 v6, vcc, s27, v6
	s_nop 1
	v_addc_co_u32_e32 v7, vcc, 0, v7, vcc
	v_add_co_u32_e32 v120, vcc, s27, v132
	s_nop 1
	v_addc_co_u32_e32 v121, vcc, 0, v133, vcc
	global_load_ushort v233, v[106:107], off
	global_load_ushort v232, v[110:111], off
	global_load_ushort v231, v[6:7], off
	global_load_ushort v176, v[120:121], off
	v_pk_mul_f32 v[6:7], v[116:117], v[4:5] op_sel:[1,1] op_sel_hi:[0,1] neg_lo:[1,0]
	ds_write2_b64 v136, v[104:105], v[4:5] offset0:4 offset1:5
	v_pk_fma_f32 v[4:5], v[116:117], v[4:5], v[6:7] op_sel_hi:[1,0,1]
	v_add_u32_e32 v110, 0x8830, v136
	ds_write2_b64 v122, v[108:109], v[4:5] offset1:1
	ds_read2_b64 v[4:7], v110 offset1:1
	v_pk_mul_f32 v[104:105], v[116:117], s[8:9] op_sel:[1,0]
	v_mov_b32_e32 v111, v177
	v_pk_fma_f32 v[104:105], v[116:117], s[30:31], v[104:105] op_sel_hi:[0,1,1]
	s_waitcnt lgkmcnt(0)
	v_pk_mul_f32 v[108:109], v[104:105], v[4:5] op_sel_hi:[1,0] neg_hi:[1,0]
	v_pk_fma_f32 v[4:5], v[104:105], v[4:5], v[108:109] op_sel:[1,1,0] op_sel_hi:[0,1,1]
	v_pk_add_f32 v[4:5], v[112:113], v[4:5]
	v_pk_mul_f32 v[2:3], v[2:3], v[4:5]
	v_pk_mul_f32 v[4:5], v[104:105], v[2:3] op_sel:[1,1] op_sel_hi:[0,1] neg_lo:[1,0]
	v_pk_mul_f32 v[106:107], v[104:105], s[8:9] op_sel:[1,0]
	v_pk_fma_f32 v[4:5], v[104:105], v[2:3], v[4:5] op_sel_hi:[1,0,1]
	v_pk_fma_f32 v[104:105], v[104:105], s[30:31], v[106:107] op_sel_hi:[0,1,1]
	v_pk_mul_f32 v[108:109], v[104:105], v[6:7] op_sel_hi:[1,0] neg_hi:[1,0]
	v_mov_b32_e32 v6, v7
	v_pk_fma_f32 v[6:7], v[104:105], v[6:7], v[108:109] op_sel:[1,1,0] op_sel_hi:[0,1,1]
	v_pk_add_f32 v[6:7], v[114:115], v[6:7]
	v_pk_mul_f32 v[0:1], v[0:1], v[6:7]
	ds_write2_b64 v136, v[2:3], v[0:1] offset0:6 offset1:7
	v_pk_mul_f32 v[2:3], v[104:105], v[0:1] op_sel:[1,1] op_sel_hi:[0,1] neg_lo:[1,0]
	v_pk_fma_f32 v[0:1], v[104:105], v[0:1], v[2:3] op_sel_hi:[1,0,1]
	ds_write2_b64 v110, v[4:5], v[0:1] offset1:1
	v_and_b32_e32 v0, 0x1ff, v212
	v_lshl_add_u32 v0, v0, 3, 0
	v_add_u32_e32 v234, 0x11040, v0
	v_mov_b32_e32 v110, 1.0
	v_pk_mul_f32 v[2:3], v[208:209], v[208:209] op_sel:[1,1] op_sel_hi:[0,1] neg_lo:[1,0]
	s_waitcnt lgkmcnt(0)
	v_pk_fma_f32 v[2:3], v[208:209], v[208:209], v[2:3] op_sel_hi:[0,1,1]
	v_pk_mul_f32 v[104:105], v[2:3], v[2:3] op_sel:[1,1] op_sel_hi:[1,0] neg_lo:[0,1]
	v_pk_mul_f32 v[4:5], v[208:209], v[176:177] op_sel:[1,1] op_sel_hi:[0,1] neg_lo:[1,0]
	v_pk_fma_f32 v[104:105], v[2:3], v[2:3], v[104:105] op_sel_hi:[1,0,1]
	v_pk_fma_f32 v[114:115], v[208:209], v[110:111], v[4:5] op_sel_hi:[1,0,1]
	v_pk_mul_f32 v[0:1], v[176:177], v[2:3] op_sel:[1,1] op_sel_hi:[1,0] neg_lo:[0,1]
	v_pk_fma_f32 v[116:117], v[110:111], v[2:3], v[0:1] op_sel_hi:[0,1,1]
	v_pk_mul_f32 v[0:1], v[114:115], v[2:3] op_sel:[1,1] op_sel_hi:[1,0] neg_lo:[0,1]
	v_pk_mul_f32 v[108:109], v[104:105], v[104:105] op_sel:[1,1] op_sel_hi:[1,0] neg_lo:[0,1]
	v_pk_fma_f32 v[118:119], v[2:3], v[114:115], v[0:1] op_sel_hi:[1,0,1]
	v_pk_mul_f32 v[0:1], v[176:177], v[104:105] op_sel:[1,1] op_sel_hi:[1,0] neg_lo:[0,1]
	v_pk_fma_f32 v[120:121], v[110:111], v[104:105], v[0:1] op_sel_hi:[0,1,1]
	v_pk_mul_f32 v[0:1], v[114:115], v[104:105] op_sel:[1,1] op_sel_hi:[1,0] neg_lo:[0,1]
	s_barrier
	v_pk_fma_f32 v[122:123], v[114:115], v[104:105], v[0:1] op_sel_hi:[0,1,1]
	v_pk_mul_f32 v[0:1], v[116:117], v[104:105] op_sel:[1,1] op_sel_hi:[1,0] neg_lo:[0,1]
	v_pk_fma_f32 v[124:125], v[104:105], v[116:117], v[0:1] op_sel_hi:[1,0,1]
	v_pk_mul_f32 v[0:1], v[118:119], v[104:105] op_sel:[1,1] op_sel_hi:[1,0] neg_lo:[0,1]
	v_pk_fma_f32 v[126:127], v[104:105], v[118:119], v[0:1] op_sel_hi:[1,0,1]
	v_pk_fma_f32 v[0:1], v[104:105], v[104:105], v[108:109] op_sel_hi:[1,0,1]
	v_pk_mul_f32 v[2:3], v[176:177], v[0:1] op_sel:[1,1] op_sel_hi:[1,0] neg_lo:[0,1]
	v_pk_fma_f32 v[112:113], v[110:111], v[0:1], v[2:3] op_sel_hi:[0,1,1]
	v_pk_mul_f32 v[2:3], v[114:115], v[0:1] op_sel:[1,1] op_sel_hi:[1,0] neg_lo:[0,1]
	v_pk_fma_f32 v[108:109], v[114:115], v[0:1], v[2:3] op_sel_hi:[0,1,1]
	v_pk_mul_f32 v[2:3], v[116:117], v[0:1] op_sel:[1,1] op_sel_hi:[1,0] neg_lo:[0,1]
	v_pk_fma_f32 v[106:107], v[116:117], v[0:1], v[2:3] op_sel_hi:[0,1,1]
	v_pk_mul_f32 v[2:3], v[118:119], v[0:1] op_sel:[1,1] op_sel_hi:[1,0] neg_lo:[0,1]
	v_pk_fma_f32 v[104:105], v[118:119], v[0:1], v[2:3] op_sel_hi:[0,1,1]
	v_pk_mul_f32 v[2:3], v[120:121], v[0:1] op_sel:[1,1] op_sel_hi:[1,0] neg_lo:[0,1]
	v_pk_fma_f32 v[6:7], v[0:1], v[120:121], v[2:3] op_sel_hi:[1,0,1]
	v_pk_mul_f32 v[2:3], v[122:123], v[0:1] op_sel:[1,1] op_sel_hi:[1,0] neg_lo:[0,1]
	v_pk_fma_f32 v[4:5], v[0:1], v[122:123], v[2:3] op_sel_hi:[1,0,1]
	v_pk_mul_f32 v[2:3], v[124:125], v[0:1] op_sel:[1,1] op_sel_hi:[1,0] neg_lo:[0,1]
	v_pk_mul_f32 v[128:129], v[126:127], v[0:1] op_sel:[1,1] op_sel_hi:[1,0] neg_lo:[0,1]
	v_pk_fma_f32 v[2:3], v[0:1], v[124:125], v[2:3] op_sel_hi:[1,0,1]
	v_pk_fma_f32 v[0:1], v[0:1], v[126:127], v[128:129] op_sel_hi:[1,0,1]
	v_mov_b32_e32 v128, v206
	s_nop 0
	v_lshlrev_b32_sdwa v129, v228, v128 dst_sel:DWORD dst_unused:UNUSED_PAD src0_sel:DWORD src1_sel:BYTE_0
	v_lshrrev_b32_e32 v128, 1, v206
	v_and_b32_e32 v128, 0x78, v128
	v_add3_u32 v164, v207, v129, v128
	ds_read_b64 v[128:129], v164
	ds_read_b64 v[130:131], v164 offset:2176
	ds_read_b64 v[132:133], v164 offset:4352
	ds_read_b64 v[134:135], v164 offset:6528
	ds_read_b64 v[136:137], v164 offset:8704
	ds_read_b64 v[138:139], v164 offset:10880
	ds_read_b64 v[140:141], v164 offset:13056
	ds_read_b64 v[142:143], v164 offset:15232
	ds_read_b64 v[144:145], v164 offset:17408
	ds_read_b64 v[146:147], v164 offset:19584
	ds_read_b64 v[148:149], v164 offset:21760
	ds_read_b64 v[150:151], v164 offset:23936
	ds_read_b64 v[152:153], v164 offset:26112
	ds_read_b64 v[154:155], v164 offset:28288
	ds_read_b64 v[156:157], v164 offset:30464
	ds_read_b64 v[158:159], v164 offset:32640
	s_waitcnt lgkmcnt(7)
	v_pk_add_f32 v[160:161], v[128:129], v[144:145]
	v_pk_add_f32 v[128:129], v[128:129], v[144:145] neg_lo:[0,1] neg_hi:[0,1]
	s_waitcnt lgkmcnt(3)
	v_pk_add_f32 v[144:145], v[136:137], v[152:153]
	v_pk_add_f32 v[136:137], v[136:137], v[152:153] neg_lo:[0,1] neg_hi:[0,1]
	v_pk_add_f32 v[162:163], v[128:129], v[136:137] op_sel:[0,1] op_sel_hi:[1,0] neg_hi:[0,1]
	v_pk_add_f32 v[128:129], v[128:129], v[136:137] op_sel:[0,1] op_sel_hi:[1,0] neg_lo:[0,1]
	v_pk_add_f32 v[152:153], v[130:131], v[146:147]
	v_pk_add_f32 v[130:131], v[130:131], v[146:147] neg_lo:[0,1] neg_hi:[0,1]
	s_waitcnt lgkmcnt(2)
	v_pk_add_f32 v[146:147], v[138:139], v[154:155]
	v_pk_add_f32 v[138:139], v[138:139], v[154:155] neg_lo:[0,1] neg_hi:[0,1]
	v_pk_add_f32 v[136:137], v[160:161], v[144:145]
	v_xor_b32_e32 v155, 0x80000000, v138
	v_mov_b32_e32 v154, v139
	v_pk_add_f32 v[138:139], v[152:153], v[146:147]
	v_pk_add_f32 v[146:147], v[152:153], v[146:147] neg_lo:[0,1] neg_hi:[0,1]
	v_pk_add_f32 v[152:153], v[132:133], v[148:149]
	v_pk_add_f32 v[132:133], v[132:133], v[148:149] neg_lo:[0,1] neg_hi:[0,1]
	s_waitcnt lgkmcnt(1)
	v_pk_add_f32 v[148:149], v[140:141], v[156:157]
	v_pk_add_f32 v[140:141], v[140:141], v[156:157] neg_lo:[0,1] neg_hi:[0,1]
	v_pk_add_f32 v[144:145], v[160:161], v[144:145] neg_lo:[0,1] neg_hi:[0,1]
	v_pk_add_f32 v[160:161], v[130:131], v[154:155]
	v_pk_add_f32 v[130:131], v[130:131], v[154:155] neg_lo:[0,1] neg_hi:[0,1]
	v_xor_b32_e32 v155, 0x80000000, v140
	v_mov_b32_e32 v154, v141
	v_pk_add_f32 v[140:141], v[152:153], v[148:149]
	v_pk_add_f32 v[148:149], v[152:153], v[148:149] neg_lo:[0,1] neg_hi:[0,1]
	v_pk_add_f32 v[152:153], v[134:135], v[150:151]
	v_pk_add_f32 v[134:135], v[134:135], v[150:151] neg_lo:[0,1] neg_hi:[0,1]
	s_waitcnt lgkmcnt(0)
	v_pk_add_f32 v[150:151], v[142:143], v[158:159]
	v_pk_add_f32 v[142:143], v[142:143], v[158:159] neg_lo:[0,1] neg_hi:[0,1]
	v_pk_add_f32 v[156:157], v[132:133], v[154:155]
	v_pk_add_f32 v[132:133], v[132:133], v[154:155] neg_lo:[0,1] neg_hi:[0,1]
	v_pk_add_f32 v[158:159], v[134:135], v[142:143] op_sel:[0,1] op_sel_hi:[1,0] neg_hi:[0,1]
	v_pk_add_f32 v[134:135], v[134:135], v[142:143] op_sel:[0,1] op_sel_hi:[1,0] neg_lo:[0,1]
	v_pk_mul_f32 v[154:155], v[146:147], s[12:13] op_sel:[1,0] op_sel_hi:[0,0] neg_lo:[1,0]
	v_pk_add_f32 v[142:143], v[152:153], v[150:151]
	v_pk_fma_f32 v[146:147], v[146:147], s[12:13], v[154:155] op_sel_hi:[1,0,1] neg_lo:[0,0,1] neg_hi:[0,0,1]
	v_pk_mul_f32 v[154:155], v[130:131], s[36:37] op_sel:[1,0] op_sel_hi:[0,0] neg_lo:[1,0]
	v_pk_add_f32 v[150:151], v[152:153], v[150:151] neg_lo:[0,1] neg_hi:[0,1]
	v_pk_fma_f32 v[130:131], v[130:131], s[22:23], v[154:155] op_sel_hi:[1,0,1] neg_lo:[0,0,1] neg_hi:[0,0,1]
	v_pk_mul_f32 v[154:155], v[156:157], s[12:13] op_sel:[1,0] op_sel_hi:[0,0] neg_lo:[1,0]
	v_pk_fma_f32 v[154:155], v[156:157], s[12:13], v[154:155] op_sel_hi:[1,0,1] neg_lo:[0,0,1] neg_hi:[0,0,1]
	v_pk_fma_f32 v[148:149], v[148:149], 0, v[148:149] op_sel:[0,0,1] op_sel_hi:[1,0,0] neg_hi:[0,0,1]
	v_pk_mul_f32 v[156:157], v[132:133], s[12:13] op_sel:[1,0] op_sel_hi:[0,0] neg_lo:[1,0]
	v_pk_fma_f32 v[132:133], v[132:133], s[18:19], v[156:157] op_sel_hi:[1,0,1] neg_lo:[0,0,1] neg_hi:[0,0,1]
	v_pk_mul_f32 v[156:157], v[158:159], s[36:37] op_sel:[1,0] op_sel_hi:[0,0] neg_lo:[1,0]
	v_pk_mul_f32 v[152:153], v[160:161], s[22:23] op_sel:[1,0] op_sel_hi:[0,0] neg_lo:[1,0]
	v_pk_fma_f32 v[156:157], v[158:159], s[22:23], v[156:157] op_sel_hi:[1,0,1] neg_lo:[0,0,1] neg_hi:[0,0,1]
	v_pk_mul_f32 v[158:159], v[150:151], s[12:13] op_sel:[1,0] op_sel_hi:[0,0] neg_lo:[1,0]
	v_pk_fma_f32 v[152:153], v[160:161], s[36:37], v[152:153] op_sel_hi:[1,0,1] neg_lo:[0,0,1] neg_hi:[0,0,1]
	v_pk_fma_f32 v[150:151], v[150:151], s[18:19], v[158:159] op_sel_hi:[1,0,1] neg_lo:[0,0,1] neg_hi:[0,0,1]
	v_xor_b32_e32 v158, 0x80000000, v135
	v_mov_b32_e32 v159, v134
	v_pk_mul_f32 v[134:135], v[134:135], s[36:37] op_sel_hi:[1,0]
	v_pk_fma_f32 v[134:135], v[158:159], s[22:23], v[134:135] op_sel_hi:[1,0,1] neg_lo:[0,0,1] neg_hi:[0,0,1]
	v_pk_add_f32 v[158:159], v[136:137], v[140:141]
	v_pk_add_f32 v[136:137], v[136:137], v[140:141] neg_lo:[0,1] neg_hi:[0,1]
	v_pk_add_f32 v[140:141], v[138:139], v[142:143]
	v_pk_add_f32 v[138:139], v[138:139], v[142:143] neg_lo:[0,1] neg_hi:[0,1]
	v_xor_b32_e32 v143, 0x80000000, v138
	v_mov_b32_e32 v142, v139
	v_pk_add_f32 v[138:139], v[158:159], v[140:141]
	v_pk_add_f32 v[140:141], v[158:159], v[140:141] neg_lo:[0,1] neg_hi:[0,1]
	v_pk_add_f32 v[158:159], v[152:153], v[156:157]
	v_pk_add_f32 v[152:153], v[152:153], v[156:157] neg_lo:[0,1] neg_hi:[0,1]
	v_pk_add_f32 v[160:161], v[136:137], v[142:143]
	v_pk_add_f32 v[136:137], v[136:137], v[142:143] neg_lo:[0,1] neg_hi:[0,1]
	v_pk_add_f32 v[142:143], v[162:163], v[154:155]
	v_pk_add_f32 v[154:155], v[162:163], v[154:155] neg_lo:[0,1] neg_hi:[0,1]
	v_pk_add_f32 v[162:163], v[154:155], v[152:153] op_sel:[0,1] op_sel_hi:[1,0] neg_hi:[0,1]
	v_pk_add_f32 v[154:155], v[154:155], v[152:153] op_sel:[0,1] op_sel_hi:[1,0] neg_lo:[0,1]
	v_pk_add_f32 v[156:157], v[144:145], v[148:149]
	v_pk_add_f32 v[144:145], v[144:145], v[148:149] neg_lo:[0,1] neg_hi:[0,1]
	v_pk_add_f32 v[148:149], v[146:147], v[150:151]
	v_pk_add_f32 v[146:147], v[146:147], v[150:151] neg_lo:[0,1] neg_hi:[0,1]
	v_pk_add_f32 v[152:153], v[142:143], v[158:159]
	v_pk_add_f32 v[142:143], v[142:143], v[158:159] neg_lo:[0,1] neg_hi:[0,1]
	v_pk_add_f32 v[158:159], v[144:145], v[146:147] op_sel:[0,1] op_sel_hi:[1,0] neg_hi:[0,1]
	v_pk_add_f32 v[144:145], v[144:145], v[146:147] op_sel:[0,1] op_sel_hi:[1,0] neg_lo:[0,1]
	v_pk_add_f32 v[150:151], v[128:129], v[132:133]
	v_pk_add_f32 v[128:129], v[128:129], v[132:133] neg_lo:[0,1] neg_hi:[0,1]
	v_pk_add_f32 v[132:133], v[130:131], v[134:135]
	v_pk_add_f32 v[130:131], v[130:131], v[134:135] neg_lo:[0,1] neg_hi:[0,1]
	v_pk_add_f32 v[146:147], v[156:157], v[148:149]
	v_pk_add_f32 v[148:149], v[156:157], v[148:149] neg_lo:[0,1] neg_hi:[0,1]
	v_pk_add_f32 v[156:157], v[128:129], v[130:131] op_sel:[0,1] op_sel_hi:[1,0] neg_hi:[0,1]
	v_pk_add_f32 v[128:129], v[128:129], v[130:131] op_sel:[0,1] op_sel_hi:[1,0] neg_lo:[0,1]
	v_xor_b32_e32 v134, 0x80000000, v111
	v_mov_b32_e32 v135, v110
	v_pk_mul_f32 v[134:135], v[134:135], v[138:139] op_sel:[0,1]
	v_pk_add_f32 v[130:131], v[150:151], v[132:133]
	v_pk_fma_f32 v[110:111], v[110:111], v[138:139], v[134:135] op_sel_hi:[1,0,1]
	ds_write_b64 v164, v[110:111]
	v_pk_mul_f32 v[110:111], v[114:115], v[152:153] op_sel:[1,1] op_sel_hi:[0,1] neg_lo:[1,0]
	v_pk_add_f32 v[132:133], v[150:151], v[132:133] neg_lo:[0,1] neg_hi:[0,1]
	v_pk_fma_f32 v[110:111], v[114:115], v[152:153], v[110:111] op_sel_hi:[1,0,1]
	ds_write_b64 v164, v[110:111] offset:2176
	v_pk_mul_f32 v[110:111], v[116:117], v[146:147] op_sel:[1,1] op_sel_hi:[0,1] neg_lo:[1,0]
	v_pk_fma_f32 v[110:111], v[116:117], v[146:147], v[110:111] op_sel_hi:[1,0,1]
	ds_write_b64 v164, v[110:111] offset:4352
	v_pk_mul_f32 v[110:111], v[118:119], v[130:131] op_sel:[1,1] op_sel_hi:[0,1] neg_lo:[1,0]
	v_pk_fma_f32 v[110:111], v[118:119], v[130:131], v[110:111] op_sel_hi:[1,0,1]
	ds_write_b64 v164, v[110:111] offset:6528
	v_pk_mul_f32 v[110:111], v[120:121], v[160:161] op_sel:[1,1] op_sel_hi:[0,1] neg_lo:[1,0]
	v_pk_fma_f32 v[110:111], v[120:121], v[160:161], v[110:111] op_sel_hi:[1,0,1]
	ds_write_b64 v164, v[110:111] offset:8704
	v_pk_mul_f32 v[110:111], v[122:123], v[162:163] op_sel:[1,1] op_sel_hi:[0,1] neg_lo:[1,0]
	v_pk_fma_f32 v[110:111], v[122:123], v[162:163], v[110:111] op_sel_hi:[1,0,1]
	ds_write_b64 v164, v[110:111] offset:10880
	v_pk_mul_f32 v[110:111], v[124:125], v[158:159] op_sel:[1,1] op_sel_hi:[0,1] neg_lo:[1,0]
	v_pk_fma_f32 v[110:111], v[124:125], v[158:159], v[110:111] op_sel_hi:[1,0,1]
	ds_write_b64 v164, v[110:111] offset:13056
	v_pk_mul_f32 v[110:111], v[126:127], v[156:157] op_sel:[1,1] op_sel_hi:[0,1] neg_lo:[1,0]
	v_pk_fma_f32 v[110:111], v[126:127], v[156:157], v[110:111] op_sel_hi:[1,0,1]
	ds_write_b64 v164, v[110:111] offset:15232
	v_pk_mul_f32 v[110:111], v[112:113], v[140:141] op_sel:[1,1] op_sel_hi:[0,1] neg_lo:[1,0]
	v_pk_fma_f32 v[110:111], v[112:113], v[140:141], v[110:111] op_sel_hi:[1,0,1]
	ds_write_b64 v164, v[110:111] offset:17408
	v_pk_mul_f32 v[110:111], v[108:109], v[142:143] op_sel:[1,1] op_sel_hi:[0,1] neg_lo:[1,0]
	v_pk_fma_f32 v[108:109], v[108:109], v[142:143], v[110:111] op_sel_hi:[1,0,1]
	ds_write_b64 v164, v[108:109] offset:19584
	v_pk_mul_f32 v[108:109], v[106:107], v[148:149] op_sel:[1,1] op_sel_hi:[0,1] neg_lo:[1,0]
	v_pk_fma_f32 v[106:107], v[106:107], v[148:149], v[108:109] op_sel_hi:[1,0,1]
	ds_write_b64 v164, v[106:107] offset:21760
	v_pk_mul_f32 v[106:107], v[104:105], v[132:133] op_sel:[1,1] op_sel_hi:[0,1] neg_lo:[1,0]
	v_pk_fma_f32 v[104:105], v[104:105], v[132:133], v[106:107] op_sel_hi:[1,0,1]
	ds_write_b64 v164, v[104:105] offset:23936
	v_pk_mul_f32 v[104:105], v[6:7], v[136:137] op_sel:[1,1] op_sel_hi:[0,1] neg_lo:[1,0]
	v_pk_fma_f32 v[6:7], v[6:7], v[136:137], v[104:105] op_sel_hi:[1,0,1]
	ds_write_b64 v164, v[6:7] offset:26112
	v_pk_mul_f32 v[6:7], v[4:5], v[154:155] op_sel:[1,1] op_sel_hi:[0,1] neg_lo:[1,0]
	v_pk_fma_f32 v[4:5], v[4:5], v[154:155], v[6:7] op_sel_hi:[1,0,1]
	ds_write_b64 v164, v[4:5] offset:28288
	v_pk_mul_f32 v[4:5], v[2:3], v[144:145] op_sel:[1,1] op_sel_hi:[0,1] neg_lo:[1,0]
	v_pk_fma_f32 v[2:3], v[2:3], v[144:145], v[4:5] op_sel_hi:[1,0,1]
	ds_write_b64 v164, v[2:3] offset:30464
	v_pk_mul_f32 v[2:3], v[0:1], v[128:129] op_sel:[1,1] op_sel_hi:[0,1] neg_lo:[1,0]
	v_pk_fma_f32 v[0:1], v[0:1], v[128:129], v[2:3] op_sel_hi:[1,0,1]
	ds_write_b64 v164, v[0:1] offset:32640
	v_mov_b32_e32 v116, 1.0
	v_pk_mul_f32 v[2:3], v[210:211], v[210:211] op_sel:[1,1] op_sel_hi:[0,1] neg_lo:[1,0]
	v_mov_b32_e32 v117, v177
	v_pk_fma_f32 v[2:3], v[210:211], v[210:211], v[2:3] op_sel_hi:[0,1,1]
	v_pk_mul_f32 v[104:105], v[2:3], v[2:3] op_sel:[1,1] op_sel_hi:[1,0] neg_lo:[0,1]
	v_pk_mul_f32 v[4:5], v[210:211], v[176:177] op_sel:[1,1] op_sel_hi:[0,1] neg_lo:[1,0]
	v_pk_fma_f32 v[104:105], v[2:3], v[2:3], v[104:105] op_sel_hi:[1,0,1]
	v_pk_fma_f32 v[126:127], v[210:211], v[116:117], v[4:5] op_sel_hi:[1,0,1]
	v_pk_mul_f32 v[0:1], v[176:177], v[2:3] op_sel:[1,1] op_sel_hi:[1,0] neg_lo:[0,1]
	v_pk_fma_f32 v[124:125], v[116:117], v[2:3], v[0:1] op_sel_hi:[0,1,1]
	v_pk_mul_f32 v[0:1], v[126:127], v[2:3] op_sel:[1,1] op_sel_hi:[1,0] neg_lo:[0,1]
	v_pk_mul_f32 v[108:109], v[104:105], v[104:105] op_sel:[1,1] op_sel_hi:[1,0] neg_lo:[0,1]
	v_pk_fma_f32 v[122:123], v[2:3], v[126:127], v[0:1] op_sel_hi:[1,0,1]
	v_pk_mul_f32 v[0:1], v[176:177], v[104:105] op_sel:[1,1] op_sel_hi:[1,0] neg_lo:[0,1]
	v_pk_fma_f32 v[120:121], v[116:117], v[104:105], v[0:1] op_sel_hi:[0,1,1]
	v_pk_mul_f32 v[0:1], v[126:127], v[104:105] op_sel:[1,1] op_sel_hi:[1,0] neg_lo:[0,1]
	s_waitcnt lgkmcnt(0)
	v_pk_fma_f32 v[118:119], v[126:127], v[104:105], v[0:1] op_sel_hi:[0,1,1]
	v_pk_mul_f32 v[0:1], v[124:125], v[104:105] op_sel:[1,1] op_sel_hi:[1,0] neg_lo:[0,1]
	s_barrier
	v_pk_fma_f32 v[114:115], v[104:105], v[124:125], v[0:1] op_sel_hi:[1,0,1]
	v_pk_mul_f32 v[0:1], v[122:123], v[104:105] op_sel:[1,1] op_sel_hi:[1,0] neg_lo:[0,1]
	v_pk_fma_f32 v[112:113], v[104:105], v[122:123], v[0:1] op_sel_hi:[1,0,1]
	v_pk_fma_f32 v[0:1], v[104:105], v[104:105], v[108:109] op_sel_hi:[1,0,1]
	v_pk_mul_f32 v[2:3], v[176:177], v[0:1] op_sel:[1,1] op_sel_hi:[1,0] neg_lo:[0,1]
	v_pk_fma_f32 v[110:111], v[116:117], v[0:1], v[2:3] op_sel_hi:[0,1,1]
	v_pk_mul_f32 v[2:3], v[126:127], v[0:1] op_sel:[1,1] op_sel_hi:[1,0] neg_lo:[0,1]
	v_pk_fma_f32 v[108:109], v[126:127], v[0:1], v[2:3] op_sel_hi:[0,1,1]
	v_pk_mul_f32 v[2:3], v[124:125], v[0:1] op_sel:[1,1] op_sel_hi:[1,0] neg_lo:[0,1]
	v_pk_fma_f32 v[106:107], v[124:125], v[0:1], v[2:3] op_sel_hi:[0,1,1]
	v_pk_mul_f32 v[2:3], v[122:123], v[0:1] op_sel:[1,1] op_sel_hi:[1,0] neg_lo:[0,1]
	v_pk_fma_f32 v[104:105], v[122:123], v[0:1], v[2:3] op_sel_hi:[0,1,1]
	v_pk_mul_f32 v[2:3], v[120:121], v[0:1] op_sel:[1,1] op_sel_hi:[1,0] neg_lo:[0,1]
	v_pk_fma_f32 v[6:7], v[0:1], v[120:121], v[2:3] op_sel_hi:[1,0,1]
	v_pk_mul_f32 v[2:3], v[118:119], v[0:1] op_sel:[1,1] op_sel_hi:[1,0] neg_lo:[0,1]
	v_pk_fma_f32 v[4:5], v[0:1], v[118:119], v[2:3] op_sel_hi:[1,0,1]
	v_pk_mul_f32 v[2:3], v[114:115], v[0:1] op_sel:[1,1] op_sel_hi:[1,0] neg_lo:[0,1]
	v_pk_mul_f32 v[128:129], v[112:113], v[0:1] op_sel:[1,1] op_sel_hi:[1,0] neg_lo:[0,1]
	v_pk_fma_f32 v[2:3], v[0:1], v[114:115], v[2:3] op_sel_hi:[1,0,1]
	v_pk_fma_f32 v[0:1], v[0:1], v[112:113], v[128:129] op_sel_hi:[1,0,1]
	s_nop 0
	v_bfe_u32 v129, v206, 4, 4
	v_and_b32_e32 v128, 15, v206
	v_mul_u32_u24_e32 v129, 0x880, v129
	v_lshlrev_b32_e32 v128, 3, v128
	v_add3_u32 v184, v207, v129, v128
	ds_read2_b64 v[128:131], v184 offset1:17
	ds_read2_b64 v[132:135], v184 offset0:34 offset1:51
	ds_read2_b64 v[136:139], v184 offset0:68 offset1:85
	ds_read2_b64 v[140:143], v184 offset0:102 offset1:119
	ds_read2_b64 v[144:147], v184 offset0:136 offset1:153
	ds_read2_b64 v[148:151], v184 offset0:170 offset1:187
	ds_read2_b64 v[152:155], v184 offset0:204 offset1:221
	ds_read2_b64 v[156:159], v184 offset0:238 offset1:255
	s_waitcnt lgkmcnt(3)
	v_pk_add_f32 v[160:161], v[128:129], v[144:145]
	v_pk_add_f32 v[128:129], v[128:129], v[144:145] neg_lo:[0,1] neg_hi:[0,1]
	s_waitcnt lgkmcnt(1)
	v_pk_add_f32 v[144:145], v[136:137], v[152:153]
	v_pk_add_f32 v[136:137], v[136:137], v[152:153] neg_lo:[0,1] neg_hi:[0,1]
	v_pk_add_f32 v[162:163], v[128:129], v[136:137] op_sel:[0,1] op_sel_hi:[1,0] neg_hi:[0,1]
	v_pk_add_f32 v[128:129], v[128:129], v[136:137] op_sel:[0,1] op_sel_hi:[1,0] neg_lo:[0,1]
	v_pk_add_f32 v[152:153], v[130:131], v[146:147]
	v_pk_add_f32 v[130:131], v[130:131], v[146:147] neg_lo:[0,1] neg_hi:[0,1]
	v_pk_add_f32 v[146:147], v[138:139], v[154:155]
	v_pk_add_f32 v[138:139], v[138:139], v[154:155] neg_lo:[0,1] neg_hi:[0,1]
	v_pk_add_f32 v[136:137], v[160:161], v[144:145]
	v_xor_b32_e32 v155, 0x80000000, v138
	v_mov_b32_e32 v154, v139
	v_pk_add_f32 v[138:139], v[152:153], v[146:147]
	v_pk_add_f32 v[146:147], v[152:153], v[146:147] neg_lo:[0,1] neg_hi:[0,1]
	v_pk_add_f32 v[152:153], v[132:133], v[148:149]
	v_pk_add_f32 v[132:133], v[132:133], v[148:149] neg_lo:[0,1] neg_hi:[0,1]
	s_waitcnt lgkmcnt(0)
	v_pk_add_f32 v[148:149], v[140:141], v[156:157]
	v_pk_add_f32 v[140:141], v[140:141], v[156:157] neg_lo:[0,1] neg_hi:[0,1]
	v_pk_add_f32 v[144:145], v[160:161], v[144:145] neg_lo:[0,1] neg_hi:[0,1]
	v_pk_add_f32 v[160:161], v[130:131], v[154:155]
	v_pk_add_f32 v[130:131], v[130:131], v[154:155] neg_lo:[0,1] neg_hi:[0,1]
	v_xor_b32_e32 v155, 0x80000000, v140
	v_mov_b32_e32 v154, v141
	v_pk_add_f32 v[140:141], v[152:153], v[148:149]
	v_pk_add_f32 v[148:149], v[152:153], v[148:149] neg_lo:[0,1] neg_hi:[0,1]
	v_pk_add_f32 v[152:153], v[134:135], v[150:151]
	v_pk_add_f32 v[134:135], v[134:135], v[150:151] neg_lo:[0,1] neg_hi:[0,1]
	v_pk_add_f32 v[150:151], v[142:143], v[158:159]
	v_pk_add_f32 v[142:143], v[142:143], v[158:159] neg_lo:[0,1] neg_hi:[0,1]
	v_pk_add_f32 v[156:157], v[132:133], v[154:155]
	v_pk_add_f32 v[132:133], v[132:133], v[154:155] neg_lo:[0,1] neg_hi:[0,1]
	v_pk_add_f32 v[158:159], v[134:135], v[142:143] op_sel:[0,1] op_sel_hi:[1,0] neg_hi:[0,1]
	v_pk_add_f32 v[134:135], v[134:135], v[142:143] op_sel:[0,1] op_sel_hi:[1,0] neg_lo:[0,1]
	v_pk_mul_f32 v[154:155], v[146:147], s[12:13] op_sel:[1,0] op_sel_hi:[0,0] neg_lo:[1,0]
	v_pk_add_f32 v[142:143], v[152:153], v[150:151]
	v_pk_fma_f32 v[146:147], v[146:147], s[12:13], v[154:155] op_sel_hi:[1,0,1] neg_lo:[0,0,1] neg_hi:[0,0,1]
	v_pk_mul_f32 v[154:155], v[130:131], s[36:37] op_sel:[1,0] op_sel_hi:[0,0] neg_lo:[1,0]
	v_pk_add_f32 v[150:151], v[152:153], v[150:151] neg_lo:[0,1] neg_hi:[0,1]
	v_pk_fma_f32 v[130:131], v[130:131], s[22:23], v[154:155] op_sel_hi:[1,0,1] neg_lo:[0,0,1] neg_hi:[0,0,1]
	v_pk_mul_f32 v[154:155], v[156:157], s[12:13] op_sel:[1,0] op_sel_hi:[0,0] neg_lo:[1,0]
	v_pk_fma_f32 v[154:155], v[156:157], s[12:13], v[154:155] op_sel_hi:[1,0,1] neg_lo:[0,0,1] neg_hi:[0,0,1]
	v_pk_fma_f32 v[148:149], v[148:149], 0, v[148:149] op_sel:[0,0,1] op_sel_hi:[1,0,0] neg_hi:[0,0,1]
	v_pk_mul_f32 v[156:157], v[132:133], s[12:13] op_sel:[1,0] op_sel_hi:[0,0] neg_lo:[1,0]
	v_pk_fma_f32 v[132:133], v[132:133], s[18:19], v[156:157] op_sel_hi:[1,0,1] neg_lo:[0,0,1] neg_hi:[0,0,1]
	v_pk_mul_f32 v[156:157], v[158:159], s[36:37] op_sel:[1,0] op_sel_hi:[0,0] neg_lo:[1,0]
	v_pk_mul_f32 v[152:153], v[160:161], s[22:23] op_sel:[1,0] op_sel_hi:[0,0] neg_lo:[1,0]
	v_pk_fma_f32 v[156:157], v[158:159], s[22:23], v[156:157] op_sel_hi:[1,0,1] neg_lo:[0,0,1] neg_hi:[0,0,1]
	v_pk_mul_f32 v[158:159], v[150:151], s[12:13] op_sel:[1,0] op_sel_hi:[0,0] neg_lo:[1,0]
	v_pk_fma_f32 v[152:153], v[160:161], s[36:37], v[152:153] op_sel_hi:[1,0,1] neg_lo:[0,0,1] neg_hi:[0,0,1]
	v_pk_fma_f32 v[150:151], v[150:151], s[18:19], v[158:159] op_sel_hi:[1,0,1] neg_lo:[0,0,1] neg_hi:[0,0,1]
	v_xor_b32_e32 v158, 0x80000000, v135
	v_mov_b32_e32 v159, v134
	v_pk_mul_f32 v[134:135], v[134:135], s[36:37] op_sel_hi:[1,0]
	v_pk_fma_f32 v[134:135], v[158:159], s[22:23], v[134:135] op_sel_hi:[1,0,1] neg_lo:[0,0,1] neg_hi:[0,0,1]
	v_pk_add_f32 v[158:159], v[136:137], v[140:141]
	v_pk_add_f32 v[136:137], v[136:137], v[140:141] neg_lo:[0,1] neg_hi:[0,1]
	v_pk_add_f32 v[140:141], v[138:139], v[142:143]
	v_pk_add_f32 v[138:139], v[138:139], v[142:143] neg_lo:[0,1] neg_hi:[0,1]
	v_pk_add_f32 v[164:165], v[158:159], v[140:141] neg_lo:[0,1] neg_hi:[0,1]
	v_pk_add_f32 v[160:161], v[136:137], v[138:139] op_sel:[0,1] op_sel_hi:[1,0] neg_hi:[0,1]
	v_pk_add_f32 v[166:167], v[136:137], v[138:139] op_sel:[0,1] op_sel_hi:[1,0] neg_lo:[0,1]
	v_pk_add_f32 v[142:143], v[152:153], v[156:157]
	v_pk_add_f32 v[152:153], v[152:153], v[156:157] neg_lo:[0,1] neg_hi:[0,1]
	v_pk_add_f32 v[138:139], v[158:159], v[140:141]
	v_pk_add_f32 v[136:137], v[162:163], v[154:155]
	v_pk_add_f32 v[140:141], v[162:163], v[154:155] neg_lo:[0,1] neg_hi:[0,1]
	v_xor_b32_e32 v155, 0x80000000, v152
	v_mov_b32_e32 v154, v153
	v_pk_add_f32 v[152:153], v[136:137], v[142:143]
	v_pk_add_f32 v[162:163], v[140:141], v[154:155]
	v_pk_add_f32 v[168:169], v[136:137], v[142:143] neg_lo:[0,1] neg_hi:[0,1]
	v_pk_add_f32 v[170:171], v[140:141], v[154:155] neg_lo:[0,1] neg_hi:[0,1]
	v_pk_add_f32 v[136:137], v[144:145], v[148:149]
	v_pk_add_f32 v[140:141], v[144:145], v[148:149] neg_lo:[0,1] neg_hi:[0,1]
	v_pk_add_f32 v[142:143], v[146:147], v[150:151]
	v_pk_add_f32 v[144:145], v[146:147], v[150:151] neg_lo:[0,1] neg_hi:[0,1]
	v_pk_add_f32 v[172:173], v[136:137], v[142:143] neg_lo:[0,1] neg_hi:[0,1]
	v_xor_b32_e32 v147, 0x80000000, v144
	v_mov_b32_e32 v146, v145
	v_pk_add_f32 v[144:145], v[136:137], v[142:143]
	v_pk_add_f32 v[136:137], v[128:129], v[132:133]
	v_pk_add_f32 v[128:129], v[128:129], v[132:133] neg_lo:[0,1] neg_hi:[0,1]
	v_pk_add_f32 v[132:133], v[130:131], v[134:135]
	v_pk_add_f32 v[130:131], v[130:131], v[134:135] neg_lo:[0,1] neg_hi:[0,1]
	v_xor_b32_e32 v142, 0x80000000, v117
	v_xor_b32_e32 v135, 0x80000000, v130
	v_mov_b32_e32 v134, v131
	v_mov_b32_e32 v143, v116
	v_pk_add_f32 v[148:149], v[140:141], v[146:147]
	v_pk_add_f32 v[174:175], v[140:141], v[146:147] neg_lo:[0,1] neg_hi:[0,1]
	v_pk_add_f32 v[130:131], v[136:137], v[132:133]
	v_pk_add_f32 v[146:147], v[128:129], v[134:135]
	v_pk_add_f32 v[198:199], v[136:137], v[132:133] neg_lo:[0,1] neg_hi:[0,1]
	v_pk_add_f32 v[200:201], v[128:129], v[134:135] neg_lo:[0,1] neg_hi:[0,1]
	v_pk_mul_f32 v[128:129], v[142:143], v[138:139] op_sel:[0,1]
	v_pk_mul_f32 v[132:133], v[126:127], v[152:153] op_sel:[1,1] op_sel_hi:[0,1] neg_lo:[1,0]
	v_pk_fma_f32 v[128:129], v[116:117], v[138:139], v[128:129] op_sel_hi:[1,0,1]
	v_pk_fma_f32 v[132:133], v[126:127], v[152:153], v[132:133] op_sel_hi:[1,0,1]
	ds_write2_b64 v184, v[128:129], v[132:133] offset1:17
	v_pk_mul_f32 v[128:129], v[124:125], v[144:145] op_sel:[1,1] op_sel_hi:[0,1] neg_lo:[1,0]
	v_pk_mul_f32 v[132:133], v[122:123], v[130:131] op_sel:[1,1] op_sel_hi:[0,1] neg_lo:[1,0]
	v_pk_fma_f32 v[128:129], v[124:125], v[144:145], v[128:129] op_sel_hi:[1,0,1]
	v_pk_fma_f32 v[130:131], v[122:123], v[130:131], v[132:133] op_sel_hi:[1,0,1]
	ds_write2_b64 v184, v[128:129], v[130:131] offset0:34 offset1:51
	v_pk_mul_f32 v[128:129], v[120:121], v[160:161] op_sel:[1,1] op_sel_hi:[0,1] neg_lo:[1,0]
	v_pk_mul_f32 v[130:131], v[118:119], v[162:163] op_sel:[1,1] op_sel_hi:[0,1] neg_lo:[1,0]
	v_pk_fma_f32 v[128:129], v[120:121], v[160:161], v[128:129] op_sel_hi:[1,0,1]
	v_pk_fma_f32 v[130:131], v[118:119], v[162:163], v[130:131] op_sel_hi:[1,0,1]
	ds_write2_b64 v184, v[128:129], v[130:131] offset0:68 offset1:85
	v_pk_mul_f32 v[128:129], v[114:115], v[148:149] op_sel:[1,1] op_sel_hi:[0,1] neg_lo:[1,0]
	v_pk_mul_f32 v[130:131], v[112:113], v[146:147] op_sel:[1,1] op_sel_hi:[0,1] neg_lo:[1,0]
	v_pk_fma_f32 v[128:129], v[114:115], v[148:149], v[128:129] op_sel_hi:[1,0,1]
	v_pk_fma_f32 v[130:131], v[112:113], v[146:147], v[130:131] op_sel_hi:[1,0,1]
	ds_write2_b64 v184, v[128:129], v[130:131] offset0:102 offset1:119
	v_pk_mul_f32 v[128:129], v[110:111], v[164:165] op_sel:[1,1] op_sel_hi:[0,1] neg_lo:[1,0]
	v_pk_mul_f32 v[130:131], v[108:109], v[168:169] op_sel:[1,1] op_sel_hi:[0,1] neg_lo:[1,0]
	v_pk_fma_f32 v[128:129], v[110:111], v[164:165], v[128:129] op_sel_hi:[1,0,1]
	v_pk_fma_f32 v[130:131], v[108:109], v[168:169], v[130:131] op_sel_hi:[1,0,1]
	ds_write2_b64 v184, v[128:129], v[130:131] offset0:136 offset1:153
	v_pk_mul_f32 v[128:129], v[106:107], v[172:173] op_sel:[1,1] op_sel_hi:[0,1] neg_lo:[1,0]
	v_pk_mul_f32 v[130:131], v[104:105], v[198:199] op_sel:[1,1] op_sel_hi:[0,1] neg_lo:[1,0]
	v_pk_fma_f32 v[128:129], v[106:107], v[172:173], v[128:129] op_sel_hi:[1,0,1]
	v_pk_fma_f32 v[130:131], v[104:105], v[198:199], v[130:131] op_sel_hi:[1,0,1]
	ds_write2_b64 v184, v[128:129], v[130:131] offset0:170 offset1:187
	v_pk_mul_f32 v[128:129], v[6:7], v[166:167] op_sel:[1,1] op_sel_hi:[0,1] neg_lo:[1,0]
	v_pk_mul_f32 v[144:145], v[4:5], v[170:171] op_sel:[1,1] op_sel_hi:[0,1] neg_lo:[1,0]
	v_pk_fma_f32 v[128:129], v[6:7], v[166:167], v[128:129] op_sel_hi:[1,0,1]
	v_pk_fma_f32 v[144:145], v[4:5], v[170:171], v[144:145] op_sel_hi:[1,0,1]
	ds_write2_b64 v184, v[128:129], v[144:145] offset0:204 offset1:221
	v_pk_mul_f32 v[144:145], v[2:3], v[174:175] op_sel:[1,1] op_sel_hi:[0,1] neg_lo:[1,0]
	v_pk_fma_f32 v[160:161], v[2:3], v[174:175], v[144:145] op_sel_hi:[1,0,1]
	v_pk_mul_f32 v[162:163], v[0:1], v[200:201] op_sel:[1,1] op_sel_hi:[0,1] neg_lo:[1,0]
	v_pk_fma_f32 v[162:163], v[0:1], v[200:201], v[162:163] op_sel_hi:[1,0,1]
	ds_write2_b64 v184, v[160:161], v[162:163] offset0:238 offset1:255
	s_waitcnt lgkmcnt(0)
	s_barrier
	s_nop 0
	v_and_b32_e32 v129, 0xff, v206
	v_mad_u32_u24 v129, v129, s19, v207
	ds_read2_b64 v[160:163], v129 offset1:1
	ds_read2_b64 v[164:167], v129 offset0:2 offset1:3
	ds_read2_b64 v[168:171], v129 offset0:4 offset1:5
	ds_read2_b64 v[172:175], v129 offset0:6 offset1:7
	ds_read2_b64 v[198:201], v129 offset0:8 offset1:9
	ds_read2_b64 v[202:205], v129 offset0:10 offset1:11
	ds_read2_b64 v[236:239], v129 offset0:12 offset1:13
	ds_read2_b64 v[240:243], v129 offset0:14 offset1:15
	s_waitcnt lgkmcnt(3)
	v_pk_add_f32 v[244:245], v[160:161], v[198:199]
	v_pk_add_f32 v[160:161], v[160:161], v[198:199] neg_lo:[0,1] neg_hi:[0,1]
	s_waitcnt lgkmcnt(1)
	v_pk_add_f32 v[198:199], v[168:169], v[236:237]
	v_pk_add_f32 v[168:169], v[168:169], v[236:237] neg_lo:[0,1] neg_hi:[0,1]
	v_pk_add_f32 v[246:247], v[160:161], v[168:169] op_sel:[0,1] op_sel_hi:[1,0] neg_hi:[0,1]
	v_pk_add_f32 v[160:161], v[160:161], v[168:169] op_sel:[0,1] op_sel_hi:[1,0] neg_lo:[0,1]
	v_pk_add_f32 v[236:237], v[162:163], v[200:201]
	v_pk_add_f32 v[162:163], v[162:163], v[200:201] neg_lo:[0,1] neg_hi:[0,1]
	v_pk_add_f32 v[200:201], v[170:171], v[238:239]
	v_pk_add_f32 v[170:171], v[170:171], v[238:239] neg_lo:[0,1] neg_hi:[0,1]
	v_pk_add_f32 v[168:169], v[244:245], v[198:199]
	v_xor_b32_e32 v239, 0x80000000, v170
	v_mov_b32_e32 v238, v171
	v_pk_add_f32 v[170:171], v[236:237], v[200:201]
	v_pk_add_f32 v[200:201], v[236:237], v[200:201] neg_lo:[0,1] neg_hi:[0,1]
	v_pk_add_f32 v[236:237], v[164:165], v[202:203]
	v_pk_add_f32 v[164:165], v[164:165], v[202:203] neg_lo:[0,1] neg_hi:[0,1]
	s_waitcnt lgkmcnt(0)
	v_pk_add_f32 v[202:203], v[172:173], v[240:241]
	v_pk_add_f32 v[172:173], v[172:173], v[240:241] neg_lo:[0,1] neg_hi:[0,1]
	v_pk_add_f32 v[198:199], v[244:245], v[198:199] neg_lo:[0,1] neg_hi:[0,1]
	v_pk_add_f32 v[244:245], v[162:163], v[238:239]
	v_pk_add_f32 v[162:163], v[162:163], v[238:239] neg_lo:[0,1] neg_hi:[0,1]
	v_xor_b32_e32 v239, 0x80000000, v172
	v_mov_b32_e32 v238, v173
	v_pk_add_f32 v[172:173], v[236:237], v[202:203]
	v_pk_add_f32 v[202:203], v[236:237], v[202:203] neg_lo:[0,1] neg_hi:[0,1]
	v_pk_add_f32 v[236:237], v[166:167], v[204:205]
	v_pk_add_f32 v[166:167], v[166:167], v[204:205] neg_lo:[0,1] neg_hi:[0,1]
	v_pk_add_f32 v[204:205], v[174:175], v[242:243]
	v_pk_add_f32 v[174:175], v[174:175], v[242:243] neg_lo:[0,1] neg_hi:[0,1]
	v_pk_add_f32 v[240:241], v[164:165], v[238:239]
	v_pk_add_f32 v[164:165], v[164:165], v[238:239] neg_lo:[0,1] neg_hi:[0,1]
	v_pk_add_f32 v[242:243], v[166:167], v[174:175] op_sel:[0,1] op_sel_hi:[1,0] neg_hi:[0,1]
	v_pk_add_f32 v[166:167], v[166:167], v[174:175] op_sel:[0,1] op_sel_hi:[1,0] neg_lo:[0,1]
	v_pk_mul_f32 v[238:239], v[200:201], s[12:13] op_sel:[1,0] op_sel_hi:[0,0] neg_lo:[1,0]
	v_pk_add_f32 v[174:175], v[236:237], v[204:205]
	v_pk_fma_f32 v[200:201], v[200:201], s[12:13], v[238:239] op_sel_hi:[1,0,1] neg_lo:[0,0,1] neg_hi:[0,0,1]
	v_pk_mul_f32 v[238:239], v[162:163], s[36:37] op_sel:[1,0] op_sel_hi:[0,0] neg_lo:[1,0]
	v_pk_add_f32 v[204:205], v[236:237], v[204:205] neg_lo:[0,1] neg_hi:[0,1]
	v_pk_fma_f32 v[162:163], v[162:163], s[22:23], v[238:239] op_sel_hi:[1,0,1] neg_lo:[0,0,1] neg_hi:[0,0,1]
	v_pk_mul_f32 v[238:239], v[240:241], s[12:13] op_sel:[1,0] op_sel_hi:[0,0] neg_lo:[1,0]
	v_pk_fma_f32 v[238:239], v[240:241], s[12:13], v[238:239] op_sel_hi:[1,0,1] neg_lo:[0,0,1] neg_hi:[0,0,1]
	v_pk_fma_f32 v[202:203], v[202:203], 0, v[202:203] op_sel:[0,0,1] op_sel_hi:[1,0,0] neg_hi:[0,0,1]
	v_pk_mul_f32 v[240:241], v[164:165], s[12:13] op_sel:[1,0] op_sel_hi:[0,0] neg_lo:[1,0]
	v_pk_fma_f32 v[164:165], v[164:165], s[18:19], v[240:241] op_sel_hi:[1,0,1] neg_lo:[0,0,1] neg_hi:[0,0,1]
	v_pk_mul_f32 v[240:241], v[242:243], s[36:37] op_sel:[1,0] op_sel_hi:[0,0] neg_lo:[1,0]
	v_pk_mul_f32 v[236:237], v[244:245], s[22:23] op_sel:[1,0] op_sel_hi:[0,0] neg_lo:[1,0]
	v_pk_fma_f32 v[240:241], v[242:243], s[22:23], v[240:241] op_sel_hi:[1,0,1] neg_lo:[0,0,1] neg_hi:[0,0,1]
	v_pk_mul_f32 v[242:243], v[204:205], s[12:13] op_sel:[1,0] op_sel_hi:[0,0] neg_lo:[1,0]
	v_pk_fma_f32 v[236:237], v[244:245], s[36:37], v[236:237] op_sel_hi:[1,0,1] neg_lo:[0,0,1] neg_hi:[0,0,1]
	v_pk_fma_f32 v[204:205], v[204:205], s[18:19], v[242:243] op_sel_hi:[1,0,1] neg_lo:[0,0,1] neg_hi:[0,0,1]
	v_xor_b32_e32 v242, 0x80000000, v167
	v_mov_b32_e32 v243, v166
	v_pk_mul_f32 v[166:167], v[166:167], s[36:37] op_sel_hi:[1,0]
	v_pk_fma_f32 v[166:167], v[242:243], s[22:23], v[166:167] op_sel_hi:[1,0,1] neg_lo:[0,0,1] neg_hi:[0,0,1]
	v_pk_add_f32 v[242:243], v[168:169], v[172:173]
	v_pk_add_f32 v[168:169], v[168:169], v[172:173] neg_lo:[0,1] neg_hi:[0,1]
	v_pk_add_f32 v[172:173], v[170:171], v[174:175]
	v_pk_add_f32 v[170:171], v[170:171], v[174:175] neg_lo:[0,1] neg_hi:[0,1]
	v_pk_add_f32 v[244:245], v[242:243], v[172:173]
	v_pk_add_f32 v[248:249], v[168:169], v[170:171] op_sel:[0,1] op_sel_hi:[1,0] neg_hi:[0,1]
	v_pk_add_f32 v[250:251], v[168:169], v[170:171] op_sel:[0,1] op_sel_hi:[1,0] neg_lo:[0,1]
	v_pk_add_f32 v[174:175], v[236:237], v[240:241] neg_lo:[0,1] neg_hi:[0,1]
	v_pk_add_f32 v[242:243], v[242:243], v[172:173] neg_lo:[0,1] neg_hi:[0,1]
	v_pk_add_f32 v[168:169], v[246:247], v[238:239]
	v_pk_add_f32 v[172:173], v[236:237], v[240:241]
	v_xor_b32_e32 v237, 0x80000000, v174
	v_mov_b32_e32 v236, v175
	v_pk_add_f32 v[174:175], v[200:201], v[204:205] neg_lo:[0,1] neg_hi:[0,1]
	v_pk_add_f32 v[170:171], v[246:247], v[238:239] neg_lo:[0,1] neg_hi:[0,1]
	v_pk_add_f32 v[238:239], v[168:169], v[172:173]
	v_pk_add_f32 v[246:247], v[168:169], v[172:173] neg_lo:[0,1] neg_hi:[0,1]
	v_pk_add_f32 v[172:173], v[200:201], v[204:205]
	v_xor_b32_e32 v201, 0x80000000, v174
	v_mov_b32_e32 v200, v175
	v_pk_add_f32 v[174:175], v[160:161], v[164:165]
	v_pk_add_f32 v[160:161], v[160:161], v[164:165] neg_lo:[0,1] neg_hi:[0,1]
	v_pk_add_f32 v[164:165], v[162:163], v[166:167]
	v_pk_add_f32 v[162:163], v[162:163], v[166:167] neg_lo:[0,1] neg_hi:[0,1]
	v_pk_add_f32 v[240:241], v[170:171], v[236:237]
	v_pk_add_f32 v[192:193], v[170:171], v[236:237] neg_lo:[0,1] neg_hi:[0,1]
	v_pk_add_f32 v[168:169], v[198:199], v[202:203]
	v_pk_add_f32 v[170:171], v[198:199], v[202:203] neg_lo:[0,1] neg_hi:[0,1]
	v_xor_b32_e32 v167, 0x80000000, v162
	v_mov_b32_e32 v166, v163
	v_pk_add_f32 v[194:195], v[168:169], v[172:173]
	v_pk_add_f32 v[184:185], v[170:171], v[200:201]
	v_pk_add_f32 v[198:199], v[168:169], v[172:173] neg_lo:[0,1] neg_hi:[0,1]
	v_pk_add_f32 v[172:173], v[170:171], v[200:201] neg_lo:[0,1] neg_hi:[0,1]
	v_pk_add_f32 v[170:171], v[174:175], v[164:165]
	v_pk_add_f32 v[168:169], v[160:161], v[162:163] op_sel:[0,1] op_sel_hi:[1,0] neg_hi:[0,1]
	v_pk_add_f32 v[162:163], v[174:175], v[164:165] neg_lo:[0,1] neg_hi:[0,1]
	v_pk_add_f32 v[160:161], v[160:161], v[166:167] neg_lo:[0,1] neg_hi:[0,1]
	ds_read2st64_b64 v[164:167], v234 offset1:8
	ds_read2st64_b64 v[200:203], v234 offset0:16 offset1:24
	s_waitcnt lgkmcnt(1)
	v_pk_mul_f32 v[174:175], v[164:165], v[244:245] op_sel:[1,1] op_sel_hi:[0,1] neg_lo:[1,0]
	v_pk_fma_f32 v[164:165], v[164:165], v[244:245], v[174:175] op_sel_hi:[1,0,1]
	v_pk_mul_f32 v[174:175], v[166:167], v[248:249] op_sel:[1,1] op_sel_hi:[0,1] neg_lo:[1,0]
	v_pk_fma_f32 v[166:167], v[166:167], v[248:249], v[174:175] op_sel_hi:[1,0,1]
	s_waitcnt lgkmcnt(0)
	v_pk_mul_f32 v[174:175], v[242:243], v[200:201] op_sel:[1,1] op_sel_hi:[1,0] neg_lo:[0,1]
	v_pk_fma_f32 v[174:175], v[200:201], v[242:243], v[174:175] op_sel_hi:[1,0,1]
	v_pk_mul_f32 v[200:201], v[202:203], v[250:251] op_sel:[1,1] op_sel_hi:[0,1] neg_lo:[1,0]
	v_pk_fma_f32 v[200:201], v[202:203], v[250:251], v[200:201] op_sel_hi:[1,0,1]
	ds_read2st64_b64 v[202:205], v234 offset0:32 offset1:40
	s_waitcnt lgkmcnt(0)
	v_pk_mul_f32 v[236:237], v[202:203], v[238:239] op_sel:[1,1] op_sel_hi:[0,1] neg_lo:[1,0]
	v_pk_fma_f32 v[202:203], v[202:203], v[238:239], v[236:237] op_sel_hi:[1,0,1]
	v_pk_mul_f32 v[236:237], v[204:205], v[240:241] op_sel:[1,1] op_sel_hi:[0,1] neg_lo:[1,0]
	v_pk_fma_f32 v[204:205], v[204:205], v[240:241], v[236:237] op_sel_hi:[1,0,1]
	ds_read2st64_b64 v[236:239], v234 offset0:48 offset1:56
	s_waitcnt lgkmcnt(0)
	v_pk_mul_f32 v[240:241], v[236:237], v[246:247] op_sel:[1,1] op_sel_hi:[0,1] neg_lo:[1,0]
	v_pk_fma_f32 v[240:241], v[236:237], v[246:247], v[240:241] op_sel_hi:[1,0,1]
	v_pk_mul_f32 v[236:237], v[238:239], v[192:193] op_sel:[1,1] op_sel_hi:[0,1] neg_lo:[1,0]
	v_pk_fma_f32 v[192:193], v[238:239], v[192:193], v[236:237] op_sel_hi:[1,0,1]
	ds_read2st64_b64 v[236:239], v234 offset0:64 offset1:72
	s_waitcnt lgkmcnt(0)
	v_pk_mul_f32 v[242:243], v[194:195], v[236:237] op_sel:[1,1] op_sel_hi:[1,0] neg_lo:[0,1]
	v_pk_fma_f32 v[194:195], v[236:237], v[194:195], v[242:243] op_sel_hi:[1,0,1]
	v_pk_mul_f32 v[236:237], v[184:185], v[238:239] op_sel:[1,1] op_sel_hi:[1,0] neg_lo:[0,1]
	v_pk_fma_f32 v[184:185], v[238:239], v[184:185], v[236:237] op_sel_hi:[1,0,1]
	ds_read2st64_b64 v[236:239], v234 offset0:80 offset1:88
	s_waitcnt lgkmcnt(0)
	v_pk_mul_f32 v[242:243], v[198:199], v[236:237] op_sel:[1,1] op_sel_hi:[1,0] neg_lo:[0,1]
	v_pk_fma_f32 v[198:199], v[198:199], v[236:237], v[242:243] op_sel_hi:[0,1,1]
	v_pk_mul_f32 v[236:237], v[172:173], v[238:239] op_sel:[1,1] op_sel_hi:[1,0] neg_lo:[0,1]
	v_pk_fma_f32 v[172:173], v[238:239], v[172:173], v[236:237] op_sel_hi:[1,0,1]
	ds_read2st64_b64 v[236:239], v234 offset0:96 offset1:104
	s_waitcnt lgkmcnt(0)
	v_pk_mul_f32 v[242:243], v[170:171], v[236:237] op_sel:[1,1] op_sel_hi:[1,0] neg_lo:[0,1]
	v_pk_fma_f32 v[236:237], v[170:171], v[236:237], v[242:243] op_sel_hi:[0,1,1]
	v_pk_mul_f32 v[170:171], v[168:169], v[238:239] op_sel:[1,1] op_sel_hi:[1,0] neg_lo:[0,1]
	v_pk_fma_f32 v[238:239], v[238:239], v[168:169], v[170:171] op_sel_hi:[1,0,1]
	ds_read2st64_b64 v[168:171], v234 offset0:112 offset1:120
	s_waitcnt lgkmcnt(0)
	v_pk_mul_f32 v[234:235], v[162:163], v[168:169] op_sel:[1,1] op_sel_hi:[1,0] neg_lo:[0,1]
	v_pk_fma_f32 v[162:163], v[162:163], v[168:169], v[234:235] op_sel_hi:[0,1,1]
	v_pk_mul_f32 v[168:169], v[160:161], v[170:171] op_sel:[1,1] op_sel_hi:[1,0] neg_lo:[0,1]
	v_pk_fma_f32 v[160:161], v[160:161], v[170:171], v[168:169] op_sel_hi:[0,1,1]
	v_pk_add_f32 v[170:171], v[166:167], v[200:201]
	v_pk_add_f32 v[166:167], v[166:167], v[200:201] neg_lo:[0,1] neg_hi:[0,1]
	v_pk_add_f32 v[168:169], v[164:165], v[174:175]
	v_pk_add_f32 v[164:165], v[164:165], v[174:175] neg_lo:[0,1] neg_hi:[0,1]
	v_xor_b32_e32 v174, 0x80000000, v167
	v_mov_b32_e32 v175, v166
	v_pk_add_f32 v[166:167], v[168:169], v[170:171]
	v_pk_add_f32 v[200:201], v[164:165], v[174:175]
	v_pk_add_f32 v[168:169], v[168:169], v[170:171] neg_lo:[0,1] neg_hi:[0,1]
	v_pk_add_f32 v[164:165], v[164:165], v[174:175] neg_lo:[0,1] neg_hi:[0,1]
	v_pk_add_f32 v[170:171], v[202:203], v[240:241]
	v_pk_add_f32 v[174:175], v[202:203], v[240:241] neg_lo:[0,1] neg_hi:[0,1]
	v_pk_add_f32 v[202:203], v[204:205], v[192:193]
	v_pk_add_f32 v[192:193], v[204:205], v[192:193] neg_lo:[0,1] neg_hi:[0,1]
	v_xor_b32_e32 v204, 0x80000000, v193
	v_mov_b32_e32 v205, v192
	v_pk_add_f32 v[192:193], v[170:171], v[202:203]
	v_pk_add_f32 v[170:171], v[170:171], v[202:203] neg_lo:[0,1] neg_hi:[0,1]
	v_pk_add_f32 v[202:203], v[194:195], v[198:199]
	v_pk_add_f32 v[194:195], v[194:195], v[198:199] neg_lo:[0,1] neg_hi:[0,1]
	v_pk_add_f32 v[198:199], v[184:185], v[172:173]
	v_pk_add_f32 v[172:173], v[184:185], v[172:173] neg_lo:[0,1] neg_hi:[0,1]
	v_pk_add_f32 v[234:235], v[174:175], v[204:205]
	v_xor_b32_e32 v184, 0x80000000, v173
	v_mov_b32_e32 v185, v172
	v_pk_add_f32 v[174:175], v[174:175], v[204:205] neg_lo:[0,1] neg_hi:[0,1]
	v_pk_add_f32 v[172:173], v[202:203], v[198:199]
	v_pk_add_f32 v[204:205], v[194:195], v[184:185]
	v_pk_add_f32 v[198:199], v[202:203], v[198:199] neg_lo:[0,1] neg_hi:[0,1]
	v_pk_add_f32 v[184:185], v[194:195], v[184:185] neg_lo:[0,1] neg_hi:[0,1]
	v_pk_add_f32 v[194:195], v[236:237], v[162:163]
	v_pk_add_f32 v[202:203], v[238:239], v[160:161]
	v_pk_add_f32 v[160:161], v[238:239], v[160:161] neg_lo:[0,1] neg_hi:[0,1]
	v_pk_add_f32 v[162:163], v[236:237], v[162:163] neg_lo:[0,1] neg_hi:[0,1]
	v_xor_b32_e32 v236, 0x80000000, v161
	v_mov_b32_e32 v237, v160
	v_pk_add_f32 v[160:161], v[194:195], v[202:203]
	v_pk_add_f32 v[194:195], v[194:195], v[202:203] neg_lo:[0,1] neg_hi:[0,1]
	v_pk_mul_f32 v[202:203], v[234:235], s[22:23] op_sel:[1,0] op_sel_hi:[0,0] neg_lo:[1,0]
	v_pk_add_f32 v[238:239], v[162:163], v[236:237]
	v_pk_fma_f32 v[202:203], v[234:235], s[36:37], v[202:203] op_sel_hi:[1,0,1]
	v_pk_mul_f32 v[234:235], v[170:171], s[12:13] op_sel:[1,0] op_sel_hi:[0,0] neg_lo:[1,0]
	v_pk_add_f32 v[162:163], v[162:163], v[236:237] neg_lo:[0,1] neg_hi:[0,1]
	v_pk_fma_f32 v[170:171], v[170:171], s[12:13], v[234:235] op_sel_hi:[1,0,1]
	v_pk_mul_f32 v[234:235], v[174:175], s[36:37] op_sel:[1,0] op_sel_hi:[0,0] neg_lo:[1,0]
	v_xor_b32_e32 v236, 0x80000000, v195
	v_pk_fma_f32 v[174:175], v[174:175], s[22:23], v[234:235] op_sel_hi:[1,0,1]
	v_pk_mul_f32 v[234:235], v[204:205], s[12:13] op_sel:[1,0] op_sel_hi:[0,0] neg_lo:[1,0]
	v_mov_b32_e32 v237, v194
	v_pk_fma_f32 v[204:205], v[204:205], s[12:13], v[234:235] op_sel_hi:[1,0,1]
	v_pk_mul_f32 v[194:195], v[194:195], s[12:13] op_sel_hi:[1,0]
	v_pk_fma_f32 v[198:199], v[198:199], 0, v[198:199] op_sel:[0,0,1] op_sel_hi:[1,0,0] neg_lo:[0,0,1]
	v_xor_b32_e32 v234, 0x80000000, v185
	v_mov_b32_e32 v235, v184
	v_pk_mul_f32 v[184:185], v[184:185], s[12:13] op_sel_hi:[1,0]
	v_pk_fma_f32 v[194:195], v[236:237], s[12:13], v[194:195] op_sel_hi:[1,0,1] neg_lo:[0,0,1] neg_hi:[0,0,1]
	v_pk_fma_f32 v[184:185], v[234:235], s[12:13], v[184:185] op_sel_hi:[1,0,1] neg_lo:[0,0,1] neg_hi:[0,0,1]
	v_pk_mul_f32 v[236:237], v[162:163], s[22:23] op_sel:[1,0] op_sel_hi:[0,0] neg_lo:[1,0]
	v_pk_mul_f32 v[234:235], v[238:239], s[36:37] op_sel:[1,0] op_sel_hi:[0,0] neg_lo:[1,0]
	v_pk_fma_f32 v[162:163], v[162:163], s[26:27], v[236:237] op_sel_hi:[1,0,1] neg_lo:[0,0,1] neg_hi:[0,0,1]
	v_pk_add_f32 v[236:237], v[166:167], v[172:173]
	v_pk_add_f32 v[166:167], v[166:167], v[172:173] neg_lo:[0,1] neg_hi:[0,1]
	v_pk_add_f32 v[172:173], v[192:193], v[160:161]
	v_pk_add_f32 v[160:161], v[192:193], v[160:161] neg_lo:[0,1] neg_hi:[0,1]
	v_pk_fma_f32 v[234:235], v[238:239], s[22:23], v[234:235] op_sel_hi:[1,0,1]
	v_pk_add_f32 v[238:239], v[166:167], v[160:161] op_sel:[0,1] op_sel_hi:[1,0] neg_lo:[0,1]
	v_pk_add_f32 v[166:167], v[166:167], v[160:161] op_sel:[0,1] op_sel_hi:[1,0] neg_hi:[0,1]
	v_pk_add_f32 v[192:193], v[200:201], v[204:205]
	v_pk_add_f32 v[200:201], v[200:201], v[204:205] neg_lo:[0,1] neg_hi:[0,1]
	v_pk_add_f32 v[204:205], v[202:203], v[234:235]
	v_pk_add_f32 v[202:203], v[202:203], v[234:235] neg_lo:[0,1] neg_hi:[0,1]
	v_pk_add_f32 v[160:161], v[236:237], v[172:173]
	v_xor_b32_e32 v234, 0x80000000, v203
	v_mov_b32_e32 v235, v202
	v_pk_add_f32 v[202:203], v[192:193], v[204:205]
	v_pk_add_f32 v[192:193], v[192:193], v[204:205] neg_lo:[0,1] neg_hi:[0,1]
	v_pk_add_f32 v[204:205], v[168:169], v[198:199]
	v_pk_add_f32 v[168:169], v[168:169], v[198:199] neg_lo:[0,1] neg_hi:[0,1]
	v_pk_add_f32 v[198:199], v[170:171], v[194:195]
	v_pk_add_f32 v[170:171], v[170:171], v[194:195] neg_lo:[0,1] neg_hi:[0,1]
	v_pk_add_f32 v[172:173], v[236:237], v[172:173] neg_lo:[0,1] neg_hi:[0,1]
	v_pk_add_f32 v[236:237], v[200:201], v[234:235]
	v_pk_add_f32 v[200:201], v[200:201], v[234:235] neg_lo:[0,1] neg_hi:[0,1]
	v_pk_add_f32 v[234:235], v[168:169], v[170:171] op_sel:[0,1] op_sel_hi:[1,0] neg_lo:[0,1]
	v_pk_add_f32 v[168:169], v[168:169], v[170:171] op_sel:[0,1] op_sel_hi:[1,0] neg_hi:[0,1]
	v_pk_add_f32 v[194:195], v[164:165], v[184:185]
	v_pk_add_f32 v[164:165], v[164:165], v[184:185] neg_lo:[0,1] neg_hi:[0,1]
	v_pk_add_f32 v[184:185], v[174:175], v[162:163]
	v_pk_add_f32 v[162:163], v[174:175], v[162:163] neg_lo:[0,1] neg_hi:[0,1]
	v_pk_add_f32 v[170:171], v[204:205], v[198:199]
	v_pk_add_f32 v[198:199], v[204:205], v[198:199] neg_lo:[0,1] neg_hi:[0,1]
	v_pk_add_f32 v[204:205], v[164:165], v[162:163] op_sel:[0,1] op_sel_hi:[1,0] neg_lo:[0,1]
	v_pk_add_f32 v[164:165], v[164:165], v[162:163] op_sel:[0,1] op_sel_hi:[1,0] neg_hi:[0,1]
	v_mov_b32_e32 v174, v116
	v_mov_b32_e32 v175, v142
	v_pk_mul_f32 v[142:143], v[174:175], v[160:161] op_sel_hi:[1,0]
	v_pk_add_f32 v[162:163], v[194:195], v[184:185]
	v_pk_fma_f32 v[116:117], v[116:117], v[160:161], v[142:143] op_sel:[1,1,0] op_sel_hi:[0,1,1]
	v_pk_mul_f32 v[142:143], v[126:127], v[202:203] op_sel_hi:[1,0] neg_hi:[1,0]
	v_pk_add_f32 v[184:185], v[194:195], v[184:185] neg_lo:[0,1] neg_hi:[0,1]
	v_pk_fma_f32 v[126:127], v[126:127], v[202:203], v[142:143] op_sel:[1,1,0] op_sel_hi:[0,1,1]
	ds_write2_b64 v129, v[116:117], v[126:127] offset1:1
	v_pk_mul_f32 v[116:117], v[124:125], v[170:171] op_sel_hi:[1,0] neg_hi:[1,0]
	v_pk_fma_f32 v[116:117], v[124:125], v[170:171], v[116:117] op_sel:[1,1,0] op_sel_hi:[0,1,1]
	v_pk_mul_f32 v[124:125], v[122:123], v[162:163] op_sel_hi:[1,0] neg_hi:[1,0]
	v_pk_fma_f32 v[122:123], v[122:123], v[162:163], v[124:125] op_sel:[1,1,0] op_sel_hi:[0,1,1]
	ds_write2_b64 v129, v[116:117], v[122:123] offset0:2 offset1:3
	v_pk_mul_f32 v[116:117], v[120:121], v[238:239] op_sel_hi:[1,0] neg_hi:[1,0]
	v_pk_fma_f32 v[116:117], v[120:121], v[238:239], v[116:117] op_sel:[1,1,0] op_sel_hi:[0,1,1]
	v_pk_mul_f32 v[120:121], v[118:119], v[236:237] op_sel_hi:[1,0] neg_hi:[1,0]
	v_pk_fma_f32 v[118:119], v[118:119], v[236:237], v[120:121] op_sel:[1,1,0] op_sel_hi:[0,1,1]
	ds_write2_b64 v129, v[116:117], v[118:119] offset0:4 offset1:5
	v_pk_mul_f32 v[116:117], v[114:115], v[234:235] op_sel_hi:[1,0] neg_hi:[1,0]
	v_pk_fma_f32 v[114:115], v[114:115], v[234:235], v[116:117] op_sel:[1,1,0] op_sel_hi:[0,1,1]
	v_pk_mul_f32 v[116:117], v[112:113], v[204:205] op_sel_hi:[1,0] neg_hi:[1,0]
	v_pk_fma_f32 v[112:113], v[112:113], v[204:205], v[116:117] op_sel:[1,1,0] op_sel_hi:[0,1,1]
	ds_write2_b64 v129, v[114:115], v[112:113] offset0:6 offset1:7
	v_pk_mul_f32 v[112:113], v[110:111], v[172:173] op_sel_hi:[1,0] neg_hi:[1,0]
	v_pk_fma_f32 v[110:111], v[110:111], v[172:173], v[112:113] op_sel:[1,1,0] op_sel_hi:[0,1,1]
	v_pk_mul_f32 v[112:113], v[108:109], v[192:193] op_sel_hi:[1,0] neg_hi:[1,0]
	v_pk_fma_f32 v[108:109], v[108:109], v[192:193], v[112:113] op_sel:[1,1,0] op_sel_hi:[0,1,1]
	ds_write2_b64 v129, v[110:111], v[108:109] offset0:8 offset1:9
	v_pk_mul_f32 v[108:109], v[106:107], v[198:199] op_sel_hi:[1,0] neg_hi:[1,0]
	v_pk_fma_f32 v[106:107], v[106:107], v[198:199], v[108:109] op_sel:[1,1,0] op_sel_hi:[0,1,1]
	v_pk_mul_f32 v[108:109], v[104:105], v[184:185] op_sel_hi:[1,0] neg_hi:[1,0]
	v_pk_fma_f32 v[104:105], v[104:105], v[184:185], v[108:109] op_sel:[1,1,0] op_sel_hi:[0,1,1]
	ds_write2_b64 v129, v[106:107], v[104:105] offset0:10 offset1:11
	v_pk_mul_f32 v[104:105], v[6:7], v[166:167] op_sel_hi:[1,0] neg_hi:[1,0]
	v_pk_fma_f32 v[6:7], v[6:7], v[166:167], v[104:105] op_sel:[1,1,0] op_sel_hi:[0,1,1]
	v_pk_mul_f32 v[104:105], v[4:5], v[200:201] op_sel_hi:[1,0] neg_hi:[1,0]
	v_pk_fma_f32 v[4:5], v[4:5], v[200:201], v[104:105] op_sel:[1,1,0] op_sel_hi:[0,1,1]
	ds_write2_b64 v129, v[6:7], v[4:5] offset0:12 offset1:13
	v_pk_mul_f32 v[4:5], v[2:3], v[168:169] op_sel_hi:[1,0] neg_hi:[1,0]
	v_pk_fma_f32 v[2:3], v[2:3], v[168:169], v[4:5] op_sel:[1,1,0] op_sel_hi:[0,1,1]
	v_pk_mul_f32 v[4:5], v[0:1], v[164:165] op_sel_hi:[1,0] neg_hi:[1,0]
	v_pk_fma_f32 v[0:1], v[0:1], v[164:165], v[4:5] op_sel:[1,1,0] op_sel_hi:[0,1,1]
	ds_write2_b64 v129, v[2:3], v[0:1] offset0:14 offset1:15
	v_mov_b32_e32 v0, v217
	v_mov_b32_e32 v1, v218
	v_mov_b32_e32 v114, v215
	v_xor_b32_e32 v4, 0x80000000, v1
	v_mov_b32_e32 v5, v0
	v_pk_mul_f32 v[2:3], v[4:5], v[218:219] op_sel_hi:[1,0]
	v_mov_b32_e32 v115, v216
	v_pk_fma_f32 v[2:3], v[216:217], v[0:1], v[2:3] op_sel:[1,0,0]
	v_pk_mul_f32 v[104:105], v[2:3], v[2:3] op_sel:[1,1] op_sel_hi:[1,0] neg_lo:[0,1]
	v_pk_mul_f32 v[4:5], v[4:5], v[216:217] op_sel_hi:[1,0]
	v_pk_fma_f32 v[104:105], v[2:3], v[2:3], v[104:105] op_sel_hi:[1,0,1]
	v_pk_fma_f32 v[126:127], v[0:1], v[214:215], v[4:5] op_sel:[0,1,0]
	v_pk_mul_f32 v[0:1], v[216:217], v[2:3] op_sel:[0,1] op_sel_hi:[0,0] neg_lo:[0,1]
	v_pk_fma_f32 v[124:125], v[214:215], v[2:3], v[0:1] op_sel:[1,0,0]
	v_pk_mul_f32 v[0:1], v[126:127], v[2:3] op_sel:[1,1] op_sel_hi:[1,0] neg_lo:[0,1]
	v_pk_mul_f32 v[108:109], v[104:105], v[104:105] op_sel:[1,1] op_sel_hi:[1,0] neg_lo:[0,1]
	v_pk_fma_f32 v[122:123], v[2:3], v[126:127], v[0:1] op_sel_hi:[1,0,1]
	v_pk_mul_f32 v[0:1], v[216:217], v[104:105] op_sel:[0,1] op_sel_hi:[0,0] neg_lo:[0,1]
	v_pk_fma_f32 v[120:121], v[214:215], v[104:105], v[0:1] op_sel:[1,0,0]
	v_pk_mul_f32 v[0:1], v[126:127], v[104:105] op_sel:[1,1] op_sel_hi:[1,0] neg_lo:[0,1]
	s_waitcnt lgkmcnt(0)
	v_pk_fma_f32 v[118:119], v[126:127], v[104:105], v[0:1] op_sel_hi:[0,1,1]
	v_pk_mul_f32 v[0:1], v[124:125], v[104:105] op_sel:[1,1] op_sel_hi:[1,0] neg_lo:[0,1]
	s_barrier
	v_pk_fma_f32 v[116:117], v[104:105], v[124:125], v[0:1] op_sel_hi:[1,0,1]
	v_pk_mul_f32 v[0:1], v[122:123], v[104:105] op_sel:[1,1] op_sel_hi:[1,0] neg_lo:[0,1]
	v_pk_fma_f32 v[110:111], v[104:105], v[122:123], v[0:1] op_sel_hi:[1,0,1]
	v_pk_fma_f32 v[0:1], v[104:105], v[104:105], v[108:109] op_sel_hi:[1,0,1]
	s_cmpk_lg_u32 s42, 0xc000
	v_pk_mul_f32 v[2:3], v[216:217], v[0:1] op_sel:[0,1] op_sel_hi:[0,0] neg_lo:[0,1]
	v_pk_fma_f32 v[112:113], v[214:215], v[0:1], v[2:3] op_sel:[1,0,0]
	v_pk_mul_f32 v[2:3], v[126:127], v[0:1] op_sel:[1,1] op_sel_hi:[1,0] neg_lo:[0,1]
	s_cselect_b32 s34, s47, 0
	v_pk_fma_f32 v[108:109], v[126:127], v[0:1], v[2:3] op_sel_hi:[0,1,1]
	v_pk_mul_f32 v[2:3], v[124:125], v[0:1] op_sel:[1,1] op_sel_hi:[1,0] neg_lo:[0,1]
	s_lshl_b64 s[2:3], s[34:35], 1
	v_pk_fma_f32 v[106:107], v[124:125], v[0:1], v[2:3] op_sel_hi:[0,1,1]
	v_pk_mul_f32 v[2:3], v[122:123], v[0:1] op_sel:[1,1] op_sel_hi:[1,0] neg_lo:[0,1]
	s_add_u32 s2, s40, s2
	v_pk_fma_f32 v[104:105], v[122:123], v[0:1], v[2:3] op_sel_hi:[0,1,1]
	v_pk_mul_f32 v[2:3], v[120:121], v[0:1] op_sel:[1,1] op_sel_hi:[1,0] neg_lo:[0,1]
	s_addc_u32 s3, s41, s3
	v_pk_fma_f32 v[6:7], v[0:1], v[120:121], v[2:3] op_sel_hi:[1,0,1]
	v_pk_mul_f32 v[2:3], v[118:119], v[0:1] op_sel:[1,1] op_sel_hi:[1,0] neg_lo:[0,1]
	s_add_u32 s6, s2, 0x2000
	v_pk_fma_f32 v[4:5], v[0:1], v[118:119], v[2:3] op_sel_hi:[1,0,1]
	v_pk_mul_f32 v[2:3], v[116:117], v[0:1] op_sel:[1,1] op_sel_hi:[1,0] neg_lo:[0,1]
	v_pk_mul_f32 v[128:129], v[110:111], v[0:1] op_sel:[1,1] op_sel_hi:[1,0] neg_lo:[0,1]
	v_pk_fma_f32 v[2:3], v[0:1], v[116:117], v[2:3] op_sel_hi:[1,0,1]
	v_pk_fma_f32 v[0:1], v[0:1], v[110:111], v[128:129] op_sel_hi:[1,0,1]
	s_addc_u32 s7, s3, 0
	v_bfe_u32 v129, v206, 4, 4
	v_and_b32_e32 v128, 15, v206
	v_mul_u32_u24_e32 v129, 0x880, v129
	v_lshlrev_b32_e32 v128, 3, v128
	v_add3_u32 v164, v207, v129, v128
	ds_read2_b64 v[128:131], v164 offset1:17
	ds_read2_b64 v[132:135], v164 offset0:34 offset1:51
	ds_read2_b64 v[136:139], v164 offset0:68 offset1:85
	ds_read2_b64 v[140:143], v164 offset0:102 offset1:119
	ds_read2_b64 v[144:147], v164 offset0:136 offset1:153
	ds_read2_b64 v[148:151], v164 offset0:170 offset1:187
	ds_read2_b64 v[152:155], v164 offset0:204 offset1:221
	ds_read2_b64 v[156:159], v164 offset0:238 offset1:255
	s_add_u32 s42, s42, 0x4000
	s_waitcnt lgkmcnt(3)
	v_pk_add_f32 v[160:161], v[128:129], v[144:145]
	v_pk_add_f32 v[128:129], v[128:129], v[144:145] neg_lo:[0,1] neg_hi:[0,1]
	s_waitcnt lgkmcnt(1)
	v_pk_add_f32 v[144:145], v[136:137], v[152:153]
	v_pk_add_f32 v[136:137], v[136:137], v[152:153] neg_lo:[0,1] neg_hi:[0,1]
	s_addc_u32 s43, s43, 0
	v_pk_add_f32 v[162:163], v[128:129], v[136:137] op_sel:[0,1] op_sel_hi:[1,0] neg_lo:[0,1]
	v_pk_add_f32 v[128:129], v[128:129], v[136:137] op_sel:[0,1] op_sel_hi:[1,0] neg_hi:[0,1]
	v_pk_add_f32 v[152:153], v[130:131], v[146:147]
	v_pk_add_f32 v[130:131], v[130:131], v[146:147] neg_lo:[0,1] neg_hi:[0,1]
	v_pk_add_f32 v[146:147], v[138:139], v[154:155]
	v_pk_add_f32 v[138:139], v[138:139], v[154:155] neg_lo:[0,1] neg_hi:[0,1]
	v_pk_add_f32 v[136:137], v[160:161], v[144:145]
	v_xor_b32_e32 v154, 0x80000000, v139
	v_mov_b32_e32 v155, v138
	v_pk_add_f32 v[138:139], v[152:153], v[146:147]
	v_pk_add_f32 v[146:147], v[152:153], v[146:147] neg_lo:[0,1] neg_hi:[0,1]
	v_pk_add_f32 v[152:153], v[132:133], v[148:149]
	v_pk_add_f32 v[132:133], v[132:133], v[148:149] neg_lo:[0,1] neg_hi:[0,1]
	s_waitcnt lgkmcnt(0)
	v_pk_add_f32 v[148:149], v[140:141], v[156:157]
	v_pk_add_f32 v[140:141], v[140:141], v[156:157] neg_lo:[0,1] neg_hi:[0,1]
	v_pk_add_f32 v[144:145], v[160:161], v[144:145] neg_lo:[0,1] neg_hi:[0,1]
	v_pk_add_f32 v[160:161], v[130:131], v[154:155]
	v_pk_add_f32 v[130:131], v[130:131], v[154:155] neg_lo:[0,1] neg_hi:[0,1]
	v_xor_b32_e32 v154, 0x80000000, v141
	v_mov_b32_e32 v155, v140
	v_pk_add_f32 v[140:141], v[152:153], v[148:149]
	v_pk_add_f32 v[148:149], v[152:153], v[148:149] neg_lo:[0,1] neg_hi:[0,1]
	v_pk_add_f32 v[152:153], v[134:135], v[150:151]
	v_pk_add_f32 v[134:135], v[134:135], v[150:151] neg_lo:[0,1] neg_hi:[0,1]
	v_pk_add_f32 v[150:151], v[142:143], v[158:159]
	v_pk_add_f32 v[142:143], v[142:143], v[158:159] neg_lo:[0,1] neg_hi:[0,1]
	v_pk_add_f32 v[156:157], v[132:133], v[154:155]
	v_pk_add_f32 v[132:133], v[132:133], v[154:155] neg_lo:[0,1] neg_hi:[0,1]
	v_pk_add_f32 v[158:159], v[134:135], v[142:143] op_sel:[0,1] op_sel_hi:[1,0] neg_lo:[0,1]
	v_pk_add_f32 v[134:135], v[134:135], v[142:143] op_sel:[0,1] op_sel_hi:[1,0] neg_hi:[0,1]
	v_pk_mul_f32 v[154:155], v[146:147], s[12:13] op_sel:[1,0] op_sel_hi:[0,0] neg_lo:[1,0]
	v_pk_add_f32 v[142:143], v[152:153], v[150:151]
	v_pk_fma_f32 v[146:147], v[146:147], s[12:13], v[154:155] op_sel_hi:[1,0,1]
	v_pk_mul_f32 v[154:155], v[130:131], s[36:37] op_sel:[1,0] op_sel_hi:[0,0] neg_lo:[1,0]
	v_pk_add_f32 v[150:151], v[152:153], v[150:151] neg_lo:[0,1] neg_hi:[0,1]
	v_pk_fma_f32 v[130:131], v[130:131], s[22:23], v[154:155] op_sel_hi:[1,0,1]
	v_pk_mul_f32 v[154:155], v[156:157], s[12:13] op_sel:[1,0] op_sel_hi:[0,0] neg_lo:[1,0]
	v_pk_fma_f32 v[154:155], v[156:157], s[12:13], v[154:155] op_sel_hi:[1,0,1]
	v_pk_fma_f32 v[148:149], v[148:149], 0, v[148:149] op_sel:[0,0,1] op_sel_hi:[1,0,0] neg_lo:[0,0,1]
	v_xor_b32_e32 v156, 0x80000000, v133
	v_mov_b32_e32 v157, v132
	v_pk_mul_f32 v[132:133], v[132:133], s[12:13] op_sel_hi:[1,0]
	v_pk_fma_f32 v[132:133], v[156:157], s[12:13], v[132:133] op_sel_hi:[1,0,1] neg_lo:[0,0,1] neg_hi:[0,0,1]
	v_pk_mul_f32 v[156:157], v[158:159], s[36:37] op_sel:[1,0] op_sel_hi:[0,0] neg_lo:[1,0]
	v_pk_mul_f32 v[152:153], v[160:161], s[22:23] op_sel:[1,0] op_sel_hi:[0,0] neg_lo:[1,0]
	v_pk_fma_f32 v[156:157], v[158:159], s[22:23], v[156:157] op_sel_hi:[1,0,1]
	v_xor_b32_e32 v158, 0x80000000, v151
	v_mov_b32_e32 v159, v150
	v_pk_mul_f32 v[150:151], v[150:151], s[12:13] op_sel_hi:[1,0]
	v_pk_fma_f32 v[152:153], v[160:161], s[36:37], v[152:153] op_sel_hi:[1,0,1]
	v_pk_fma_f32 v[150:151], v[158:159], s[12:13], v[150:151] op_sel_hi:[1,0,1] neg_lo:[0,0,1] neg_hi:[0,0,1]
	v_pk_mul_f32 v[158:159], v[134:135], s[22:23] op_sel:[1,0] op_sel_hi:[0,0] neg_lo:[1,0]
	s_addk_i32 s47, 0x2000
	v_pk_fma_f32 v[134:135], v[134:135], s[26:27], v[158:159] op_sel_hi:[1,0,1] neg_lo:[0,0,1] neg_hi:[0,0,1]
	v_pk_add_f32 v[158:159], v[136:137], v[140:141]
	v_pk_add_f32 v[136:137], v[136:137], v[140:141] neg_lo:[0,1] neg_hi:[0,1]
	v_pk_add_f32 v[140:141], v[138:139], v[142:143]
	v_pk_add_f32 v[138:139], v[138:139], v[142:143] neg_lo:[0,1] neg_hi:[0,1]
	s_cmp_eq_u32 s42, 0x10000
	v_xor_b32_e32 v142, 0x80000000, v139
	v_mov_b32_e32 v143, v138
	v_pk_add_f32 v[138:139], v[158:159], v[140:141]
	v_pk_add_f32 v[140:141], v[158:159], v[140:141] neg_lo:[0,1] neg_hi:[0,1]
	v_pk_add_f32 v[158:159], v[152:153], v[156:157]
	v_pk_add_f32 v[152:153], v[152:153], v[156:157] neg_lo:[0,1] neg_hi:[0,1]
	v_pk_add_f32 v[160:161], v[136:137], v[142:143]
	v_pk_add_f32 v[136:137], v[136:137], v[142:143] neg_lo:[0,1] neg_hi:[0,1]
	v_pk_add_f32 v[142:143], v[162:163], v[154:155]
	v_pk_add_f32 v[154:155], v[162:163], v[154:155] neg_lo:[0,1] neg_hi:[0,1]
	v_pk_add_f32 v[162:163], v[154:155], v[152:153] op_sel:[0,1] op_sel_hi:[1,0] neg_lo:[0,1]
	v_pk_add_f32 v[154:155], v[154:155], v[152:153] op_sel:[0,1] op_sel_hi:[1,0] neg_hi:[0,1]
	v_pk_add_f32 v[156:157], v[144:145], v[148:149]
	v_pk_add_f32 v[144:145], v[144:145], v[148:149] neg_lo:[0,1] neg_hi:[0,1]
	v_pk_add_f32 v[148:149], v[146:147], v[150:151]
	v_pk_add_f32 v[146:147], v[146:147], v[150:151] neg_lo:[0,1] neg_hi:[0,1]
	v_pk_add_f32 v[152:153], v[142:143], v[158:159]
	v_pk_add_f32 v[142:143], v[142:143], v[158:159] neg_lo:[0,1] neg_hi:[0,1]
	v_pk_add_f32 v[158:159], v[144:145], v[146:147] op_sel:[0,1] op_sel_hi:[1,0] neg_lo:[0,1]
	v_pk_add_f32 v[144:145], v[144:145], v[146:147] op_sel:[0,1] op_sel_hi:[1,0] neg_hi:[0,1]
	v_pk_add_f32 v[150:151], v[128:129], v[132:133]
	v_pk_add_f32 v[128:129], v[128:129], v[132:133] neg_lo:[0,1] neg_hi:[0,1]
	v_pk_add_f32 v[132:133], v[130:131], v[134:135]
	v_pk_add_f32 v[130:131], v[130:131], v[134:135] neg_lo:[0,1] neg_hi:[0,1]
	v_pk_add_f32 v[146:147], v[156:157], v[148:149]
	v_pk_add_f32 v[148:149], v[156:157], v[148:149] neg_lo:[0,1] neg_hi:[0,1]
	v_pk_add_f32 v[156:157], v[128:129], v[130:131] op_sel:[0,1] op_sel_hi:[1,0] neg_lo:[0,1]
	v_pk_add_f32 v[128:129], v[128:129], v[130:131] op_sel:[0,1] op_sel_hi:[1,0] neg_hi:[0,1]
	v_xor_b32_e32 v134, 0x80000000, v115
	v_mov_b32_e32 v135, v114
	v_pk_mul_f32 v[134:135], v[134:135], v[138:139] op_sel:[0,1]
	v_pk_add_f32 v[130:131], v[150:151], v[132:133]
	v_pk_fma_f32 v[114:115], v[114:115], v[138:139], v[134:135] op_sel_hi:[1,0,1]
	v_pk_mul_f32 v[134:135], v[126:127], v[152:153] op_sel:[1,1] op_sel_hi:[0,1] neg_lo:[1,0]
	v_pk_add_f32 v[132:133], v[150:151], v[132:133] neg_lo:[0,1] neg_hi:[0,1]
	v_pk_fma_f32 v[126:127], v[126:127], v[152:153], v[134:135] op_sel_hi:[1,0,1]
	ds_write2_b64 v164, v[114:115], v[126:127] offset1:17
	v_pk_mul_f32 v[114:115], v[124:125], v[146:147] op_sel:[1,1] op_sel_hi:[0,1] neg_lo:[1,0]
	v_pk_fma_f32 v[114:115], v[124:125], v[146:147], v[114:115] op_sel_hi:[1,0,1]
	v_pk_mul_f32 v[124:125], v[122:123], v[130:131] op_sel:[1,1] op_sel_hi:[0,1] neg_lo:[1,0]
	v_pk_fma_f32 v[122:123], v[122:123], v[130:131], v[124:125] op_sel_hi:[1,0,1]
	ds_write2_b64 v164, v[114:115], v[122:123] offset0:34 offset1:51
	v_pk_mul_f32 v[114:115], v[120:121], v[160:161] op_sel:[1,1] op_sel_hi:[0,1] neg_lo:[1,0]
	v_pk_fma_f32 v[114:115], v[120:121], v[160:161], v[114:115] op_sel_hi:[1,0,1]
	v_pk_mul_f32 v[120:121], v[118:119], v[162:163] op_sel:[1,1] op_sel_hi:[0,1] neg_lo:[1,0]
	v_pk_fma_f32 v[118:119], v[118:119], v[162:163], v[120:121] op_sel_hi:[1,0,1]
	ds_write2_b64 v164, v[114:115], v[118:119] offset0:68 offset1:85
	v_pk_mul_f32 v[114:115], v[116:117], v[158:159] op_sel:[1,1] op_sel_hi:[0,1] neg_lo:[1,0]
	v_pk_fma_f32 v[114:115], v[116:117], v[158:159], v[114:115] op_sel_hi:[1,0,1]
	v_pk_mul_f32 v[116:117], v[110:111], v[156:157] op_sel:[1,1] op_sel_hi:[0,1] neg_lo:[1,0]
	v_pk_fma_f32 v[110:111], v[110:111], v[156:157], v[116:117] op_sel_hi:[1,0,1]
	ds_write2_b64 v164, v[114:115], v[110:111] offset0:102 offset1:119
	v_pk_mul_f32 v[110:111], v[112:113], v[140:141] op_sel:[1,1] op_sel_hi:[0,1] neg_lo:[1,0]
	v_pk_fma_f32 v[110:111], v[112:113], v[140:141], v[110:111] op_sel_hi:[1,0,1]
	v_pk_mul_f32 v[112:113], v[108:109], v[142:143] op_sel:[1,1] op_sel_hi:[0,1] neg_lo:[1,0]
	v_pk_fma_f32 v[108:109], v[108:109], v[142:143], v[112:113] op_sel_hi:[1,0,1]
	ds_write2_b64 v164, v[110:111], v[108:109] offset0:136 offset1:153
	v_pk_mul_f32 v[108:109], v[106:107], v[148:149] op_sel:[1,1] op_sel_hi:[0,1] neg_lo:[1,0]
	v_pk_fma_f32 v[106:107], v[106:107], v[148:149], v[108:109] op_sel_hi:[1,0,1]
	v_pk_mul_f32 v[108:109], v[104:105], v[132:133] op_sel:[1,1] op_sel_hi:[0,1] neg_lo:[1,0]
	v_pk_fma_f32 v[104:105], v[104:105], v[132:133], v[108:109] op_sel_hi:[1,0,1]
	ds_write2_b64 v164, v[106:107], v[104:105] offset0:170 offset1:187
	v_pk_mul_f32 v[104:105], v[6:7], v[136:137] op_sel:[1,1] op_sel_hi:[0,1] neg_lo:[1,0]
	s_waitcnt vmcnt(5)
	v_and_b32_e32 v133, 0xffff0000, v13
	v_pk_fma_f32 v[6:7], v[6:7], v[136:137], v[104:105] op_sel_hi:[1,0,1]
	v_pk_mul_f32 v[104:105], v[4:5], v[154:155] op_sel:[1,1] op_sel_hi:[0,1] neg_lo:[1,0]
	v_lshlrev_b32_e32 v136, 16, v12
	v_pk_fma_f32 v[4:5], v[4:5], v[154:155], v[104:105] op_sel_hi:[1,0,1]
	ds_write2_b64 v164, v[6:7], v[4:5] offset0:204 offset1:221
	v_pk_mul_f32 v[4:5], v[2:3], v[144:145] op_sel:[1,1] op_sel_hi:[0,1] neg_lo:[1,0]
	v_and_b32_e32 v137, 0xffff0000, v12
	v_pk_fma_f32 v[2:3], v[2:3], v[144:145], v[4:5] op_sel_hi:[1,0,1]
	v_pk_mul_f32 v[4:5], v[0:1], v[128:129] op_sel:[1,1] op_sel_hi:[0,1] neg_lo:[1,0]
	v_pk_fma_f32 v[0:1], v[0:1], v[128:129], v[4:5] op_sel_hi:[1,0,1]
	ds_write2_b64 v164, v[2:3], v[0:1] offset0:238 offset1:255
	v_mov_b32_e32 v0, v206
	s_waitcnt lgkmcnt(0)
	s_barrier
	s_nop 0
	v_lshlrev_b32_sdwa v1, v228, v0 dst_sel:DWORD dst_unused:UNUSED_PAD src0_sel:DWORD src1_sel:BYTE_0
	v_lshrrev_b32_e32 v0, 1, v206
	v_and_b32_e32 v0, 0x78, v0
	v_add3_u32 v132, v207, v1, v0
	ds_read_b64 v[0:1], v132
	ds_read_b64 v[2:3], v132 offset:2176
	ds_read_b64 v[4:5], v132 offset:4352
	ds_read_b64 v[6:7], v132 offset:6528
	ds_read_b64 v[104:105], v132 offset:8704
	ds_read_b64 v[106:107], v132 offset:10880
	ds_read_b64 v[108:109], v132 offset:13056
	ds_read_b64 v[110:111], v132 offset:15232
	ds_read_b64 v[112:113], v132 offset:17408
	ds_read_b64 v[114:115], v132 offset:19584
	ds_read_b64 v[116:117], v132 offset:21760
	ds_read_b64 v[118:119], v132 offset:23936
	ds_read_b64 v[120:121], v132 offset:26112
	ds_read_b64 v[122:123], v132 offset:28288
	ds_read_b64 v[124:125], v132 offset:30464
	ds_read_b64 v[126:127], v132 offset:32640
	s_waitcnt lgkmcnt(7)
	v_pk_add_f32 v[128:129], v[0:1], v[112:113]
	v_pk_add_f32 v[0:1], v[0:1], v[112:113] neg_lo:[0,1] neg_hi:[0,1]
	s_waitcnt lgkmcnt(3)
	v_pk_add_f32 v[112:113], v[104:105], v[120:121]
	v_pk_add_f32 v[104:105], v[104:105], v[120:121] neg_lo:[0,1] neg_hi:[0,1]
	v_pk_add_f32 v[130:131], v[0:1], v[104:105] op_sel:[0,1] op_sel_hi:[1,0] neg_lo:[0,1]
	v_pk_add_f32 v[0:1], v[0:1], v[104:105] op_sel:[0,1] op_sel_hi:[1,0] neg_hi:[0,1]
	v_pk_add_f32 v[120:121], v[2:3], v[114:115]
	v_pk_add_f32 v[2:3], v[2:3], v[114:115] neg_lo:[0,1] neg_hi:[0,1]
	s_waitcnt lgkmcnt(2)
	v_pk_add_f32 v[114:115], v[106:107], v[122:123]
	v_pk_add_f32 v[106:107], v[106:107], v[122:123] neg_lo:[0,1] neg_hi:[0,1]
	v_pk_add_f32 v[104:105], v[128:129], v[112:113]
	v_xor_b32_e32 v122, 0x80000000, v107
	v_mov_b32_e32 v123, v106
	v_pk_add_f32 v[106:107], v[120:121], v[114:115]
	v_pk_add_f32 v[114:115], v[120:121], v[114:115] neg_lo:[0,1] neg_hi:[0,1]
	v_pk_add_f32 v[120:121], v[4:5], v[116:117]
	v_pk_add_f32 v[4:5], v[4:5], v[116:117] neg_lo:[0,1] neg_hi:[0,1]
	s_waitcnt lgkmcnt(1)
	v_pk_add_f32 v[116:117], v[108:109], v[124:125]
	v_pk_add_f32 v[108:109], v[108:109], v[124:125] neg_lo:[0,1] neg_hi:[0,1]
	v_pk_add_f32 v[112:113], v[128:129], v[112:113] neg_lo:[0,1] neg_hi:[0,1]
	v_pk_add_f32 v[128:129], v[2:3], v[122:123]
	v_pk_add_f32 v[2:3], v[2:3], v[122:123] neg_lo:[0,1] neg_hi:[0,1]
	v_xor_b32_e32 v122, 0x80000000, v109
	v_mov_b32_e32 v123, v108
	v_pk_add_f32 v[108:109], v[120:121], v[116:117]
	v_pk_add_f32 v[116:117], v[120:121], v[116:117] neg_lo:[0,1] neg_hi:[0,1]
	v_pk_add_f32 v[120:121], v[6:7], v[118:119]
	v_pk_add_f32 v[6:7], v[6:7], v[118:119] neg_lo:[0,1] neg_hi:[0,1]
	s_waitcnt lgkmcnt(0)
	v_pk_add_f32 v[118:119], v[110:111], v[126:127]
	v_pk_add_f32 v[110:111], v[110:111], v[126:127] neg_lo:[0,1] neg_hi:[0,1]
	v_pk_add_f32 v[124:125], v[4:5], v[122:123]
	v_pk_add_f32 v[4:5], v[4:5], v[122:123] neg_lo:[0,1] neg_hi:[0,1]
	v_pk_add_f32 v[126:127], v[6:7], v[110:111] op_sel:[0,1] op_sel_hi:[1,0] neg_lo:[0,1]
	v_pk_add_f32 v[6:7], v[6:7], v[110:111] op_sel:[0,1] op_sel_hi:[1,0] neg_hi:[0,1]
	v_pk_mul_f32 v[122:123], v[114:115], s[12:13] op_sel:[1,0] op_sel_hi:[0,0] neg_lo:[1,0]
	v_pk_add_f32 v[110:111], v[120:121], v[118:119]
	v_pk_fma_f32 v[114:115], v[114:115], s[12:13], v[122:123] op_sel_hi:[1,0,1]
	v_pk_mul_f32 v[122:123], v[2:3], s[36:37] op_sel:[1,0] op_sel_hi:[0,0] neg_lo:[1,0]
	v_pk_add_f32 v[118:119], v[120:121], v[118:119] neg_lo:[0,1] neg_hi:[0,1]
	v_pk_fma_f32 v[2:3], v[2:3], s[22:23], v[122:123] op_sel_hi:[1,0,1]
	v_pk_mul_f32 v[122:123], v[124:125], s[12:13] op_sel:[1,0] op_sel_hi:[0,0] neg_lo:[1,0]
	v_pk_fma_f32 v[122:123], v[124:125], s[12:13], v[122:123] op_sel_hi:[1,0,1]
	v_pk_fma_f32 v[116:117], v[116:117], 0, v[116:117] op_sel:[0,0,1] op_sel_hi:[1,0,0] neg_lo:[0,0,1]
	v_xor_b32_e32 v124, 0x80000000, v5
	v_mov_b32_e32 v125, v4
	v_pk_mul_f32 v[4:5], v[4:5], s[12:13] op_sel_hi:[1,0]
	v_pk_fma_f32 v[4:5], v[124:125], s[12:13], v[4:5] op_sel_hi:[1,0,1] neg_lo:[0,0,1] neg_hi:[0,0,1]
	v_pk_mul_f32 v[124:125], v[126:127], s[36:37] op_sel:[1,0] op_sel_hi:[0,0] neg_lo:[1,0]
	v_pk_mul_f32 v[120:121], v[128:129], s[22:23] op_sel:[1,0] op_sel_hi:[0,0] neg_lo:[1,0]
	v_pk_fma_f32 v[124:125], v[126:127], s[22:23], v[124:125] op_sel_hi:[1,0,1]
	v_xor_b32_e32 v126, 0x80000000, v119
	v_mov_b32_e32 v127, v118
	v_pk_mul_f32 v[118:119], v[118:119], s[12:13] op_sel_hi:[1,0]
	v_pk_fma_f32 v[120:121], v[128:129], s[36:37], v[120:121] op_sel_hi:[1,0,1]
	v_pk_fma_f32 v[118:119], v[126:127], s[12:13], v[118:119] op_sel_hi:[1,0,1] neg_lo:[0,0,1] neg_hi:[0,0,1]
	v_pk_mul_f32 v[126:127], v[6:7], s[22:23] op_sel:[1,0] op_sel_hi:[0,0] neg_lo:[1,0]
	v_pk_fma_f32 v[6:7], v[6:7], s[26:27], v[126:127] op_sel_hi:[1,0,1] neg_lo:[0,0,1] neg_hi:[0,0,1]
	v_pk_add_f32 v[126:127], v[104:105], v[108:109]
	v_pk_add_f32 v[104:105], v[104:105], v[108:109] neg_lo:[0,1] neg_hi:[0,1]
	v_pk_add_f32 v[108:109], v[106:107], v[110:111]
	v_pk_add_f32 v[106:107], v[106:107], v[110:111] neg_lo:[0,1] neg_hi:[0,1]
	v_xor_b32_e32 v110, 0x80000000, v107
	v_mov_b32_e32 v111, v106
	v_pk_add_f32 v[106:107], v[126:127], v[108:109]
	v_pk_add_f32 v[108:109], v[126:127], v[108:109] neg_lo:[0,1] neg_hi:[0,1]
	v_pk_add_f32 v[126:127], v[120:121], v[124:125]
	v_pk_add_f32 v[120:121], v[120:121], v[124:125] neg_lo:[0,1] neg_hi:[0,1]
	v_pk_add_f32 v[128:129], v[104:105], v[110:111]
	v_pk_add_f32 v[104:105], v[104:105], v[110:111] neg_lo:[0,1] neg_hi:[0,1]
	v_pk_add_f32 v[110:111], v[130:131], v[122:123]
	v_pk_add_f32 v[122:123], v[130:131], v[122:123] neg_lo:[0,1] neg_hi:[0,1]
	v_pk_add_f32 v[130:131], v[122:123], v[120:121] op_sel:[0,1] op_sel_hi:[1,0] neg_lo:[0,1]
	v_pk_add_f32 v[122:123], v[122:123], v[120:121] op_sel:[0,1] op_sel_hi:[1,0] neg_hi:[0,1]
	v_pk_add_f32 v[124:125], v[112:113], v[116:117]
	v_pk_add_f32 v[112:113], v[112:113], v[116:117] neg_lo:[0,1] neg_hi:[0,1]
	v_pk_add_f32 v[116:117], v[114:115], v[118:119]
	v_pk_add_f32 v[114:115], v[114:115], v[118:119] neg_lo:[0,1] neg_hi:[0,1]
	v_pk_add_f32 v[120:121], v[110:111], v[126:127]
	v_pk_add_f32 v[110:111], v[110:111], v[126:127] neg_lo:[0,1] neg_hi:[0,1]
	v_pk_add_f32 v[126:127], v[112:113], v[114:115] op_sel:[0,1] op_sel_hi:[1,0] neg_lo:[0,1]
	v_pk_add_f32 v[112:113], v[112:113], v[114:115] op_sel:[0,1] op_sel_hi:[1,0] neg_hi:[0,1]
	v_pk_add_f32 v[118:119], v[0:1], v[4:5]
	v_pk_add_f32 v[0:1], v[0:1], v[4:5] neg_lo:[0,1] neg_hi:[0,1]
	v_pk_add_f32 v[4:5], v[2:3], v[6:7]
	v_pk_add_f32 v[2:3], v[2:3], v[6:7] neg_lo:[0,1] neg_hi:[0,1]
	v_pk_add_f32 v[114:115], v[124:125], v[116:117]
	v_pk_add_f32 v[116:117], v[124:125], v[116:117] neg_lo:[0,1] neg_hi:[0,1]
	v_pk_add_f32 v[124:125], v[0:1], v[2:3] op_sel:[0,1] op_sel_hi:[1,0] neg_lo:[0,1]
	v_pk_add_f32 v[0:1], v[0:1], v[2:3] op_sel:[0,1] op_sel_hi:[1,0] neg_hi:[0,1]
	v_pk_add_f32 v[2:3], v[118:119], v[4:5]
	v_pk_add_f32 v[4:5], v[118:119], v[4:5] neg_lo:[0,1] neg_hi:[0,1]
	ds_write_b64 v132, v[106:107]
	ds_write_b64 v132, v[128:129] offset:8704
	ds_write_b64 v132, v[108:109] offset:17408
	ds_write_b64 v132, v[104:105] offset:26112
	ds_write_b64 v132, v[120:121] offset:2176
	ds_write_b64 v132, v[130:131] offset:10880
	ds_write_b64 v132, v[110:111] offset:19584
	ds_write_b64 v132, v[122:123] offset:28288
	ds_write_b64 v132, v[114:115] offset:4352
	ds_write_b64 v132, v[126:127] offset:13056
	ds_write_b64 v132, v[116:117] offset:21760
	ds_write_b64 v132, v[112:113] offset:30464
	ds_write_b64 v132, v[2:3] offset:6528
	ds_write_b64 v132, v[124:125] offset:15232
	ds_write_b64 v132, v[4:5] offset:23936
	ds_write_b64 v132, v[0:1] offset:32640
	s_waitcnt lgkmcnt(0)
	s_barrier
	v_mov_b32_e32 v115, v214
	v_and_b32_e32 v1, 0x1ff, v212
	v_lshlrev_b32_e32 v2, 3, v1
	v_bfe_u32 v0, v212, 1, 8
	v_add_u32_e32 v104, v2, v0
	v_cmp_eq_u32_e32 vcc, 0, v1
	s_waitcnt vmcnt(3)
	v_lshlrev_b32_e32 v0, 16, v233
	v_cmp_eq_u32_e64 s[0:1], s37, v1
	v_cndmask_b32_e64 v139, v0, 0, vcc
	s_waitcnt vmcnt(2)
	v_lshlrev_b32_e32 v0, 16, v232
	v_cndmask_b32_e64 v135, v0, 0, s[0:1]
	s_waitcnt vmcnt(1)
	v_lshlrev_b32_e32 v0, 16, v231
	v_cndmask_b32_e64 v121, v0, 0, vcc
	s_waitcnt vmcnt(0)
	v_lshlrev_b32_e32 v0, 16, v176
	v_cndmask_b32_e64 v107, v0, 0, s[0:1]
	v_add_u32_e32 v0, -1, v2
	v_cndmask_b32_e64 v176, v0, 0, vcc
	v_add_u32_e32 v0, 8, v2
	v_cndmask_b32_e64 v12, v0, v229, s[0:1]
	v_lshlrev_b64 v[110:111], 1, v[176:177]
	v_mov_b32_e32 v114, v213
	v_lshlrev_b32_e32 v116, 16, v8
	v_and_b32_e32 v117, 0xffff0000, v8
	v_lshlrev_b32_e32 v8, 4, v1
	v_lshl_add_u64 v[112:113], s[2:3], 0, v[110:111]
	v_lshlrev_b32_e32 v12, 1, v12
	v_lshl_add_u64 v[110:111], s[6:7], 0, v[110:111]
	v_lshl_add_u32 v104, v104, 3, 0
	global_load_dwordx4 v[4:7], v8, s[2:3]
	global_load_dwordx4 v[0:3], v8, s[6:7]
	global_load_ushort v143, v[112:113], off
	global_load_ushort v142, v12, s[2:3]
	global_load_ushort v141, v[110:111], off
	global_load_ushort v140, v12, s[6:7]
	v_add_u32_e32 v12, 0x8800, v104
	ds_read2_b64 v[110:113], v104 offset1:1
	ds_read2_b64 v[122:125], v12 offset1:1
	v_xor_b32_e32 v119, 0x80000000, v115
	v_mov_b32_e32 v118, v114
	v_mov_b32_e32 v132, v137
	s_waitcnt lgkmcnt(0)
	v_pk_mul_f32 v[118:119], v[118:119], v[122:123] op_sel_hi:[1,0]
	v_lshlrev_b32_e32 v131, 16, v15
	v_pk_fma_f32 v[118:119], v[114:115], v[122:123], v[118:119] op_sel:[1,1,0] op_sel_hi:[0,1,1]
	v_pk_add_f32 v[122:123], v[110:111], v[118:119]
	v_pk_mul_f32 v[110:111], v[214:215], s[8:9] op_sel_hi:[0,1]
	v_pk_fma_f32 v[110:111], v[212:213], s[30:31], v[110:111] op_sel:[1,0,0]
	v_pk_add_f32 v[114:115], v[110:111], 0 neg_lo:[1,1] neg_hi:[1,1]
	v_mov_b32_e32 v114, v110
	v_pk_mul_f32 v[114:115], v[114:115], v[124:125] op_sel_hi:[1,0]
	v_and_b32_e32 v15, 0xffff0000, v15
	v_pk_fma_f32 v[114:115], v[110:111], v[124:125], v[114:115] op_sel:[1,1,0] op_sel_hi:[0,1,1]
	v_pk_add_f32 v[124:125], v[112:113], v[114:115]
	v_pk_mul_f32 v[112:113], v[110:111], s[8:9] op_sel:[1,0]
	v_add_u32_e32 v12, 0x8810, v104
	v_pk_fma_f32 v[114:115], v[110:111], s[30:31], v[112:113] op_sel_hi:[0,1,1]
	ds_read2_b64 v[110:113], v104 offset0:2 offset1:3
	ds_read2_b64 v[126:129], v12 offset1:1
	v_pk_add_f32 v[118:119], v[114:115], 0 neg_lo:[1,1] neg_hi:[1,1]
	v_mov_b32_e32 v134, v131
	v_mov_b32_e32 v118, v114
	v_and_b32_e32 v109, 0xffff0000, v9
	s_waitcnt lgkmcnt(0)
	v_pk_mul_f32 v[118:119], v[118:119], v[126:127] op_sel_hi:[1,0]
	v_pk_fma_f32 v[118:119], v[114:115], v[126:127], v[118:119] op_sel:[1,1,0] op_sel_hi:[0,1,1]
	v_pk_add_f32 v[126:127], v[110:111], v[118:119]
	v_pk_mul_f32 v[110:111], v[114:115], s[8:9] op_sel:[1,0]
	v_lshlrev_b32_e32 v105, 16, v11
	v_pk_fma_f32 v[110:111], v[114:115], s[30:31], v[110:111] op_sel_hi:[0,1,1]
	v_pk_add_f32 v[114:115], v[110:111], 0 neg_lo:[1,1] neg_hi:[1,1]
	v_and_b32_e32 v11, 0xffff0000, v11
	v_mov_b32_e32 v114, v110
	v_pk_mul_f32 v[114:115], v[114:115], v[128:129] op_sel_hi:[1,0]
	s_brev_b32 s0, 48
	v_pk_fma_f32 v[114:115], v[110:111], v[128:129], v[114:115] op_sel:[1,1,0] op_sel_hi:[0,1,1]
	v_pk_add_f32 v[128:129], v[112:113], v[114:115]
	v_pk_mul_f32 v[112:113], v[110:111], s[8:9] op_sel:[1,0]
	v_add_u32_e32 v12, 0x8820, v104
	v_pk_fma_f32 v[114:115], v[110:111], s[30:31], v[112:113] op_sel_hi:[0,1,1]
	ds_read2_b64 v[110:113], v104 offset0:4 offset1:5
	ds_read2_b64 v[144:147], v12 offset1:1
	v_pk_add_f32 v[118:119], v[114:115], 0 neg_lo:[1,1] neg_hi:[1,1]
	s_waitcnt lgkmcnt(0)
	v_mov_b32_e32 v12, v147
	v_mov_b32_e32 v118, v114
	v_pk_mul_f32 v[118:119], v[118:119], v[144:145] op_sel_hi:[1,0]
	v_pk_fma_f32 v[118:119], v[114:115], v[144:145], v[118:119] op_sel:[1,1,0] op_sel_hi:[0,1,1]
	v_pk_add_f32 v[110:111], v[110:111], v[118:119]
	v_pk_mul_f32 v[118:119], v[114:115], s[8:9] op_sel:[1,0]
	v_pk_fma_f32 v[114:115], v[114:115], s[30:31], v[118:119] op_sel_hi:[0,1,1]
	v_pk_add_f32 v[118:119], v[114:115], 0 neg_lo:[1,1] neg_hi:[1,1]
	v_mov_b32_e32 v118, v114
	v_pk_mul_f32 v[118:119], v[118:119], v[146:147] op_sel_hi:[1,0]
	ds_read2_b64 v[144:147], v104 offset0:6 offset1:7
	v_pk_fma_f32 v[118:119], v[114:115], v[12:13], v[118:119] op_sel:[1,0,0] op_sel_hi:[0,0,1]
	v_add_u32_e32 v12, 0x8830, v104
	ds_read2_b64 v[148:151], v12 offset1:1
	v_pk_add_f32 v[112:113], v[112:113], v[118:119]
	v_pk_mul_f32 v[118:119], v[114:115], s[8:9] op_sel:[1,0]
	s_waitcnt lgkmcnt(0)
	v_pk_fma_f32 v[118:119], v[114:115], s[30:31], v[118:119] op_sel_hi:[0,1,1]
	v_pk_add_f32 v[114:115], v[118:119], 0 neg_lo:[1,1] neg_hi:[1,1]
	v_mov_b32_e32 v114, v118
	v_pk_mul_f32 v[114:115], v[114:115], v[148:149] op_sel_hi:[1,0]
	v_pk_fma_f32 v[114:115], v[118:119], v[148:149], v[114:115] op_sel:[1,1,0] op_sel_hi:[0,1,1]
	v_pk_add_f32 v[114:115], v[144:145], v[114:115]
	v_pk_mul_f32 v[144:145], v[118:119], s[8:9] op_sel:[1,0]
	v_pk_fma_f32 v[118:119], v[118:119], s[30:31], v[144:145] op_sel_hi:[0,1,1]
	v_pk_add_f32 v[144:145], v[118:119], 0 neg_lo:[1,1] neg_hi:[1,1]
	v_mov_b32_e32 v144, v118
	v_pk_mul_f32 v[144:145], v[150:151], v[144:145] op_sel_hi:[0,1]
	v_pk_fma_f32 v[118:119], v[118:119], v[150:151], v[144:145] op_sel:[1,1,0] op_sel_hi:[0,1,1]
	v_lshlrev_b32_e32 v144, 16, v13
	v_mov_b32_e32 v138, v144
	v_pk_mul_f32 v[138:139], v[30:31], v[138:139]
	v_mov_b32_e32 v12, v136
	v_mov_b32_e32 v13, v144
	v_pk_fma_f32 v[136:137], v[30:31], v[136:137], v[138:139] op_sel:[0,0,1] op_sel_hi:[1,1,0]
	v_pk_mul_f32 v[138:139], v[102:103], v[132:133]
	v_lshlrev_b32_e32 v145, 16, v14
	v_pk_fma_f32 v[136:137], v[34:35], v[132:133], v[136:137]
	v_pk_fma_f32 v[12:13], v[100:101], v[12:13], v[138:139]
	v_pk_add_f32 v[136:137], v[36:37], v[136:137]
	v_pk_fma_f32 v[12:13], v[34:35], v[144:145], v[12:13]
	v_mov_b32_e32 v138, v122
	v_mov_b32_e32 v139, v126
	v_pk_add_f32 v[12:13], v[36:37], v[12:13]
	v_pk_mul_f32 v[136:137], v[136:137], v[138:139]
	v_mov_b32_e32 v138, v124
	v_mov_b32_e32 v139, v128
	v_pk_mul_f32 v[12:13], v[12:13], v[138:139]
	v_and_b32_e32 v14, 0xffff0000, v14
	v_mov_b32_e32 v138, v145
	v_mov_b32_e32 v139, v131
	v_pk_mov_b32 v[132:133], v[132:133], v[14:15] op_sel:[1,0]
	v_pk_mul_f32 v[138:139], v[102:103], v[138:139]
	v_mov_b32_e32 v144, v15
	v_pk_fma_f32 v[132:133], v[100:101], v[132:133], v[138:139]
	v_mov_b32_e32 v130, v14
	v_pk_fma_f32 v[132:133], v[34:35], v[14:15], v[132:133]
	v_pk_mul_f32 v[14:15], v[30:31], v[144:145]
	v_pk_add_f32 v[118:119], v[146:147], v[118:119]
	v_pk_fma_f32 v[14:15], v[30:31], v[130:131], v[14:15] op_sel:[0,0,1] op_sel_hi:[1,1,0]
	v_pk_add_f32 v[132:133], v[36:37], v[132:133]
	v_pk_fma_f32 v[14:15], v[34:35], v[134:135], v[14:15]
	v_mov_b32_e32 v130, v110
	v_mov_b32_e32 v131, v114
	v_pk_add_f32 v[14:15], v[36:37], v[14:15]
	v_pk_mul_f32 v[130:131], v[132:133], v[130:131]
	v_mov_b32_e32 v132, v112
	v_mov_b32_e32 v133, v118
	v_pk_mul_f32 v[14:15], v[14:15], v[132:133]
	v_mov_b32_e32 v104, v130
	v_mov_b32_e32 v108, v136
	v_lshlrev_b32_e32 v130, 16, v9
	v_mov_b32_e32 v120, v130
	v_mov_b32_e32 v106, v131
	v_cvt_pk_bf16_f32 v12, v108, v12
	v_lshlrev_b32_e32 v131, 16, v10
	v_mov_b32_e32 v108, v117
	v_pk_mul_f32 v[120:121], v[30:31], v[120:121]
	v_mov_b32_e32 v132, v116
	v_mov_b32_e32 v133, v130
	v_pk_fma_f32 v[116:117], v[30:31], v[116:117], v[120:121] op_sel:[0,0,1] op_sel_hi:[1,1,0]
	v_pk_mul_f32 v[120:121], v[102:103], v[108:109]
	v_mov_b32_e32 v126, v123
	v_and_b32_e32 v10, 0xffff0000, v10
	v_mov_b32_e32 v122, v131
	v_mov_b32_e32 v123, v105
	v_pk_fma_f32 v[116:117], v[34:35], v[108:109], v[116:117]
	v_pk_fma_f32 v[120:121], v[100:101], v[132:133], v[120:121]
	v_pk_mov_b32 v[108:109], v[108:109], v[10:11] op_sel:[1,0]
	v_pk_mul_f32 v[122:123], v[102:103], v[122:123]
	v_pk_fma_f32 v[120:121], v[34:35], v[130:131], v[120:121]
	v_pk_fma_f32 v[108:109], v[100:101], v[108:109], v[122:123]
	v_mov_b32_e32 v130, v11
	v_cvt_pk_bf16_f32 v14, v104, v14
	v_mov_b32_e32 v104, v10
	v_pk_fma_f32 v[108:109], v[34:35], v[10:11], v[108:109]
	v_pk_mul_f32 v[10:11], v[30:31], v[130:131]
	v_cvt_pk_bf16_f32 v15, v106, v15
	v_mov_b32_e32 v106, v105
	v_pk_fma_f32 v[10:11], v[30:31], v[104:105], v[10:11] op_sel:[0,0,1] op_sel_hi:[1,1,0]
	v_pk_add_f32 v[120:121], v[36:37], v[120:121]
	v_pk_fma_f32 v[10:11], v[34:35], v[106:107], v[10:11]
	v_mov_b32_e32 v128, v125
	v_pk_add_f32 v[10:11], v[36:37], v[10:11]
	v_mov_b32_e32 v118, v113
	v_pk_mul_f32 v[120:121], v[120:121], v[128:129]
	v_pk_add_f32 v[108:109], v[36:37], v[108:109]
	v_mov_b32_e32 v114, v111
	v_pk_mul_f32 v[10:11], v[10:11], v[118:119]
	v_pk_add_f32 v[116:117], v[36:37], v[116:117]
	v_pk_mul_f32 v[104:105], v[108:109], v[114:115]
	v_pk_mul_f32 v[116:117], v[116:117], v[126:127]
	v_mov_b32_e32 v9, v11
	v_mov_b32_e32 v11, v120
	v_mov_b32_e32 v108, v121
	v_mov_b32_e32 v110, v137
	v_mov_b32_e32 v107, v116
	v_cvt_pk_bf16_f32 v13, v110, v13
	v_mov_b32_e32 v109, v107
	v_cvt_pk_bf16_f32 v107, v105, v9
	v_mov_b32_e32 v9, v177
	v_mov_b32_e32 v106, v117
	v_lshl_add_u64 v[8:9], s[44:45], 0, v[8:9]
	v_mov_b32_e32 v110, v106
	v_cvt_pk_bf16_f32 v106, v104, v10
	v_add_co_u32_e32 v10, vcc, s0, v8
	v_cvt_pk_bf16_f32 v104, v109, v11
	s_nop 0
	v_addc_co_u32_e32 v11, vcc, 0, v9, vcc
	v_add_co_u32_e32 v8, vcc, 0xc002000, v8
	v_cvt_pk_bf16_f32 v105, v110, v108
	s_nop 0
	v_addc_co_u32_e32 v9, vcc, 0, v9, vcc
	global_store_dwordx4 v[10:11], v[12:15], off sc1
	global_store_dwordx4 v[8:9], v[104:107], off sc1
	s_cbranch_scc0 .LBB0_209
	s_load_dword s0, s[74:75], 0x0
	s_waitcnt lgkmcnt(0)
	s_add_i32 s38, s0, s38
	s_cmpk_gt_i32 s38, 0x1ff
	s_cbranch_scc0 .LBB0_204

.LBB0_305:
	s_waitcnt lgkmcnt(3)
	v_cvt_pk_bf16_f32 v0, v0, v1
	s_waitcnt lgkmcnt(2)
	v_mov_b32_e32 v1, v2
	s_ashr_i32 s6, s3, 31
	v_mov_b32_e32 v2, v3
	s_lshr_b32 s6, s6, 28
	v_cvt_pk_bf16_f32 v1, v1, v2
	s_waitcnt lgkmcnt(1)
	s_add_i32 s7, s3, s6
	v_mov_b32_e32 v2, v4
	s_and_b32 s6, s7, 0x3fffff0
	v_mov_b32_e32 v3, v5
	s_sub_i32 s3, s3, s6
	v_cvt_pk_bf16_f32 v2, v2, v3
	s_waitcnt lgkmcnt(0)
	s_lshl_b32 s6, s3, 6
	s_lshl_b32 s3, s7, 2
	v_mov_b32_e32 v3, v6
	s_andn2_b32 s3, s3, 63
	v_mov_b32_e32 v4, v7
	v_cvt_pk_bf16_f32 v3, v3, v4
	v_add_u32_e32 v4, s3, v31
	v_ashrrev_i32_e32 v5, 31, v4
	v_readlane_b32 s20, v254, 15
	v_lshlrev_b64 v[4:5], 11, v[4:5]
	v_readlane_b32 s21, v254, 16
	s_ashr_i32 s7, s6, 31
	s_andn2_b64 vcc, exec, s[0:1]
	v_lshl_add_u64 v[4:5], s[20:21], 0, v[4:5]
	v_lshl_add_u64 v[4:5], s[6:7], 1, v[4:5]
	v_lshl_add_u64 v[4:5], v[4:5], 0, v[176:177]
	s_mov_b32 s3, s2
	global_store_dwordx4 v[4:5], v[0:3], off sc1
	s_cbranch_vccz .LBB0_321

.LBB0_324:
	s_waitcnt lgkmcnt(3)
	v_cvt_pk_bf16_f32 v0, v0, v1
	s_waitcnt lgkmcnt(2)
	v_mov_b32_e32 v1, v2
	s_ashr_i32 s6, s3, 31
	v_mov_b32_e32 v2, v3
	s_lshr_b32 s6, s6, 28
	v_cvt_pk_bf16_f32 v1, v1, v2
	s_waitcnt lgkmcnt(1)
	s_add_i32 s7, s3, s6
	v_mov_b32_e32 v2, v4
	s_and_b32 s6, s7, 0x3fffff0
	v_mov_b32_e32 v3, v5
	s_sub_i32 s3, s3, s6
	v_cvt_pk_bf16_f32 v2, v2, v3
	s_waitcnt lgkmcnt(0)
	s_lshl_b32 s6, s3, 6
	s_lshl_b32 s3, s7, 2
	v_mov_b32_e32 v3, v6
	s_andn2_b32 s3, s3, 63
	v_mov_b32_e32 v4, v7
	v_cvt_pk_bf16_f32 v3, v3, v4
	v_add_u32_e32 v4, s3, v31
	v_ashrrev_i32_e32 v5, 31, v4
	v_readlane_b32 s20, v254, 41
	v_lshlrev_b64 v[4:5], 11, v[4:5]
	v_readlane_b32 s21, v254, 42
	s_ashr_i32 s7, s6, 31
	s_andn2_b64 vcc, exec, s[0:1]
	v_lshl_add_u64 v[4:5], s[20:21], 0, v[4:5]
	v_lshl_add_u64 v[4:5], s[6:7], 1, v[4:5]
	v_lshl_add_u64 v[4:5], v[4:5], 0, v[176:177]
	s_mov_b32 s3, s2
	global_store_dwordx4 v[4:5], v[0:3], off sc1
	s_cbranch_vccz .LBB0_340

.LBB0_342:
	s_waitcnt lgkmcnt(3)
	v_cvt_pk_bf16_f32 v0, v0, v1
	s_waitcnt lgkmcnt(2)
	v_mov_b32_e32 v1, v2
	v_mov_b32_e32 v2, v3
	v_cvt_pk_bf16_f32 v1, v1, v2
	s_waitcnt lgkmcnt(1)
	v_mov_b32_e32 v2, v4
	v_mov_b32_e32 v3, v5
	v_cvt_pk_bf16_f32 v2, v2, v3
	s_waitcnt lgkmcnt(0)
	v_mov_b32_e32 v3, v6
	s_ashr_i32 s3, s6, 4
	v_mov_b32_e32 v4, v7
	v_cvt_pk_bf16_f32 v3, v3, v4
	v_lshl_add_u32 v4, s3, 6, v32
	v_ashrrev_i32_e32 v5, 31, v4
	v_readlane_b32 s6, v253, 62
	v_lshlrev_b64 v[4:5], 11, v[4:5]
	v_readlane_b32 s7, v253, 63
	s_ashr_i32 s29, s28, 31
	v_lshlrev_b32_e32 v176, 1, v16
	v_lshl_add_u64 v[4:5], s[6:7], 0, v[4:5]
	v_lshl_add_u64 v[4:5], s[28:29], 1, v[4:5]
	v_lshl_add_u64 v[4:5], v[4:5], 0, v[176:177]
	s_andn2_b64 vcc, exec, s[0:1]
	s_mov_b32 s3, s2
	global_store_dwordx4 v[4:5], v[0:3], off sc1
	s_cbranch_vccz .LBB0_361

.LBB0_364:
	s_waitcnt lgkmcnt(3)
	v_cvt_pk_bf16_f32 v0, v0, v1
	s_waitcnt lgkmcnt(2)
	v_mov_b32_e32 v1, v2
	v_mov_b32_e32 v2, v3
	v_cvt_pk_bf16_f32 v1, v1, v2
	s_waitcnt lgkmcnt(1)
	v_mov_b32_e32 v2, v4
	s_ashr_i32 s6, s3, 31
	v_mov_b32_e32 v3, v5
	s_lshr_b32 s6, s6, 26
	v_cvt_pk_bf16_f32 v2, v2, v3
	s_waitcnt lgkmcnt(0)
	s_add_i32 s6, s3, s6
	v_mov_b32_e32 v3, v6
	s_and_b32 s7, s6, 0xffffffc0
	v_mov_b32_e32 v4, v7
	v_cvt_pk_bf16_f32 v3, v3, v4
	v_add_u32_e32 v4, s7, v31
	s_sub_i32 s3, s3, s7
	v_ashrrev_i32_e32 v5, 31, v4
	v_readlane_b32 s20, v254, 27
	s_lshl_b32 s6, s3, 6
	v_lshlrev_b64 v[4:5], 13, v[4:5]
	v_readlane_b32 s21, v254, 28
	s_ashr_i32 s7, s6, 31
	s_andn2_b64 vcc, exec, s[0:1]
	v_lshl_add_u64 v[4:5], s[20:21], 0, v[4:5]
	v_lshl_add_u64 v[4:5], s[6:7], 1, v[4:5]
	v_lshl_add_u64 v[4:5], v[4:5], 0, v[176:177]
	s_mov_b32 s3, s2
	global_store_dwordx4 v[4:5], v[0:3], off sc1
	s_cbranch_vccz .LBB0_380

.LBB0_446:
	v_ashrrev_i32_e32 v81, 31, v80
	v_lshlrev_b64 v[16:17], 12, v[80:81]
	v_lshl_add_u64 v[16:17], v[82:83], 0, v[16:17]
	v_add_u32_e32 v94, 1, v80
	global_load_dwordx4 v[76:79], v[16:17], off nt
	global_load_dwordx4 v[72:75], v[16:17], off offset:1024 nt
	global_load_dwordx4 v[68:71], v[16:17], off offset:2048 nt
	global_load_dwordx4 v[64:67], v[16:17], off offset:3072 nt
	v_ashrrev_i32_e32 v95, 31, v94
	v_lshlrev_b64 v[16:17], 12, v[94:95]
	v_lshl_add_u64 v[16:17], v[82:83], 0, v[16:17]
	global_load_dwordx4 v[60:63], v[16:17], off nt
	global_load_dwordx4 v[56:59], v[16:17], off offset:1024 nt
	global_load_dwordx4 v[52:55], v[16:17], off offset:2048 nt
	global_load_dwordx4 v[48:51], v[16:17], off offset:3072 nt
	v_add_u32_e32 v92, 2, v80
	v_ashrrev_i32_e32 v93, 31, v92
	v_lshlrev_b64 v[16:17], 12, v[92:93]
	v_lshl_add_u64 v[16:17], v[82:83], 0, v[16:17]
	global_load_dwordx4 v[44:47], v[16:17], off nt
	global_load_dwordx4 v[40:43], v[16:17], off offset:1024 nt
	global_load_dwordx4 v[36:39], v[16:17], off offset:2048 nt
	global_load_dwordx4 v[32:35], v[16:17], off offset:3072 nt
	v_add_u32_e32 v90, 3, v80
	v_ashrrev_i32_e32 v91, 31, v90
	v_lshlrev_b64 v[16:17], 12, v[90:91]
	v_lshl_add_u64 v[16:17], v[82:83], 0, v[16:17]
	global_load_dwordx4 v[28:31], v[16:17], off nt
	global_load_dwordx4 v[24:27], v[16:17], off offset:1024 nt
	global_load_dwordx4 v[20:23], v[16:17], off offset:2048 nt
	s_nop 0
	global_load_dwordx4 v[16:19], v[16:17], off offset:3072 nt
	v_mov_b32_e32 v85, v177
	s_waitcnt vmcnt(15)
	v_mov_b32_e32 v98, v77
	s_waitcnt vmcnt(14)
	v_mov_b32_e32 v99, v73
	s_waitcnt vmcnt(13)
	v_mov_b32_e32 v112, v69
	s_waitcnt vmcnt(12)
	v_mov_b32_e32 v113, v65
	v_mov_b32_e32 v110, v68
	v_mov_b32_e32 v111, v64
	v_pk_mul_f32 v[112:113], v[112:113], v[112:113]
	v_mov_b32_e32 v96, v76
	v_mov_b32_e32 v97, v72
	v_mov_b32_e32 v114, v70
	v_mov_b32_e32 v115, v66
	v_pk_mul_f32 v[98:99], v[98:99], v[98:99]
	v_pk_fma_f32 v[110:111], v[110:111], v[110:111], v[112:113]
	v_mov_b32_e32 v100, v78
	v_mov_b32_e32 v101, v74
	v_pk_fma_f32 v[96:97], v[96:97], v[96:97], v[98:99]
	v_pk_fma_f32 v[110:111], v[114:115], v[114:115], v[110:111]
	s_waitcnt vmcnt(9)
	v_mov_b32_e32 v114, v53
	s_waitcnt vmcnt(8)
	v_mov_b32_e32 v115, v49
	v_mov_b32_e32 v120, v61
	v_mov_b32_e32 v121, v57
	v_pk_fma_f32 v[96:97], v[100:101], v[100:101], v[96:97]
	v_mov_b32_e32 v100, v52
	v_mov_b32_e32 v101, v48
	v_pk_mul_f32 v[114:115], v[114:115], v[114:115]
	v_mov_b32_e32 v118, v60
	v_mov_b32_e32 v119, v56
	v_pk_mul_f32 v[120:121], v[120:121], v[120:121]
	v_pk_fma_f32 v[100:101], v[100:101], v[100:101], v[114:115]
	s_waitcnt vmcnt(7)
	v_mov_b32_e32 v114, v45
	s_waitcnt vmcnt(6)
	v_mov_b32_e32 v115, v41
	v_mov_b32_e32 v98, v62
	v_mov_b32_e32 v99, v58
	v_pk_fma_f32 v[118:119], v[118:119], v[118:119], v[120:121]
	v_mov_b32_e32 v120, v44
	v_mov_b32_e32 v121, v40
	v_pk_mul_f32 v[114:115], v[114:115], v[114:115]
	v_mov_b32_e32 v108, v79
	v_mov_b32_e32 v109, v75
	v_mov_b32_e32 v116, v71
	v_mov_b32_e32 v117, v67
	v_mov_b32_e32 v112, v63
	v_mov_b32_e32 v113, v59
	v_pk_fma_f32 v[114:115], v[120:121], v[120:121], v[114:115]
	v_mov_b32_e32 v120, v54
	v_mov_b32_e32 v121, v50
	v_pk_fma_f32 v[98:99], v[98:99], v[98:99], v[118:119]
	v_pk_fma_f32 v[108:109], v[108:109], v[108:109], v[96:97]
	v_mov_b32_e32 v96, v55
	v_mov_b32_e32 v97, v51
	v_pk_fma_f32 v[110:111], v[116:117], v[116:117], v[110:111]
	v_mov_b32_e32 v116, v46
	v_mov_b32_e32 v117, v42
	v_pk_fma_f32 v[100:101], v[120:121], v[120:121], v[100:101]
	v_pk_fma_f32 v[112:113], v[112:113], v[112:113], v[98:99]
	v_pk_fma_f32 v[114:115], v[116:117], v[116:117], v[114:115]
	v_pk_fma_f32 v[100:101], v[96:97], v[96:97], v[100:101]
	v_mov_b32_e32 v116, v112
	v_mov_b32_e32 v117, v108
	v_mov_b32_e32 v108, v113
	v_pk_add_f32 v[108:109], v[116:117], v[108:109]
	v_mov_b32_e32 v112, v100
	v_mov_b32_e32 v113, v110
	v_pk_add_f32 v[108:109], v[108:109], v[112:113]
	v_mov_b32_e32 v110, v101
	v_pk_add_f32 v[100:101], v[108:109], v[110:111]
	ds_bpermute_b32 v109, v102, v101
	ds_bpermute_b32 v108, v102, v100
	v_mov_b32_e32 v118, v47
	v_mov_b32_e32 v119, v43
	v_pk_fma_f32 v[96:97], v[118:119], v[118:119], v[114:115]
	s_waitcnt vmcnt(5)
	v_mov_b32_e32 v114, v37
	s_waitcnt lgkmcnt(0)
	v_pk_add_f32 v[100:101], v[100:101], v[108:109]
	ds_bpermute_b32 v109, v103, v101
	ds_bpermute_b32 v108, v103, v100
	s_waitcnt vmcnt(4)
	v_mov_b32_e32 v115, v33
	v_mov_b32_e32 v98, v36
	v_mov_b32_e32 v99, v32
	v_pk_mul_f32 v[114:115], v[114:115], v[114:115]
	s_waitcnt lgkmcnt(0)
	v_pk_add_f32 v[100:101], v[100:101], v[108:109]
	ds_bpermute_b32 v109, v104, v101
	ds_bpermute_b32 v108, v104, v100
	v_pk_fma_f32 v[98:99], v[98:99], v[98:99], v[114:115]
	v_mov_b32_e32 v114, v38
	v_mov_b32_e32 v115, v34
	v_pk_fma_f32 v[98:99], v[114:115], v[114:115], v[98:99]
	s_waitcnt lgkmcnt(0)
	v_pk_add_f32 v[100:101], v[100:101], v[108:109]
	ds_bpermute_b32 v109, v105, v101
	ds_bpermute_b32 v108, v105, v100
	v_mov_b32_e32 v114, v39
	v_mov_b32_e32 v115, v35
	s_waitcnt vmcnt(3)
	v_mov_b32_e32 v110, v29
	s_waitcnt vmcnt(2)
	v_mov_b32_e32 v111, v25
	s_waitcnt lgkmcnt(0)
	v_pk_add_f32 v[100:101], v[100:101], v[108:109]
	ds_bpermute_b32 v109, v106, v101
	ds_bpermute_b32 v108, v106, v100
	v_pk_fma_f32 v[98:99], v[114:115], v[114:115], v[98:99]
	v_mov_b32_e32 v114, v28
	v_mov_b32_e32 v115, v24
	v_pk_mul_f32 v[110:111], v[110:111], v[110:111]
	s_waitcnt lgkmcnt(0)
	v_pk_add_f32 v[100:101], v[100:101], v[108:109]
	ds_bpermute_b32 v109, v107, v101
	ds_bpermute_b32 v108, v107, v100
	v_pk_fma_f32 v[110:111], v[114:115], v[114:115], v[110:111]
	v_mov_b32_e32 v112, v30
	v_mov_b32_e32 v113, v26
	v_pk_fma_f32 v[110:111], v[112:113], v[112:113], v[110:111]
	v_mov_b32_e32 v112, v31
	v_mov_b32_e32 v113, v27
	s_waitcnt vmcnt(1)
	v_mov_b32_e32 v114, v21
	s_waitcnt vmcnt(0)
	v_mov_b32_e32 v115, v17
	v_pk_fma_f32 v[110:111], v[112:113], v[112:113], v[110:111]
	v_mov_b32_e32 v112, v20
	v_mov_b32_e32 v113, v16
	v_pk_mul_f32 v[114:115], v[114:115], v[114:115]
	s_waitcnt lgkmcnt(0)
	v_pk_add_f32 v[108:109], v[100:101], v[108:109]
	v_pk_fma_f32 v[112:113], v[112:113], v[112:113], v[114:115]
	v_mov_b32_e32 v114, v22
	v_mov_b32_e32 v115, v18
	v_mov_b64_e32 v[100:101], s[20:21]
	v_pk_fma_f32 v[112:113], v[114:115], v[114:115], v[112:113]
	v_mov_b32_e32 v114, v23
	v_mov_b32_e32 v115, v19
	v_pk_fma_f32 v[108:109], v[108:109], s[6:7], v[100:101] op_sel_hi:[1,0,0]
	v_pk_fma_f32 v[112:113], v[114:115], v[114:115], v[112:113]
	v_lshlrev_b64 v[114:115], 11, v[80:81]
	v_mul_f32_e32 v81, 0x4b800000, v109
	v_cmp_gt_f32_e32 vcc, s23, v109
	v_lshl_add_u64 v[114:115], s[50:51], 0, v[114:115]
	v_lshl_add_u64 v[116:117], v[114:115], 0, v[176:177]
	v_cndmask_b32_e32 v81, v109, v81, vcc
	v_rsq_f32_e32 v81, v81
	v_add_u32_e32 v80, s2, v80
	v_mul_f32_e32 v87, 0x45800000, v81
	v_cndmask_b32_e32 v118, v81, v87, vcc
	v_pk_mul_f32 v[76:77], v[76:77], v[118:119] op_sel_hi:[1,0]
	v_pk_mul_f32 v[78:79], v[78:79], v[118:119] op_sel_hi:[1,0]
	v_pk_mul_f32 v[76:77], v[0:1], v[76:77]
	v_pk_mul_f32 v[78:79], v[2:3], v[78:79]
	v_mov_b32_e32 v81, v76
	v_mov_b32_e32 v89, v77
	v_mov_b32_e32 v109, v78
	v_mov_b32_e32 v78, v81
	v_mov_b32_e32 v81, v109
	v_pk_mul_f32 v[72:73], v[72:73], v[118:119] op_sel_hi:[1,0]
	v_cvt_pk_bf16_f32 v78, v78, v89
	v_cvt_pk_bf16_f32 v79, v81, v79
	v_pk_mul_f32 v[72:73], v[4:5], v[72:73]
	global_store_dwordx2 v[116:117], v[78:79], off sc1
	v_pk_mul_f32 v[74:75], v[74:75], v[118:119] op_sel_hi:[1,0]
	v_pk_mul_f32 v[74:75], v[6:7], v[74:75]
	v_cvt_pk_bf16_f32 v72, v72, v73
	v_mov_b32_e32 v73, v74
	v_mov_b32_e32 v74, v75
	v_pk_mul_f32 v[68:69], v[68:69], v[118:119] op_sel_hi:[1,0]
	v_lshl_add_u64 v[76:77], v[114:115], 0, v[84:85]
	v_cvt_pk_bf16_f32 v73, v73, v74
	v_pk_mul_f32 v[68:69], v[8:9], v[68:69]
	global_store_dwordx2 v[76:77], v[72:73], off sc1
	v_pk_mul_f32 v[70:71], v[70:71], v[118:119] op_sel_hi:[1,0]
	v_pk_mul_f32 v[70:71], v[10:11], v[70:71]
	v_cvt_pk_bf16_f32 v68, v68, v69
	v_mov_b32_e32 v69, v70
	v_mov_b32_e32 v87, v177
	v_mov_b32_e32 v70, v71
	v_pk_mul_f32 v[64:65], v[64:65], v[118:119] op_sel_hi:[1,0]
	v_lshl_add_u64 v[120:121], v[114:115], 0, v[86:87]
	v_cvt_pk_bf16_f32 v69, v69, v70
	v_pk_mul_f32 v[64:65], v[12:13], v[64:65]
	global_store_dwordx2 v[120:121], v[68:69], off sc1
	v_pk_mul_f32 v[66:67], v[66:67], v[118:119] op_sel_hi:[1,0]
	v_mul_f32_e32 v68, 0x4b800000, v108
	v_cmp_gt_f32_e32 vcc, s23, v108
	v_pk_mul_f32 v[66:67], v[14:15], v[66:67]
	v_cndmask_b32_e32 v68, v108, v68, vcc
	v_cvt_pk_bf16_f32 v64, v64, v65
	v_rsq_f32_e32 v68, v68
	v_mov_b32_e32 v65, v66
	v_mov_b32_e32 v89, v177
	v_mov_b32_e32 v66, v67
	v_lshl_add_u64 v[114:115], v[114:115], 0, v[88:89]
	v_cvt_pk_bf16_f32 v65, v65, v66
	global_store_dwordx2 v[114:115], v[64:65], off sc1
	v_mul_f32_e32 v64, 0x45800000, v68
	v_cndmask_b32_e32 v64, v68, v64, vcc
	v_pk_mul_f32 v[60:61], v[60:61], v[64:65] op_sel_hi:[1,0]
	v_pk_mul_f32 v[62:63], v[62:63], v[64:65] op_sel_hi:[1,0]
	v_pk_mul_f32 v[60:61], v[0:1], v[60:61]
	v_pk_mul_f32 v[62:63], v[2:3], v[62:63]
	v_bfe_u32 v65, v60, 16, 1
	v_add3_u32 v60, v60, v65, s13
	v_bfe_u32 v65, v61, 16, 1
	v_lshrrev_b32_e32 v60, 16, v60
	v_add3_u32 v61, v61, v65, s13
	v_and_or_b32 v60, v61, s33, v60
	v_lshlrev_b64 v[66:67], 11, v[94:95]
	v_mov_b32_e32 v61, v62
	v_lshl_add_u64 v[66:67], s[50:51], 0, v[66:67]
	v_mov_b32_e32 v62, v63
	v_pk_mul_f32 v[56:57], v[56:57], v[64:65] op_sel_hi:[1,0]
	v_cvt_pk_bf16_f32 v61, v61, v62
	v_lshl_add_u64 v[62:63], v[66:67], 0, v[176:177]
	v_pk_mul_f32 v[56:57], v[4:5], v[56:57]
	global_store_dwordx2 v[62:63], v[60:61], off sc1
	v_pk_mul_f32 v[58:59], v[58:59], v[64:65] op_sel_hi:[1,0]
	v_pk_mul_f32 v[58:59], v[6:7], v[58:59]
	v_cvt_pk_bf16_f32 v56, v56, v57
	v_mov_b32_e32 v57, v58
	v_mov_b32_e32 v58, v59
	v_pk_mul_f32 v[52:53], v[52:53], v[64:65] op_sel_hi:[1,0]
	v_cvt_pk_bf16_f32 v57, v57, v58
	v_lshl_add_u64 v[58:59], v[66:67], 0, v[84:85]
	v_pk_mul_f32 v[52:53], v[8:9], v[52:53]
	global_store_dwordx2 v[58:59], v[56:57], off sc1
	v_pk_mul_f32 v[54:55], v[54:55], v[64:65] op_sel_hi:[1,0]
	v_pk_mul_f32 v[54:55], v[10:11], v[54:55]
	v_cvt_pk_bf16_f32 v52, v52, v53
	v_mov_b32_e32 v53, v54
	v_mov_b32_e32 v58, v55
	v_mov_b32_e32 v54, v110
	v_mov_b32_e32 v55, v96
	v_mov_b32_e32 v96, v111
	v_pk_add_f32 v[54:55], v[54:55], v[96:97]
	v_mov_b32_e32 v56, v112
	v_mov_b32_e32 v57, v98
	v_pk_add_f32 v[54:55], v[54:55], v[56:57]
	v_mov_b32_e32 v98, v113
	v_pk_add_f32 v[54:55], v[54:55], v[98:99]
	ds_bpermute_b32 v57, v102, v55
	ds_bpermute_b32 v56, v102, v54
	v_cvt_pk_bf16_f32 v53, v53, v58
	v_lshl_add_u64 v[58:59], v[66:67], 0, v[86:87]
	global_store_dwordx2 v[58:59], v[52:53], off sc1
	s_waitcnt lgkmcnt(0)
	v_pk_add_f32 v[52:53], v[54:55], v[56:57]
	ds_bpermute_b32 v55, v103, v53
	ds_bpermute_b32 v54, v103, v52
	v_pk_mul_f32 v[48:49], v[48:49], v[64:65] op_sel_hi:[1,0]
	v_pk_mul_f32 v[50:51], v[50:51], v[64:65] op_sel_hi:[1,0]
	v_pk_mul_f32 v[48:49], v[12:13], v[48:49]
	v_pk_mul_f32 v[50:51], v[14:15], v[50:51]
	s_waitcnt lgkmcnt(0)
	v_pk_add_f32 v[52:53], v[52:53], v[54:55]
	ds_bpermute_b32 v55, v104, v53
	ds_bpermute_b32 v54, v104, v52
	v_mov_b32_e32 v56, v48
	v_mov_b32_e32 v57, v49
	s_waitcnt lgkmcnt(0)
	v_pk_add_f32 v[48:49], v[52:53], v[54:55]
	ds_bpermute_b32 v53, v105, v49
	ds_bpermute_b32 v52, v105, v48
	s_waitcnt lgkmcnt(0)
	v_pk_add_f32 v[48:49], v[48:49], v[52:53]
	ds_bpermute_b32 v53, v106, v49
	ds_bpermute_b32 v52, v106, v48
	v_cvt_pk_bf16_f32 v54, v56, v57
	v_cvt_pk_bf16_f32 v55, v50, v51
	v_lshl_add_u64 v[50:51], v[66:67], 0, v[88:89]
	s_waitcnt lgkmcnt(0)
	v_pk_add_f32 v[48:49], v[48:49], v[52:53]
	ds_bpermute_b32 v53, v107, v49
	ds_bpermute_b32 v52, v107, v48
	global_store_dwordx2 v[50:51], v[54:55], off sc1
	v_lshlrev_b64 v[50:51], 11, v[92:93]
	v_lshl_add_u64 v[50:51], s[50:51], 0, v[50:51]
	v_lshl_add_u64 v[54:55], v[50:51], 0, v[176:177]
	s_waitcnt lgkmcnt(0)
	v_pk_add_f32 v[48:49], v[48:49], v[52:53]
	v_lshl_add_u64 v[56:57], v[50:51], 0, v[86:87]
	v_pk_fma_f32 v[48:49], v[48:49], s[6:7], v[100:101] op_sel_hi:[1,0,0]
	s_nop 0
	v_mul_f32_e32 v52, 0x4b800000, v49
	v_cmp_gt_f32_e32 vcc, s23, v49
	s_nop 1
	v_cndmask_b32_e32 v49, v49, v52, vcc
	v_rsq_f32_e32 v49, v49
	v_lshl_add_u64 v[52:53], v[50:51], 0, v[84:85]
	v_lshl_add_u64 v[50:51], v[50:51], 0, v[88:89]
	v_mul_f32_e32 v58, 0x45800000, v49
	v_cndmask_b32_e32 v58, v49, v58, vcc
	v_pk_mul_f32 v[44:45], v[44:45], v[58:59] op_sel_hi:[1,0]
	v_pk_mul_f32 v[46:47], v[46:47], v[58:59] op_sel_hi:[1,0]
	v_pk_mul_f32 v[44:45], v[0:1], v[44:45]
	v_pk_mul_f32 v[46:47], v[2:3], v[46:47]
	v_cvt_pk_bf16_f32 v44, v44, v45
	v_mov_b32_e32 v45, v46
	v_mov_b32_e32 v46, v47
	v_pk_mul_f32 v[40:41], v[40:41], v[58:59] op_sel_hi:[1,0]
	v_cvt_pk_bf16_f32 v45, v45, v46
	v_pk_mul_f32 v[40:41], v[4:5], v[40:41]
	global_store_dwordx2 v[54:55], v[44:45], off sc1
	v_pk_mul_f32 v[42:43], v[42:43], v[58:59] op_sel_hi:[1,0]
	v_pk_mul_f32 v[42:43], v[6:7], v[42:43]
	v_cvt_pk_bf16_f32 v40, v40, v41
	v_mov_b32_e32 v41, v42
	v_mov_b32_e32 v42, v43
	v_pk_mul_f32 v[36:37], v[36:37], v[58:59] op_sel_hi:[1,0]
	v_cvt_pk_bf16_f32 v41, v41, v42
	v_pk_mul_f32 v[36:37], v[8:9], v[36:37]
	global_store_dwordx2 v[52:53], v[40:41], off sc1
	v_pk_mul_f32 v[38:39], v[38:39], v[58:59] op_sel_hi:[1,0]
	v_pk_mul_f32 v[38:39], v[10:11], v[38:39]
	v_cvt_pk_bf16_f32 v36, v36, v37
	v_mov_b32_e32 v37, v38
	v_mov_b32_e32 v38, v39
	v_pk_mul_f32 v[32:33], v[32:33], v[58:59] op_sel_hi:[1,0]
	v_cvt_pk_bf16_f32 v37, v37, v38
	v_pk_mul_f32 v[32:33], v[12:13], v[32:33]
	global_store_dwordx2 v[56:57], v[36:37], off sc1
	v_pk_mul_f32 v[34:35], v[34:35], v[58:59] op_sel_hi:[1,0]
	v_mul_f32_e32 v36, 0x4b800000, v48
	v_cmp_gt_f32_e32 vcc, s23, v48
	v_pk_mul_f32 v[34:35], v[14:15], v[34:35]
	v_cndmask_b32_e32 v36, v48, v36, vcc
	v_cvt_pk_bf16_f32 v32, v32, v33
	v_rsq_f32_e32 v36, v36
	v_mov_b32_e32 v33, v34
	v_mov_b32_e32 v34, v35
	v_cvt_pk_bf16_f32 v33, v33, v34
	global_store_dwordx2 v[50:51], v[32:33], off sc1
	v_mul_f32_e32 v32, 0x45800000, v36
	v_cndmask_b32_e32 v32, v36, v32, vcc
	v_pk_mul_f32 v[28:29], v[28:29], v[32:33] op_sel_hi:[1,0]
	v_pk_mul_f32 v[30:31], v[30:31], v[32:33] op_sel_hi:[1,0]
	v_pk_mul_f32 v[28:29], v[0:1], v[28:29]
	v_pk_mul_f32 v[30:31], v[2:3], v[30:31]
	v_bfe_u32 v33, v28, 16, 1
	v_add3_u32 v28, v28, v33, s13
	v_bfe_u32 v33, v29, 16, 1
	v_lshrrev_b32_e32 v28, 16, v28
	v_add3_u32 v29, v29, v33, s13
	v_and_or_b32 v28, v29, s33, v28
	v_lshlrev_b64 v[34:35], 11, v[90:91]
	v_mov_b32_e32 v29, v30
	v_lshl_add_u64 v[34:35], s[50:51], 0, v[34:35]
	v_mov_b32_e32 v30, v31
	v_pk_mul_f32 v[24:25], v[24:25], v[32:33] op_sel_hi:[1,0]
	v_cvt_pk_bf16_f32 v29, v29, v30
	v_lshl_add_u64 v[30:31], v[34:35], 0, v[176:177]
	v_pk_mul_f32 v[24:25], v[4:5], v[24:25]
	global_store_dwordx2 v[30:31], v[28:29], off sc1
	v_pk_mul_f32 v[26:27], v[26:27], v[32:33] op_sel_hi:[1,0]
	v_pk_mul_f32 v[26:27], v[6:7], v[26:27]
	v_cvt_pk_bf16_f32 v24, v24, v25
	v_mov_b32_e32 v25, v26
	v_mov_b32_e32 v26, v27
	v_pk_mul_f32 v[20:21], v[20:21], v[32:33] op_sel_hi:[1,0]
	v_cvt_pk_bf16_f32 v25, v25, v26
	v_lshl_add_u64 v[26:27], v[34:35], 0, v[84:85]
	v_pk_mul_f32 v[20:21], v[8:9], v[20:21]
	global_store_dwordx2 v[26:27], v[24:25], off sc1
	v_pk_mul_f32 v[22:23], v[22:23], v[32:33] op_sel_hi:[1,0]
	v_pk_mul_f32 v[22:23], v[10:11], v[22:23]
	v_cvt_pk_bf16_f32 v20, v20, v21
	v_mov_b32_e32 v21, v22
	v_mov_b32_e32 v22, v23
	v_pk_mul_f32 v[16:17], v[16:17], v[32:33] op_sel_hi:[1,0]
	v_cvt_pk_bf16_f32 v21, v21, v22
	v_lshl_add_u64 v[22:23], v[34:35], 0, v[86:87]
	v_pk_mul_f32 v[16:17], v[12:13], v[16:17]
	global_store_dwordx2 v[22:23], v[20:21], off sc1
	v_pk_mul_f32 v[18:19], v[18:19], v[32:33] op_sel_hi:[1,0]
	v_pk_mul_f32 v[18:19], v[14:15], v[18:19]
	v_cvt_pk_bf16_f32 v16, v16, v17
	v_mov_b32_e32 v17, v18
	v_mov_b32_e32 v18, v19
	v_cmp_lt_i32_e32 vcc, s13, v80
	v_cvt_pk_bf16_f32 v17, v17, v18
	v_lshl_add_u64 v[18:19], v[34:35], 0, v[88:89]
	s_or_b64 s[38:39], vcc, s[38:39]
	global_store_dwordx2 v[18:19], v[16:17], off sc1
	s_andn2_b64 exec, exec, s[38:39]
	s_cbranch_execnz .LBB0_446
	s_branch .Lp0_norm_done
